# GLA/retention y short stores issued by all lanes (no exec toggling)
# baseline (speedup 1.0000x reference)
.Lret2_loop:
	global_load_dword v84, v32, s[10:11]
	global_load_dword v85, v32, s[10:11] offset:-1024
	global_load_dword v86, v33, s[10:11]
	global_load_dword v87, v33, s[10:11] offset:-1024
	global_load_dword v88, v34, s[10:11]
	global_load_dword v90, v35, s[12:13]
	global_load_dword v91, v35, s[12:13] offset:4
	s_add_u32 s10, s10, 0x18000
	s_addc_u32 s11, s11, 0
	s_add_u32 s12, s12, 0x4000
	s_addc_u32 s13, s13, 0
	s_waitcnt lgkmcnt(3)
	v_pk_fma_f32 v[6:7], v[64:65], v[48:49], v[6:7] op_sel_hi:[1,0,1]
	v_pk_mul_f32 v[38:39], v[6:7], v[48:49] op_sel:[0,1] op_sel_hi:[1,1]
	v_pk_fma_f32 v[8:9], v[64:65], v[50:51], v[8:9] op_sel_hi:[1,0,1]
	v_pk_fma_f32 v[38:39], v[8:9], v[50:51], v[38:39] op_sel:[0,1,0] op_sel_hi:[1,1,1]
	s_waitcnt lgkmcnt(2)
	v_pk_fma_f32 v[10:11], v[64:65], v[52:53], v[10:11] op_sel_hi:[1,0,1]
	v_pk_fma_f32 v[38:39], v[10:11], v[52:53], v[38:39] op_sel:[0,1,0] op_sel_hi:[1,1,1]
	v_pk_fma_f32 v[12:13], v[64:65], v[54:55], v[12:13] op_sel_hi:[1,0,1]
	v_pk_fma_f32 v[38:39], v[12:13], v[54:55], v[38:39] op_sel:[0,1,0] op_sel_hi:[1,1,1]
	s_waitcnt lgkmcnt(1)
	v_pk_fma_f32 v[14:15], v[64:65], v[56:57], v[14:15] op_sel_hi:[1,0,1]
	v_pk_fma_f32 v[38:39], v[14:15], v[56:57], v[38:39] op_sel:[0,1,0] op_sel_hi:[1,1,1]
	v_pk_fma_f32 v[16:17], v[64:65], v[58:59], v[16:17] op_sel_hi:[1,0,1]
	v_pk_fma_f32 v[38:39], v[16:17], v[58:59], v[38:39] op_sel:[0,1,0] op_sel_hi:[1,1,1]
	s_waitcnt lgkmcnt(0)
	v_pk_fma_f32 v[18:19], v[64:65], v[60:61], v[18:19] op_sel_hi:[1,0,1]
	v_pk_fma_f32 v[38:39], v[18:19], v[60:61], v[38:39] op_sel:[0,1,0] op_sel_hi:[1,1,1]
	v_pk_fma_f32 v[20:21], v[64:65], v[62:63], v[20:21] op_sel_hi:[1,0,1]
	v_pk_fma_f32 v[38:39], v[20:21], v[62:63], v[38:39] op_sel:[0,1,0] op_sel_hi:[1,1,1]
	s_add_u32 s14, s14, 0x1000
	s_addc_u32 s15, s15, 0
	v_add_f32_dpp v38, v38, v38 row_ror:8 row_mask:0xf bank_mask:0x3 bound_ctrl:1
	v_add_f32_dpp v38, v39, v39 row_ror:8 row_mask:0xf bank_mask:0xc bound_ctrl:1
	ds_read_b64 v[82:83], v3 offset:20992
	ds_read_b128 v[66:69], v2 offset:9472
	v_add_f32_dpp v38, v38, v38 row_half_mirror row_mask:0xf bank_mask:0xf bound_ctrl:1
	ds_read_b128 v[70:73], v2 offset:9728
	ds_read_b128 v[74:77], v2 offset:9984
	v_add_f32_dpp v38, v38, v38 quad_perm:[1,0,3,2] row_mask:0xf bank_mask:0xf bound_ctrl:1
	ds_read_b128 v[78:81], v2 offset:10240
	s_nop 0
	v_add_f32_dpp v38, v38, v38 quad_perm:[2,3,0,1] row_mask:0xf bank_mask:0xf bound_ctrl:1
	v_cvt_pk_bf16_f32 v47, v38, v38
	global_store_short v28, v47, s[14:15] offset:-4096
	s_waitcnt lgkmcnt(3)
	v_pk_fma_f32 v[6:7], v[82:83], v[66:67], v[6:7] op_sel_hi:[1,0,1]
	v_pk_mul_f32 v[38:39], v[6:7], v[66:67] op_sel:[0,1] op_sel_hi:[1,1]
	v_pk_fma_f32 v[8:9], v[82:83], v[68:69], v[8:9] op_sel_hi:[1,0,1]
	v_pk_fma_f32 v[38:39], v[8:9], v[68:69], v[38:39] op_sel:[0,1,0] op_sel_hi:[1,1,1]
	s_waitcnt lgkmcnt(2)
	v_pk_fma_f32 v[10:11], v[82:83], v[70:71], v[10:11] op_sel_hi:[1,0,1]
	v_pk_fma_f32 v[38:39], v[10:11], v[70:71], v[38:39] op_sel:[0,1,0] op_sel_hi:[1,1,1]
	v_pk_fma_f32 v[12:13], v[82:83], v[72:73], v[12:13] op_sel_hi:[1,0,1]
	v_pk_fma_f32 v[38:39], v[12:13], v[72:73], v[38:39] op_sel:[0,1,0] op_sel_hi:[1,1,1]
	s_waitcnt lgkmcnt(1)
	v_pk_fma_f32 v[14:15], v[82:83], v[74:75], v[14:15] op_sel_hi:[1,0,1]
	v_pk_fma_f32 v[38:39], v[14:15], v[74:75], v[38:39] op_sel:[0,1,0] op_sel_hi:[1,1,1]
	v_pk_fma_f32 v[16:17], v[82:83], v[76:77], v[16:17] op_sel_hi:[1,0,1]
	v_pk_fma_f32 v[38:39], v[16:17], v[76:77], v[38:39] op_sel:[0,1,0] op_sel_hi:[1,1,1]
	s_waitcnt lgkmcnt(0)
	v_pk_fma_f32 v[18:19], v[82:83], v[78:79], v[18:19] op_sel_hi:[1,0,1]
	v_pk_fma_f32 v[38:39], v[18:19], v[78:79], v[38:39] op_sel:[0,1,0] op_sel_hi:[1,1,1]
	v_pk_fma_f32 v[20:21], v[82:83], v[80:81], v[20:21] op_sel_hi:[1,0,1]
	v_pk_fma_f32 v[38:39], v[20:21], v[80:81], v[38:39] op_sel:[0,1,0] op_sel_hi:[1,1,1]
	s_add_u32 s14, s14, 0x1000
	s_addc_u32 s15, s15, 0
	v_add_f32_dpp v38, v38, v38 row_ror:8 row_mask:0xf bank_mask:0x3 bound_ctrl:1
	v_add_f32_dpp v38, v39, v39 row_ror:8 row_mask:0xf bank_mask:0xc bound_ctrl:1
	ds_read_b64 v[64:65], v3 offset:21248
	ds_read_b128 v[48:51], v2 offset:10496
	v_add_f32_dpp v38, v38, v38 row_half_mirror row_mask:0xf bank_mask:0xf bound_ctrl:1
	ds_read_b128 v[52:55], v2 offset:10752
	ds_read_b128 v[56:59], v2 offset:11008
	v_add_f32_dpp v38, v38, v38 quad_perm:[1,0,3,2] row_mask:0xf bank_mask:0xf bound_ctrl:1
	ds_read_b128 v[60:63], v2 offset:11264
	s_nop 0
	v_add_f32_dpp v38, v38, v38 quad_perm:[2,3,0,1] row_mask:0xf bank_mask:0xf bound_ctrl:1
	v_cvt_pk_bf16_f32 v47, v38, v38
	global_store_short v28, v47, s[14:15] offset:-4096
	s_waitcnt lgkmcnt(3)
	v_pk_fma_f32 v[6:7], v[64:65], v[48:49], v[6:7] op_sel_hi:[1,0,1]
	v_pk_mul_f32 v[38:39], v[6:7], v[48:49] op_sel:[0,1] op_sel_hi:[1,1]
	v_pk_fma_f32 v[8:9], v[64:65], v[50:51], v[8:9] op_sel_hi:[1,0,1]
	v_pk_fma_f32 v[38:39], v[8:9], v[50:51], v[38:39] op_sel:[0,1,0] op_sel_hi:[1,1,1]
	s_waitcnt lgkmcnt(2)
	v_pk_fma_f32 v[10:11], v[64:65], v[52:53], v[10:11] op_sel_hi:[1,0,1]
	v_pk_fma_f32 v[38:39], v[10:11], v[52:53], v[38:39] op_sel:[0,1,0] op_sel_hi:[1,1,1]
	v_pk_fma_f32 v[12:13], v[64:65], v[54:55], v[12:13] op_sel_hi:[1,0,1]
	v_pk_fma_f32 v[38:39], v[12:13], v[54:55], v[38:39] op_sel:[0,1,0] op_sel_hi:[1,1,1]
	s_waitcnt lgkmcnt(1)
	v_pk_fma_f32 v[14:15], v[64:65], v[56:57], v[14:15] op_sel_hi:[1,0,1]
	v_pk_fma_f32 v[38:39], v[14:15], v[56:57], v[38:39] op_sel:[0,1,0] op_sel_hi:[1,1,1]
	v_pk_fma_f32 v[16:17], v[64:65], v[58:59], v[16:17] op_sel_hi:[1,0,1]
	v_pk_fma_f32 v[38:39], v[16:17], v[58:59], v[38:39] op_sel:[0,1,0] op_sel_hi:[1,1,1]
	s_waitcnt lgkmcnt(0)
	v_pk_fma_f32 v[18:19], v[64:65], v[60:61], v[18:19] op_sel_hi:[1,0,1]
	v_pk_fma_f32 v[38:39], v[18:19], v[60:61], v[38:39] op_sel:[0,1,0] op_sel_hi:[1,1,1]
	v_pk_fma_f32 v[20:21], v[64:65], v[62:63], v[20:21] op_sel_hi:[1,0,1]
	v_pk_fma_f32 v[38:39], v[20:21], v[62:63], v[38:39] op_sel:[0,1,0] op_sel_hi:[1,1,1]
	s_add_u32 s14, s14, 0x1000
	s_addc_u32 s15, s15, 0
	v_add_f32_dpp v38, v38, v38 row_ror:8 row_mask:0xf bank_mask:0x3 bound_ctrl:1
	v_add_f32_dpp v38, v39, v39 row_ror:8 row_mask:0xf bank_mask:0xc bound_ctrl:1
	ds_read_b64 v[82:83], v3 offset:21504
	ds_read_b128 v[66:69], v2 offset:11520
	v_add_f32_dpp v38, v38, v38 row_half_mirror row_mask:0xf bank_mask:0xf bound_ctrl:1
	ds_read_b128 v[70:73], v2 offset:11776
	ds_read_b128 v[74:77], v2 offset:12032
	v_add_f32_dpp v38, v38, v38 quad_perm:[1,0,3,2] row_mask:0xf bank_mask:0xf bound_ctrl:1
	ds_read_b128 v[78:81], v2 offset:12288
	s_nop 0
	v_add_f32_dpp v38, v38, v38 quad_perm:[2,3,0,1] row_mask:0xf bank_mask:0xf bound_ctrl:1
	v_cvt_pk_bf16_f32 v47, v38, v38
	global_store_short v28, v47, s[14:15] offset:-4096
	s_waitcnt lgkmcnt(3)
	v_pk_fma_f32 v[6:7], v[82:83], v[66:67], v[6:7] op_sel_hi:[1,0,1]
	v_pk_mul_f32 v[38:39], v[6:7], v[66:67] op_sel:[0,1] op_sel_hi:[1,1]
	v_pk_fma_f32 v[8:9], v[82:83], v[68:69], v[8:9] op_sel_hi:[1,0,1]
	v_pk_fma_f32 v[38:39], v[8:9], v[68:69], v[38:39] op_sel:[0,1,0] op_sel_hi:[1,1,1]
	s_waitcnt lgkmcnt(2)
	v_pk_fma_f32 v[10:11], v[82:83], v[70:71], v[10:11] op_sel_hi:[1,0,1]
	v_pk_fma_f32 v[38:39], v[10:11], v[70:71], v[38:39] op_sel:[0,1,0] op_sel_hi:[1,1,1]
	v_pk_fma_f32 v[12:13], v[82:83], v[72:73], v[12:13] op_sel_hi:[1,0,1]
	v_pk_fma_f32 v[38:39], v[12:13], v[72:73], v[38:39] op_sel:[0,1,0] op_sel_hi:[1,1,1]
	s_waitcnt lgkmcnt(1)
	v_pk_fma_f32 v[14:15], v[82:83], v[74:75], v[14:15] op_sel_hi:[1,0,1]
	v_pk_fma_f32 v[38:39], v[14:15], v[74:75], v[38:39] op_sel:[0,1,0] op_sel_hi:[1,1,1]
	v_pk_fma_f32 v[16:17], v[82:83], v[76:77], v[16:17] op_sel_hi:[1,0,1]
	v_pk_fma_f32 v[38:39], v[16:17], v[76:77], v[38:39] op_sel:[0,1,0] op_sel_hi:[1,1,1]
	s_waitcnt lgkmcnt(0)
	v_pk_fma_f32 v[18:19], v[82:83], v[78:79], v[18:19] op_sel_hi:[1,0,1]
	v_pk_fma_f32 v[38:39], v[18:19], v[78:79], v[38:39] op_sel:[0,1,0] op_sel_hi:[1,1,1]
	v_pk_fma_f32 v[20:21], v[82:83], v[80:81], v[20:21] op_sel_hi:[1,0,1]
	v_pk_fma_f32 v[38:39], v[20:21], v[80:81], v[38:39] op_sel:[0,1,0] op_sel_hi:[1,1,1]
	s_add_u32 s14, s14, 0x1000
	s_addc_u32 s15, s15, 0
	v_add_f32_dpp v38, v38, v38 row_ror:8 row_mask:0xf bank_mask:0x3 bound_ctrl:1
	v_add_f32_dpp v38, v39, v39 row_ror:8 row_mask:0xf bank_mask:0xc bound_ctrl:1
	ds_read_b64 v[64:65], v3 offset:21760
	ds_read_b128 v[48:51], v2 offset:12544
	v_add_f32_dpp v38, v38, v38 row_half_mirror row_mask:0xf bank_mask:0xf bound_ctrl:1
	ds_read_b128 v[52:55], v2 offset:12800
	ds_read_b128 v[56:59], v2 offset:13056
	v_add_f32_dpp v38, v38, v38 quad_perm:[1,0,3,2] row_mask:0xf bank_mask:0xf bound_ctrl:1
	ds_read_b128 v[60:63], v2 offset:13312
	s_nop 0
	v_add_f32_dpp v38, v38, v38 quad_perm:[2,3,0,1] row_mask:0xf bank_mask:0xf bound_ctrl:1
	v_cvt_pk_bf16_f32 v47, v38, v38
	global_store_short v28, v47, s[14:15] offset:-4096
	s_waitcnt lgkmcnt(3)
	v_pk_fma_f32 v[6:7], v[64:65], v[48:49], v[6:7] op_sel_hi:[1,0,1]
	v_pk_mul_f32 v[38:39], v[6:7], v[48:49] op_sel:[0,1] op_sel_hi:[1,1]
	v_pk_fma_f32 v[8:9], v[64:65], v[50:51], v[8:9] op_sel_hi:[1,0,1]
	v_pk_fma_f32 v[38:39], v[8:9], v[50:51], v[38:39] op_sel:[0,1,0] op_sel_hi:[1,1,1]
	s_waitcnt lgkmcnt(2)
	v_pk_fma_f32 v[10:11], v[64:65], v[52:53], v[10:11] op_sel_hi:[1,0,1]
	v_pk_fma_f32 v[38:39], v[10:11], v[52:53], v[38:39] op_sel:[0,1,0] op_sel_hi:[1,1,1]
	v_pk_fma_f32 v[12:13], v[64:65], v[54:55], v[12:13] op_sel_hi:[1,0,1]
	v_pk_fma_f32 v[38:39], v[12:13], v[54:55], v[38:39] op_sel:[0,1,0] op_sel_hi:[1,1,1]
	s_waitcnt lgkmcnt(1)
	v_pk_fma_f32 v[14:15], v[64:65], v[56:57], v[14:15] op_sel_hi:[1,0,1]
	v_pk_fma_f32 v[38:39], v[14:15], v[56:57], v[38:39] op_sel:[0,1,0] op_sel_hi:[1,1,1]
	v_pk_fma_f32 v[16:17], v[64:65], v[58:59], v[16:17] op_sel_hi:[1,0,1]
	v_pk_fma_f32 v[38:39], v[16:17], v[58:59], v[38:39] op_sel:[0,1,0] op_sel_hi:[1,1,1]
	s_waitcnt lgkmcnt(0)
	v_pk_fma_f32 v[18:19], v[64:65], v[60:61], v[18:19] op_sel_hi:[1,0,1]
	v_pk_fma_f32 v[38:39], v[18:19], v[60:61], v[38:39] op_sel:[0,1,0] op_sel_hi:[1,1,1]
	v_pk_fma_f32 v[20:21], v[64:65], v[62:63], v[20:21] op_sel_hi:[1,0,1]
	v_pk_fma_f32 v[38:39], v[20:21], v[62:63], v[38:39] op_sel:[0,1,0] op_sel_hi:[1,1,1]
	s_add_u32 s14, s14, 0x1000
	s_addc_u32 s15, s15, 0
	v_add_f32_dpp v38, v38, v38 row_ror:8 row_mask:0xf bank_mask:0x3 bound_ctrl:1
	v_add_f32_dpp v38, v39, v39 row_ror:8 row_mask:0xf bank_mask:0xc bound_ctrl:1
	ds_read_b64 v[82:83], v3 offset:22016
	ds_read_b128 v[66:69], v2 offset:13568
	v_add_f32_dpp v38, v38, v38 row_half_mirror row_mask:0xf bank_mask:0xf bound_ctrl:1
	ds_read_b128 v[70:73], v2 offset:13824
	ds_read_b128 v[74:77], v2 offset:14080
	v_add_f32_dpp v38, v38, v38 quad_perm:[1,0,3,2] row_mask:0xf bank_mask:0xf bound_ctrl:1
	ds_read_b128 v[78:81], v2 offset:14336
	s_nop 0
	v_add_f32_dpp v38, v38, v38 quad_perm:[2,3,0,1] row_mask:0xf bank_mask:0xf bound_ctrl:1
	v_cvt_pk_bf16_f32 v47, v38, v38
	global_store_short v28, v47, s[14:15] offset:-4096
	s_waitcnt lgkmcnt(3)
	v_pk_fma_f32 v[6:7], v[82:83], v[66:67], v[6:7] op_sel_hi:[1,0,1]
	v_pk_mul_f32 v[38:39], v[6:7], v[66:67] op_sel:[0,1] op_sel_hi:[1,1]
	v_pk_fma_f32 v[8:9], v[82:83], v[68:69], v[8:9] op_sel_hi:[1,0,1]
	v_pk_fma_f32 v[38:39], v[8:9], v[68:69], v[38:39] op_sel:[0,1,0] op_sel_hi:[1,1,1]
	s_waitcnt lgkmcnt(2)
	v_pk_fma_f32 v[10:11], v[82:83], v[70:71], v[10:11] op_sel_hi:[1,0,1]
	v_pk_fma_f32 v[38:39], v[10:11], v[70:71], v[38:39] op_sel:[0,1,0] op_sel_hi:[1,1,1]
	v_pk_fma_f32 v[12:13], v[82:83], v[72:73], v[12:13] op_sel_hi:[1,0,1]
	v_pk_fma_f32 v[38:39], v[12:13], v[72:73], v[38:39] op_sel:[0,1,0] op_sel_hi:[1,1,1]
	s_waitcnt lgkmcnt(1)
	v_pk_fma_f32 v[14:15], v[82:83], v[74:75], v[14:15] op_sel_hi:[1,0,1]
	v_pk_fma_f32 v[38:39], v[14:15], v[74:75], v[38:39] op_sel:[0,1,0] op_sel_hi:[1,1,1]
	v_pk_fma_f32 v[16:17], v[82:83], v[76:77], v[16:17] op_sel_hi:[1,0,1]
	v_pk_fma_f32 v[38:39], v[16:17], v[76:77], v[38:39] op_sel:[0,1,0] op_sel_hi:[1,1,1]
	s_waitcnt lgkmcnt(0)
	v_pk_fma_f32 v[18:19], v[82:83], v[78:79], v[18:19] op_sel_hi:[1,0,1]
	v_pk_fma_f32 v[38:39], v[18:19], v[78:79], v[38:39] op_sel:[0,1,0] op_sel_hi:[1,1,1]
	v_pk_fma_f32 v[20:21], v[82:83], v[80:81], v[20:21] op_sel_hi:[1,0,1]
	v_pk_fma_f32 v[38:39], v[20:21], v[80:81], v[38:39] op_sel:[0,1,0] op_sel_hi:[1,1,1]
	s_add_u32 s14, s14, 0x1000
	s_addc_u32 s15, s15, 0
	v_add_f32_dpp v38, v38, v38 row_ror:8 row_mask:0xf bank_mask:0x3 bound_ctrl:1
	v_add_f32_dpp v38, v39, v39 row_ror:8 row_mask:0xf bank_mask:0xc bound_ctrl:1
	ds_read_b64 v[64:65], v3 offset:22272
	ds_read_b128 v[48:51], v2 offset:14592
	v_add_f32_dpp v38, v38, v38 row_half_mirror row_mask:0xf bank_mask:0xf bound_ctrl:1
	ds_read_b128 v[52:55], v2 offset:14848
	ds_read_b128 v[56:59], v2 offset:15104
	v_add_f32_dpp v38, v38, v38 quad_perm:[1,0,3,2] row_mask:0xf bank_mask:0xf bound_ctrl:1
	ds_read_b128 v[60:63], v2 offset:15360
	s_nop 0
	v_add_f32_dpp v38, v38, v38 quad_perm:[2,3,0,1] row_mask:0xf bank_mask:0xf bound_ctrl:1
	v_cvt_pk_bf16_f32 v47, v38, v38
	global_store_short v28, v47, s[14:15] offset:-4096
	s_waitcnt lgkmcnt(3)
	v_pk_fma_f32 v[6:7], v[64:65], v[48:49], v[6:7] op_sel_hi:[1,0,1]
	v_pk_mul_f32 v[38:39], v[6:7], v[48:49] op_sel:[0,1] op_sel_hi:[1,1]
	v_pk_fma_f32 v[8:9], v[64:65], v[50:51], v[8:9] op_sel_hi:[1,0,1]
	v_pk_fma_f32 v[38:39], v[8:9], v[50:51], v[38:39] op_sel:[0,1,0] op_sel_hi:[1,1,1]
	s_waitcnt lgkmcnt(2)
	v_pk_fma_f32 v[10:11], v[64:65], v[52:53], v[10:11] op_sel_hi:[1,0,1]
	v_pk_fma_f32 v[38:39], v[10:11], v[52:53], v[38:39] op_sel:[0,1,0] op_sel_hi:[1,1,1]
	v_pk_fma_f32 v[12:13], v[64:65], v[54:55], v[12:13] op_sel_hi:[1,0,1]
	v_pk_fma_f32 v[38:39], v[12:13], v[54:55], v[38:39] op_sel:[0,1,0] op_sel_hi:[1,1,1]
	s_waitcnt lgkmcnt(1)
	v_pk_fma_f32 v[14:15], v[64:65], v[56:57], v[14:15] op_sel_hi:[1,0,1]
	v_pk_fma_f32 v[38:39], v[14:15], v[56:57], v[38:39] op_sel:[0,1,0] op_sel_hi:[1,1,1]
	v_pk_fma_f32 v[16:17], v[64:65], v[58:59], v[16:17] op_sel_hi:[1,0,1]
	v_pk_fma_f32 v[38:39], v[16:17], v[58:59], v[38:39] op_sel:[0,1,0] op_sel_hi:[1,1,1]
	s_waitcnt lgkmcnt(0)
	v_pk_fma_f32 v[18:19], v[64:65], v[60:61], v[18:19] op_sel_hi:[1,0,1]
	v_pk_fma_f32 v[38:39], v[18:19], v[60:61], v[38:39] op_sel:[0,1,0] op_sel_hi:[1,1,1]
	v_pk_fma_f32 v[20:21], v[64:65], v[62:63], v[20:21] op_sel_hi:[1,0,1]
	v_pk_fma_f32 v[38:39], v[20:21], v[62:63], v[38:39] op_sel:[0,1,0] op_sel_hi:[1,1,1]
	s_add_u32 s14, s14, 0x1000
	s_addc_u32 s15, s15, 0
	v_add_f32_dpp v38, v38, v38 row_ror:8 row_mask:0xf bank_mask:0x3 bound_ctrl:1
	v_add_f32_dpp v38, v39, v39 row_ror:8 row_mask:0xf bank_mask:0xc bound_ctrl:1
	ds_read_b64 v[82:83], v3 offset:22528
	ds_read_b128 v[66:69], v2 offset:15616
	v_add_f32_dpp v38, v38, v38 row_half_mirror row_mask:0xf bank_mask:0xf bound_ctrl:1
	ds_read_b128 v[70:73], v2 offset:15872
	ds_read_b128 v[74:77], v2 offset:16128
	v_add_f32_dpp v38, v38, v38 quad_perm:[1,0,3,2] row_mask:0xf bank_mask:0xf bound_ctrl:1
	ds_read_b128 v[78:81], v2 offset:16384
	s_nop 0
	v_add_f32_dpp v38, v38, v38 quad_perm:[2,3,0,1] row_mask:0xf bank_mask:0xf bound_ctrl:1
	v_cvt_pk_bf16_f32 v47, v38, v38
	global_store_short v28, v47, s[14:15] offset:-4096
	s_waitcnt lgkmcnt(3)
	v_pk_fma_f32 v[6:7], v[82:83], v[66:67], v[6:7] op_sel_hi:[1,0,1]
	v_pk_mul_f32 v[38:39], v[6:7], v[66:67] op_sel:[0,1] op_sel_hi:[1,1]
	v_pk_fma_f32 v[8:9], v[82:83], v[68:69], v[8:9] op_sel_hi:[1,0,1]
	v_pk_fma_f32 v[38:39], v[8:9], v[68:69], v[38:39] op_sel:[0,1,0] op_sel_hi:[1,1,1]
	s_waitcnt lgkmcnt(2)
	v_pk_fma_f32 v[10:11], v[82:83], v[70:71], v[10:11] op_sel_hi:[1,0,1]
	v_pk_fma_f32 v[38:39], v[10:11], v[70:71], v[38:39] op_sel:[0,1,0] op_sel_hi:[1,1,1]
	v_pk_fma_f32 v[12:13], v[82:83], v[72:73], v[12:13] op_sel_hi:[1,0,1]
	v_pk_fma_f32 v[38:39], v[12:13], v[72:73], v[38:39] op_sel:[0,1,0] op_sel_hi:[1,1,1]
	s_waitcnt lgkmcnt(1)
	v_pk_fma_f32 v[14:15], v[82:83], v[74:75], v[14:15] op_sel_hi:[1,0,1]
	v_pk_fma_f32 v[38:39], v[14:15], v[74:75], v[38:39] op_sel:[0,1,0] op_sel_hi:[1,1,1]
	v_pk_fma_f32 v[16:17], v[82:83], v[76:77], v[16:17] op_sel_hi:[1,0,1]
	v_pk_fma_f32 v[38:39], v[16:17], v[76:77], v[38:39] op_sel:[0,1,0] op_sel_hi:[1,1,1]
	s_waitcnt lgkmcnt(0)
	v_pk_fma_f32 v[18:19], v[82:83], v[78:79], v[18:19] op_sel_hi:[1,0,1]
	v_pk_fma_f32 v[38:39], v[18:19], v[78:79], v[38:39] op_sel:[0,1,0] op_sel_hi:[1,1,1]
	v_pk_fma_f32 v[20:21], v[82:83], v[80:81], v[20:21] op_sel_hi:[1,0,1]
	v_pk_fma_f32 v[38:39], v[20:21], v[80:81], v[38:39] op_sel:[0,1,0] op_sel_hi:[1,1,1]
	s_add_u32 s14, s14, 0x1000
	s_addc_u32 s15, s15, 0
	v_add_f32_dpp v38, v38, v38 row_ror:8 row_mask:0xf bank_mask:0x3 bound_ctrl:1
	v_add_f32_dpp v38, v39, v39 row_ror:8 row_mask:0xf bank_mask:0xc bound_ctrl:1
	ds_read_b64 v[64:65], v3 offset:45312
	ds_read_b128 v[48:51], v2 offset:33024
	v_add_f32_dpp v38, v38, v38 row_half_mirror row_mask:0xf bank_mask:0xf bound_ctrl:1
	ds_read_b128 v[52:55], v2 offset:33280
	ds_read_b128 v[56:59], v2 offset:33536
	v_add_f32_dpp v38, v38, v38 quad_perm:[1,0,3,2] row_mask:0xf bank_mask:0xf bound_ctrl:1
	ds_read_b128 v[60:63], v2 offset:33792
	s_nop 0
	v_add_f32_dpp v38, v38, v38 quad_perm:[2,3,0,1] row_mask:0xf bank_mask:0xf bound_ctrl:1
	v_cvt_pk_bf16_f32 v47, v38, v38
	global_store_short v28, v47, s[14:15] offset:-4096
	s_waitcnt vmcnt(8)
	v_lshlrev_b32_e32 v108, 16, v84
	v_lshlrev_b32_e32 v109, 16, v85
	v_and_b32_e32 v110, s17, v84
	v_and_b32_e32 v111, s17, v85
	v_lshlrev_b32_e32 v112, 16, v86
	v_lshlrev_b32_e32 v113, 16, v87
	v_and_b32_e32 v114, s17, v86
	v_and_b32_e32 v115, s17, v87
	v_lshlrev_b32_e32 v116, 16, v88
	v_and_b32_e32 v117, s17, v88
	v_rcp_f32_e32 v25, v24
	v_mul_f32_e32 v113, v24, v113
	v_mul_f32_e32 v115, v24, v115
	v_mul_f32_e32 v109, 0x3db504f3, v109
	v_mul_f32_e32 v111, 0x3db504f3, v111
	v_cndmask_b32_e64 v27, 1.0, v25, s[20:21]
	v_mul_f32_e32 v24, v24, v26
	v_mul_f32_e32 v116, v27, v116
	v_mul_f32_e32 v117, v27, v117
	ds_write_b128 v29, v[108:111] offset:49408
	ds_write_b128 v29, v[112:115] offset:57600
	ds_write_b64 v30, v[90:91] offset:49408
	ds_write_b64 v31, v[116:117] offset:49408
	s_add_i32 s16, s16, 8
	s_waitcnt lgkmcnt(0)
	s_barrier
	s_cmpk_lt_u32 s16, 0x800
	s_cbranch_scc0 .Lret2_done
	global_load_dword v84, v32, s[10:11]
	global_load_dword v85, v32, s[10:11] offset:-1024
	global_load_dword v86, v33, s[10:11]
	global_load_dword v87, v33, s[10:11] offset:-1024
	global_load_dword v88, v34, s[10:11]
	global_load_dword v90, v35, s[12:13]
	global_load_dword v91, v35, s[12:13] offset:4
	s_add_u32 s10, s10, 0x18000
	s_addc_u32 s11, s11, 0
	s_add_u32 s12, s12, 0x4000
	s_addc_u32 s13, s13, 0
	s_waitcnt lgkmcnt(3)
	v_pk_fma_f32 v[6:7], v[64:65], v[48:49], v[6:7] op_sel_hi:[1,0,1]
	v_pk_mul_f32 v[38:39], v[6:7], v[48:49] op_sel:[0,1] op_sel_hi:[1,1]
	v_pk_fma_f32 v[8:9], v[64:65], v[50:51], v[8:9] op_sel_hi:[1,0,1]
	v_pk_fma_f32 v[38:39], v[8:9], v[50:51], v[38:39] op_sel:[0,1,0] op_sel_hi:[1,1,1]
	s_waitcnt lgkmcnt(2)
	v_pk_fma_f32 v[10:11], v[64:65], v[52:53], v[10:11] op_sel_hi:[1,0,1]
	v_pk_fma_f32 v[38:39], v[10:11], v[52:53], v[38:39] op_sel:[0,1,0] op_sel_hi:[1,1,1]
	v_pk_fma_f32 v[12:13], v[64:65], v[54:55], v[12:13] op_sel_hi:[1,0,1]
	v_pk_fma_f32 v[38:39], v[12:13], v[54:55], v[38:39] op_sel:[0,1,0] op_sel_hi:[1,1,1]
	s_waitcnt lgkmcnt(1)
	v_pk_fma_f32 v[14:15], v[64:65], v[56:57], v[14:15] op_sel_hi:[1,0,1]
	v_pk_fma_f32 v[38:39], v[14:15], v[56:57], v[38:39] op_sel:[0,1,0] op_sel_hi:[1,1,1]
	v_pk_fma_f32 v[16:17], v[64:65], v[58:59], v[16:17] op_sel_hi:[1,0,1]
	v_pk_fma_f32 v[38:39], v[16:17], v[58:59], v[38:39] op_sel:[0,1,0] op_sel_hi:[1,1,1]
	s_waitcnt lgkmcnt(0)
	v_pk_fma_f32 v[18:19], v[64:65], v[60:61], v[18:19] op_sel_hi:[1,0,1]
	v_pk_fma_f32 v[38:39], v[18:19], v[60:61], v[38:39] op_sel:[0,1,0] op_sel_hi:[1,1,1]
	v_pk_fma_f32 v[20:21], v[64:65], v[62:63], v[20:21] op_sel_hi:[1,0,1]
	v_pk_fma_f32 v[38:39], v[20:21], v[62:63], v[38:39] op_sel:[0,1,0] op_sel_hi:[1,1,1]
	s_add_u32 s14, s14, 0x1000
	s_addc_u32 s15, s15, 0
	v_add_f32_dpp v38, v38, v38 row_ror:8 row_mask:0xf bank_mask:0x3 bound_ctrl:1
	v_add_f32_dpp v38, v39, v39 row_ror:8 row_mask:0xf bank_mask:0xc bound_ctrl:1
	ds_read_b64 v[82:83], v3 offset:45568
	ds_read_b128 v[66:69], v2 offset:34048
	v_add_f32_dpp v38, v38, v38 row_half_mirror row_mask:0xf bank_mask:0xf bound_ctrl:1
	ds_read_b128 v[70:73], v2 offset:34304
	ds_read_b128 v[74:77], v2 offset:34560
	v_add_f32_dpp v38, v38, v38 quad_perm:[1,0,3,2] row_mask:0xf bank_mask:0xf bound_ctrl:1
	ds_read_b128 v[78:81], v2 offset:34816
	s_nop 0
	v_add_f32_dpp v38, v38, v38 quad_perm:[2,3,0,1] row_mask:0xf bank_mask:0xf bound_ctrl:1
	v_cvt_pk_bf16_f32 v47, v38, v38
	global_store_short v28, v47, s[14:15] offset:-4096
	s_waitcnt lgkmcnt(3)
	v_pk_fma_f32 v[6:7], v[82:83], v[66:67], v[6:7] op_sel_hi:[1,0,1]
	v_pk_mul_f32 v[38:39], v[6:7], v[66:67] op_sel:[0,1] op_sel_hi:[1,1]
	v_pk_fma_f32 v[8:9], v[82:83], v[68:69], v[8:9] op_sel_hi:[1,0,1]
	v_pk_fma_f32 v[38:39], v[8:9], v[68:69], v[38:39] op_sel:[0,1,0] op_sel_hi:[1,1,1]
	s_waitcnt lgkmcnt(2)
	v_pk_fma_f32 v[10:11], v[82:83], v[70:71], v[10:11] op_sel_hi:[1,0,1]
	v_pk_fma_f32 v[38:39], v[10:11], v[70:71], v[38:39] op_sel:[0,1,0] op_sel_hi:[1,1,1]
	v_pk_fma_f32 v[12:13], v[82:83], v[72:73], v[12:13] op_sel_hi:[1,0,1]
	v_pk_fma_f32 v[38:39], v[12:13], v[72:73], v[38:39] op_sel:[0,1,0] op_sel_hi:[1,1,1]
	s_waitcnt lgkmcnt(1)
	v_pk_fma_f32 v[14:15], v[82:83], v[74:75], v[14:15] op_sel_hi:[1,0,1]
	v_pk_fma_f32 v[38:39], v[14:15], v[74:75], v[38:39] op_sel:[0,1,0] op_sel_hi:[1,1,1]
	v_pk_fma_f32 v[16:17], v[82:83], v[76:77], v[16:17] op_sel_hi:[1,0,1]
	v_pk_fma_f32 v[38:39], v[16:17], v[76:77], v[38:39] op_sel:[0,1,0] op_sel_hi:[1,1,1]
	s_waitcnt lgkmcnt(0)
	v_pk_fma_f32 v[18:19], v[82:83], v[78:79], v[18:19] op_sel_hi:[1,0,1]
	v_pk_fma_f32 v[38:39], v[18:19], v[78:79], v[38:39] op_sel:[0,1,0] op_sel_hi:[1,1,1]
	v_pk_fma_f32 v[20:21], v[82:83], v[80:81], v[20:21] op_sel_hi:[1,0,1]
	v_pk_fma_f32 v[38:39], v[20:21], v[80:81], v[38:39] op_sel:[0,1,0] op_sel_hi:[1,1,1]
	s_add_u32 s14, s14, 0x1000
	s_addc_u32 s15, s15, 0
	v_add_f32_dpp v38, v38, v38 row_ror:8 row_mask:0xf bank_mask:0x3 bound_ctrl:1
	v_add_f32_dpp v38, v39, v39 row_ror:8 row_mask:0xf bank_mask:0xc bound_ctrl:1
	ds_read_b64 v[64:65], v3 offset:45824
	ds_read_b128 v[48:51], v2 offset:35072
	v_add_f32_dpp v38, v38, v38 row_half_mirror row_mask:0xf bank_mask:0xf bound_ctrl:1
	ds_read_b128 v[52:55], v2 offset:35328
	ds_read_b128 v[56:59], v2 offset:35584
	v_add_f32_dpp v38, v38, v38 quad_perm:[1,0,3,2] row_mask:0xf bank_mask:0xf bound_ctrl:1
	ds_read_b128 v[60:63], v2 offset:35840
	s_nop 0
	v_add_f32_dpp v38, v38, v38 quad_perm:[2,3,0,1] row_mask:0xf bank_mask:0xf bound_ctrl:1
	v_cvt_pk_bf16_f32 v47, v38, v38
	global_store_short v28, v47, s[14:15] offset:-4096
	s_waitcnt lgkmcnt(3)
	v_pk_fma_f32 v[6:7], v[64:65], v[48:49], v[6:7] op_sel_hi:[1,0,1]
	v_pk_mul_f32 v[38:39], v[6:7], v[48:49] op_sel:[0,1] op_sel_hi:[1,1]
	v_pk_fma_f32 v[8:9], v[64:65], v[50:51], v[8:9] op_sel_hi:[1,0,1]
	v_pk_fma_f32 v[38:39], v[8:9], v[50:51], v[38:39] op_sel:[0,1,0] op_sel_hi:[1,1,1]
	s_waitcnt lgkmcnt(2)
	v_pk_fma_f32 v[10:11], v[64:65], v[52:53], v[10:11] op_sel_hi:[1,0,1]
	v_pk_fma_f32 v[38:39], v[10:11], v[52:53], v[38:39] op_sel:[0,1,0] op_sel_hi:[1,1,1]
	v_pk_fma_f32 v[12:13], v[64:65], v[54:55], v[12:13] op_sel_hi:[1,0,1]
	v_pk_fma_f32 v[38:39], v[12:13], v[54:55], v[38:39] op_sel:[0,1,0] op_sel_hi:[1,1,1]
	s_waitcnt lgkmcnt(1)
	v_pk_fma_f32 v[14:15], v[64:65], v[56:57], v[14:15] op_sel_hi:[1,0,1]
	v_pk_fma_f32 v[38:39], v[14:15], v[56:57], v[38:39] op_sel:[0,1,0] op_sel_hi:[1,1,1]
	v_pk_fma_f32 v[16:17], v[64:65], v[58:59], v[16:17] op_sel_hi:[1,0,1]
	v_pk_fma_f32 v[38:39], v[16:17], v[58:59], v[38:39] op_sel:[0,1,0] op_sel_hi:[1,1,1]
	s_waitcnt lgkmcnt(0)
	v_pk_fma_f32 v[18:19], v[64:65], v[60:61], v[18:19] op_sel_hi:[1,0,1]
	v_pk_fma_f32 v[38:39], v[18:19], v[60:61], v[38:39] op_sel:[0,1,0] op_sel_hi:[1,1,1]
	v_pk_fma_f32 v[20:21], v[64:65], v[62:63], v[20:21] op_sel_hi:[1,0,1]
	v_pk_fma_f32 v[38:39], v[20:21], v[62:63], v[38:39] op_sel:[0,1,0] op_sel_hi:[1,1,1]
	s_add_u32 s14, s14, 0x1000
	s_addc_u32 s15, s15, 0
	v_add_f32_dpp v38, v38, v38 row_ror:8 row_mask:0xf bank_mask:0x3 bound_ctrl:1
	v_add_f32_dpp v38, v39, v39 row_ror:8 row_mask:0xf bank_mask:0xc bound_ctrl:1
	ds_read_b64 v[82:83], v3 offset:46080
	ds_read_b128 v[66:69], v2 offset:36096
	v_add_f32_dpp v38, v38, v38 row_half_mirror row_mask:0xf bank_mask:0xf bound_ctrl:1
	ds_read_b128 v[70:73], v2 offset:36352
	ds_read_b128 v[74:77], v2 offset:36608
	v_add_f32_dpp v38, v38, v38 quad_perm:[1,0,3,2] row_mask:0xf bank_mask:0xf bound_ctrl:1
	ds_read_b128 v[78:81], v2 offset:36864
	s_nop 0
	v_add_f32_dpp v38, v38, v38 quad_perm:[2,3,0,1] row_mask:0xf bank_mask:0xf bound_ctrl:1
	v_cvt_pk_bf16_f32 v47, v38, v38
	global_store_short v28, v47, s[14:15] offset:-4096
	s_waitcnt lgkmcnt(3)
	v_pk_fma_f32 v[6:7], v[82:83], v[66:67], v[6:7] op_sel_hi:[1,0,1]
	v_pk_mul_f32 v[38:39], v[6:7], v[66:67] op_sel:[0,1] op_sel_hi:[1,1]
	v_pk_fma_f32 v[8:9], v[82:83], v[68:69], v[8:9] op_sel_hi:[1,0,1]
	v_pk_fma_f32 v[38:39], v[8:9], v[68:69], v[38:39] op_sel:[0,1,0] op_sel_hi:[1,1,1]
	s_waitcnt lgkmcnt(2)
	v_pk_fma_f32 v[10:11], v[82:83], v[70:71], v[10:11] op_sel_hi:[1,0,1]
	v_pk_fma_f32 v[38:39], v[10:11], v[70:71], v[38:39] op_sel:[0,1,0] op_sel_hi:[1,1,1]
	v_pk_fma_f32 v[12:13], v[82:83], v[72:73], v[12:13] op_sel_hi:[1,0,1]
	v_pk_fma_f32 v[38:39], v[12:13], v[72:73], v[38:39] op_sel:[0,1,0] op_sel_hi:[1,1,1]
	s_waitcnt lgkmcnt(1)
	v_pk_fma_f32 v[14:15], v[82:83], v[74:75], v[14:15] op_sel_hi:[1,0,1]
	v_pk_fma_f32 v[38:39], v[14:15], v[74:75], v[38:39] op_sel:[0,1,0] op_sel_hi:[1,1,1]
	v_pk_fma_f32 v[16:17], v[82:83], v[76:77], v[16:17] op_sel_hi:[1,0,1]
	v_pk_fma_f32 v[38:39], v[16:17], v[76:77], v[38:39] op_sel:[0,1,0] op_sel_hi:[1,1,1]
	s_waitcnt lgkmcnt(0)
	v_pk_fma_f32 v[18:19], v[82:83], v[78:79], v[18:19] op_sel_hi:[1,0,1]
	v_pk_fma_f32 v[38:39], v[18:19], v[78:79], v[38:39] op_sel:[0,1,0] op_sel_hi:[1,1,1]
	v_pk_fma_f32 v[20:21], v[82:83], v[80:81], v[20:21] op_sel_hi:[1,0,1]
	v_pk_fma_f32 v[38:39], v[20:21], v[80:81], v[38:39] op_sel:[0,1,0] op_sel_hi:[1,1,1]
	s_add_u32 s14, s14, 0x1000
	s_addc_u32 s15, s15, 0
	v_add_f32_dpp v38, v38, v38 row_ror:8 row_mask:0xf bank_mask:0x3 bound_ctrl:1
	v_add_f32_dpp v38, v39, v39 row_ror:8 row_mask:0xf bank_mask:0xc bound_ctrl:1
	ds_read_b64 v[64:65], v3 offset:46336
	ds_read_b128 v[48:51], v2 offset:37120
	v_add_f32_dpp v38, v38, v38 row_half_mirror row_mask:0xf bank_mask:0xf bound_ctrl:1
	ds_read_b128 v[52:55], v2 offset:37376
	ds_read_b128 v[56:59], v2 offset:37632
	v_add_f32_dpp v38, v38, v38 quad_perm:[1,0,3,2] row_mask:0xf bank_mask:0xf bound_ctrl:1
	ds_read_b128 v[60:63], v2 offset:37888
	s_nop 0
	v_add_f32_dpp v38, v38, v38 quad_perm:[2,3,0,1] row_mask:0xf bank_mask:0xf bound_ctrl:1
	v_cvt_pk_bf16_f32 v47, v38, v38
	global_store_short v28, v47, s[14:15] offset:-4096
	s_waitcnt lgkmcnt(3)
	v_pk_fma_f32 v[6:7], v[64:65], v[48:49], v[6:7] op_sel_hi:[1,0,1]
	v_pk_mul_f32 v[38:39], v[6:7], v[48:49] op_sel:[0,1] op_sel_hi:[1,1]
	v_pk_fma_f32 v[8:9], v[64:65], v[50:51], v[8:9] op_sel_hi:[1,0,1]
	v_pk_fma_f32 v[38:39], v[8:9], v[50:51], v[38:39] op_sel:[0,1,0] op_sel_hi:[1,1,1]
	s_waitcnt lgkmcnt(2)
	v_pk_fma_f32 v[10:11], v[64:65], v[52:53], v[10:11] op_sel_hi:[1,0,1]
	v_pk_fma_f32 v[38:39], v[10:11], v[52:53], v[38:39] op_sel:[0,1,0] op_sel_hi:[1,1,1]
	v_pk_fma_f32 v[12:13], v[64:65], v[54:55], v[12:13] op_sel_hi:[1,0,1]
	v_pk_fma_f32 v[38:39], v[12:13], v[54:55], v[38:39] op_sel:[0,1,0] op_sel_hi:[1,1,1]
	s_waitcnt lgkmcnt(1)
	v_pk_fma_f32 v[14:15], v[64:65], v[56:57], v[14:15] op_sel_hi:[1,0,1]
	v_pk_fma_f32 v[38:39], v[14:15], v[56:57], v[38:39] op_sel:[0,1,0] op_sel_hi:[1,1,1]
	v_pk_fma_f32 v[16:17], v[64:65], v[58:59], v[16:17] op_sel_hi:[1,0,1]
	v_pk_fma_f32 v[38:39], v[16:17], v[58:59], v[38:39] op_sel:[0,1,0] op_sel_hi:[1,1,1]
	s_waitcnt lgkmcnt(0)
	v_pk_fma_f32 v[18:19], v[64:65], v[60:61], v[18:19] op_sel_hi:[1,0,1]
	v_pk_fma_f32 v[38:39], v[18:19], v[60:61], v[38:39] op_sel:[0,1,0] op_sel_hi:[1,1,1]
	v_pk_fma_f32 v[20:21], v[64:65], v[62:63], v[20:21] op_sel_hi:[1,0,1]
	v_pk_fma_f32 v[38:39], v[20:21], v[62:63], v[38:39] op_sel:[0,1,0] op_sel_hi:[1,1,1]
	s_add_u32 s14, s14, 0x1000
	s_addc_u32 s15, s15, 0
	v_add_f32_dpp v38, v38, v38 row_ror:8 row_mask:0xf bank_mask:0x3 bound_ctrl:1
	v_add_f32_dpp v38, v39, v39 row_ror:8 row_mask:0xf bank_mask:0xc bound_ctrl:1
	ds_read_b64 v[82:83], v3 offset:46592
	ds_read_b128 v[66:69], v2 offset:38144
	v_add_f32_dpp v38, v38, v38 row_half_mirror row_mask:0xf bank_mask:0xf bound_ctrl:1
	ds_read_b128 v[70:73], v2 offset:38400
	ds_read_b128 v[74:77], v2 offset:38656
	v_add_f32_dpp v38, v38, v38 quad_perm:[1,0,3,2] row_mask:0xf bank_mask:0xf bound_ctrl:1
	ds_read_b128 v[78:81], v2 offset:38912
	s_nop 0
	v_add_f32_dpp v38, v38, v38 quad_perm:[2,3,0,1] row_mask:0xf bank_mask:0xf bound_ctrl:1
	v_cvt_pk_bf16_f32 v47, v38, v38
	global_store_short v28, v47, s[14:15] offset:-4096
	s_waitcnt lgkmcnt(3)
	v_pk_fma_f32 v[6:7], v[82:83], v[66:67], v[6:7] op_sel_hi:[1,0,1]
	v_pk_mul_f32 v[38:39], v[6:7], v[66:67] op_sel:[0,1] op_sel_hi:[1,1]
	v_pk_fma_f32 v[8:9], v[82:83], v[68:69], v[8:9] op_sel_hi:[1,0,1]
	v_pk_fma_f32 v[38:39], v[8:9], v[68:69], v[38:39] op_sel:[0,1,0] op_sel_hi:[1,1,1]
	s_waitcnt lgkmcnt(2)
	v_pk_fma_f32 v[10:11], v[82:83], v[70:71], v[10:11] op_sel_hi:[1,0,1]
	v_pk_fma_f32 v[38:39], v[10:11], v[70:71], v[38:39] op_sel:[0,1,0] op_sel_hi:[1,1,1]
	v_pk_fma_f32 v[12:13], v[82:83], v[72:73], v[12:13] op_sel_hi:[1,0,1]
	v_pk_fma_f32 v[38:39], v[12:13], v[72:73], v[38:39] op_sel:[0,1,0] op_sel_hi:[1,1,1]
	s_waitcnt lgkmcnt(1)
	v_pk_fma_f32 v[14:15], v[82:83], v[74:75], v[14:15] op_sel_hi:[1,0,1]
	v_pk_fma_f32 v[38:39], v[14:15], v[74:75], v[38:39] op_sel:[0,1,0] op_sel_hi:[1,1,1]
	v_pk_fma_f32 v[16:17], v[82:83], v[76:77], v[16:17] op_sel_hi:[1,0,1]
	v_pk_fma_f32 v[38:39], v[16:17], v[76:77], v[38:39] op_sel:[0,1,0] op_sel_hi:[1,1,1]
	s_waitcnt lgkmcnt(0)
	v_pk_fma_f32 v[18:19], v[82:83], v[78:79], v[18:19] op_sel_hi:[1,0,1]
	v_pk_fma_f32 v[38:39], v[18:19], v[78:79], v[38:39] op_sel:[0,1,0] op_sel_hi:[1,1,1]
	v_pk_fma_f32 v[20:21], v[82:83], v[80:81], v[20:21] op_sel_hi:[1,0,1]
	v_pk_fma_f32 v[38:39], v[20:21], v[80:81], v[38:39] op_sel:[0,1,0] op_sel_hi:[1,1,1]
	s_add_u32 s14, s14, 0x1000
	s_addc_u32 s15, s15, 0
	v_add_f32_dpp v38, v38, v38 row_ror:8 row_mask:0xf bank_mask:0x3 bound_ctrl:1
	v_add_f32_dpp v38, v39, v39 row_ror:8 row_mask:0xf bank_mask:0xc bound_ctrl:1
	ds_read_b64 v[64:65], v3 offset:46848
	ds_read_b128 v[48:51], v2 offset:39168
	v_add_f32_dpp v38, v38, v38 row_half_mirror row_mask:0xf bank_mask:0xf bound_ctrl:1
	ds_read_b128 v[52:55], v2 offset:39424
	ds_read_b128 v[56:59], v2 offset:39680
	v_add_f32_dpp v38, v38, v38 quad_perm:[1,0,3,2] row_mask:0xf bank_mask:0xf bound_ctrl:1
	ds_read_b128 v[60:63], v2 offset:39936
	s_nop 0
	v_add_f32_dpp v38, v38, v38 quad_perm:[2,3,0,1] row_mask:0xf bank_mask:0xf bound_ctrl:1
	v_cvt_pk_bf16_f32 v47, v38, v38
	global_store_short v28, v47, s[14:15] offset:-4096
	s_waitcnt lgkmcnt(3)
	v_pk_fma_f32 v[6:7], v[64:65], v[48:49], v[6:7] op_sel_hi:[1,0,1]
	v_pk_mul_f32 v[38:39], v[6:7], v[48:49] op_sel:[0,1] op_sel_hi:[1,1]
	v_pk_fma_f32 v[8:9], v[64:65], v[50:51], v[8:9] op_sel_hi:[1,0,1]
	v_pk_fma_f32 v[38:39], v[8:9], v[50:51], v[38:39] op_sel:[0,1,0] op_sel_hi:[1,1,1]
	s_waitcnt lgkmcnt(2)
	v_pk_fma_f32 v[10:11], v[64:65], v[52:53], v[10:11] op_sel_hi:[1,0,1]
	v_pk_fma_f32 v[38:39], v[10:11], v[52:53], v[38:39] op_sel:[0,1,0] op_sel_hi:[1,1,1]
	v_pk_fma_f32 v[12:13], v[64:65], v[54:55], v[12:13] op_sel_hi:[1,0,1]
	v_pk_fma_f32 v[38:39], v[12:13], v[54:55], v[38:39] op_sel:[0,1,0] op_sel_hi:[1,1,1]
	s_waitcnt lgkmcnt(1)
	v_pk_fma_f32 v[14:15], v[64:65], v[56:57], v[14:15] op_sel_hi:[1,0,1]
	v_pk_fma_f32 v[38:39], v[14:15], v[56:57], v[38:39] op_sel:[0,1,0] op_sel_hi:[1,1,1]
	v_pk_fma_f32 v[16:17], v[64:65], v[58:59], v[16:17] op_sel_hi:[1,0,1]
	v_pk_fma_f32 v[38:39], v[16:17], v[58:59], v[38:39] op_sel:[0,1,0] op_sel_hi:[1,1,1]
	s_waitcnt lgkmcnt(0)
	v_pk_fma_f32 v[18:19], v[64:65], v[60:61], v[18:19] op_sel_hi:[1,0,1]
	v_pk_fma_f32 v[38:39], v[18:19], v[60:61], v[38:39] op_sel:[0,1,0] op_sel_hi:[1,1,1]
	v_pk_fma_f32 v[20:21], v[64:65], v[62:63], v[20:21] op_sel_hi:[1,0,1]
	v_pk_fma_f32 v[38:39], v[20:21], v[62:63], v[38:39] op_sel:[0,1,0] op_sel_hi:[1,1,1]
	s_add_u32 s14, s14, 0x1000
	s_addc_u32 s15, s15, 0
	v_add_f32_dpp v38, v38, v38 row_ror:8 row_mask:0xf bank_mask:0x3 bound_ctrl:1
	v_add_f32_dpp v38, v39, v39 row_ror:8 row_mask:0xf bank_mask:0xc bound_ctrl:1
	ds_read_b64 v[82:83], v3 offset:47104
	ds_read_b128 v[66:69], v2 offset:40192
	v_add_f32_dpp v38, v38, v38 row_half_mirror row_mask:0xf bank_mask:0xf bound_ctrl:1
	ds_read_b128 v[70:73], v2 offset:40448
	ds_read_b128 v[74:77], v2 offset:40704
	v_add_f32_dpp v38, v38, v38 quad_perm:[1,0,3,2] row_mask:0xf bank_mask:0xf bound_ctrl:1
	ds_read_b128 v[78:81], v2 offset:40960
	s_nop 0
	v_add_f32_dpp v38, v38, v38 quad_perm:[2,3,0,1] row_mask:0xf bank_mask:0xf bound_ctrl:1
	v_cvt_pk_bf16_f32 v47, v38, v38
	global_store_short v28, v47, s[14:15] offset:-4096
	s_waitcnt lgkmcnt(3)
	v_pk_fma_f32 v[6:7], v[82:83], v[66:67], v[6:7] op_sel_hi:[1,0,1]
	v_pk_mul_f32 v[38:39], v[6:7], v[66:67] op_sel:[0,1] op_sel_hi:[1,1]
	v_pk_fma_f32 v[8:9], v[82:83], v[68:69], v[8:9] op_sel_hi:[1,0,1]
	v_pk_fma_f32 v[38:39], v[8:9], v[68:69], v[38:39] op_sel:[0,1,0] op_sel_hi:[1,1,1]
	s_waitcnt lgkmcnt(2)
	v_pk_fma_f32 v[10:11], v[82:83], v[70:71], v[10:11] op_sel_hi:[1,0,1]
	v_pk_fma_f32 v[38:39], v[10:11], v[70:71], v[38:39] op_sel:[0,1,0] op_sel_hi:[1,1,1]
	v_pk_fma_f32 v[12:13], v[82:83], v[72:73], v[12:13] op_sel_hi:[1,0,1]
	v_pk_fma_f32 v[38:39], v[12:13], v[72:73], v[38:39] op_sel:[0,1,0] op_sel_hi:[1,1,1]
	s_waitcnt lgkmcnt(1)
	v_pk_fma_f32 v[14:15], v[82:83], v[74:75], v[14:15] op_sel_hi:[1,0,1]
	v_pk_fma_f32 v[38:39], v[14:15], v[74:75], v[38:39] op_sel:[0,1,0] op_sel_hi:[1,1,1]
	v_pk_fma_f32 v[16:17], v[82:83], v[76:77], v[16:17] op_sel_hi:[1,0,1]
	v_pk_fma_f32 v[38:39], v[16:17], v[76:77], v[38:39] op_sel:[0,1,0] op_sel_hi:[1,1,1]
	s_waitcnt lgkmcnt(0)
	v_pk_fma_f32 v[18:19], v[82:83], v[78:79], v[18:19] op_sel_hi:[1,0,1]
	v_pk_fma_f32 v[38:39], v[18:19], v[78:79], v[38:39] op_sel:[0,1,0] op_sel_hi:[1,1,1]
	v_pk_fma_f32 v[20:21], v[82:83], v[80:81], v[20:21] op_sel_hi:[1,0,1]
	v_pk_fma_f32 v[38:39], v[20:21], v[80:81], v[38:39] op_sel:[0,1,0] op_sel_hi:[1,1,1]
	s_add_u32 s14, s14, 0x1000
	s_addc_u32 s15, s15, 0
	v_add_f32_dpp v38, v38, v38 row_ror:8 row_mask:0xf bank_mask:0x3 bound_ctrl:1
	v_add_f32_dpp v38, v39, v39 row_ror:8 row_mask:0xf bank_mask:0xc bound_ctrl:1
	ds_read_b64 v[64:65], v23 offset:37120
	ds_read_b128 v[48:51], v2 offset:57600
	v_add_f32_dpp v38, v38, v38 row_half_mirror row_mask:0xf bank_mask:0xf bound_ctrl:1
	ds_read_b128 v[52:55], v2 offset:57856
	ds_read_b128 v[56:59], v2 offset:58112
	v_add_f32_dpp v38, v38, v38 quad_perm:[1,0,3,2] row_mask:0xf bank_mask:0xf bound_ctrl:1
	ds_read_b128 v[60:63], v2 offset:58368
	s_nop 0
	v_add_f32_dpp v38, v38, v38 quad_perm:[2,3,0,1] row_mask:0xf bank_mask:0xf bound_ctrl:1
	v_cvt_pk_bf16_f32 v47, v38, v38
	global_store_short v28, v47, s[14:15] offset:-4096
	s_waitcnt vmcnt(8)
	v_lshlrev_b32_e32 v108, 16, v84
	v_lshlrev_b32_e32 v109, 16, v85
	v_and_b32_e32 v110, s17, v84
	v_and_b32_e32 v111, s17, v85
	v_lshlrev_b32_e32 v112, 16, v86
	v_lshlrev_b32_e32 v113, 16, v87
	v_and_b32_e32 v114, s17, v86
	v_and_b32_e32 v115, s17, v87
	v_lshlrev_b32_e32 v116, 16, v88
	v_and_b32_e32 v117, s17, v88
	v_rcp_f32_e32 v25, v24
	v_mul_f32_e32 v113, v24, v113
	v_mul_f32_e32 v115, v24, v115
	v_mul_f32_e32 v109, 0x3db504f3, v109
	v_mul_f32_e32 v111, 0x3db504f3, v111
	v_cndmask_b32_e64 v27, 1.0, v25, s[20:21]
	v_mul_f32_e32 v24, v24, v26
	v_mul_f32_e32 v116, v27, v116
	v_mul_f32_e32 v117, v27, v117
	ds_write_b128 v29, v[108:111] offset:256
	ds_write_b128 v29, v[112:115] offset:8448
	ds_write_b64 v30, v[90:91] offset:256
	ds_write_b64 v31, v[116:117] offset:256
	s_add_i32 s16, s16, 8
	s_waitcnt lgkmcnt(0)
	s_barrier
	s_cmpk_lt_u32 s16, 0x800
	s_cbranch_scc0 .Lret2_done
	global_load_dword v84, v32, s[10:11]
	global_load_dword v85, v32, s[10:11] offset:-1024
	global_load_dword v86, v33, s[10:11]
	global_load_dword v87, v33, s[10:11] offset:-1024
	global_load_dword v88, v34, s[10:11]
	global_load_dword v90, v35, s[12:13]
	global_load_dword v91, v35, s[12:13] offset:4
	s_add_u32 s10, s10, 0x18000
	s_addc_u32 s11, s11, 0
	s_add_u32 s12, s12, 0x4000
	s_addc_u32 s13, s13, 0
	s_waitcnt lgkmcnt(3)
	v_pk_fma_f32 v[6:7], v[64:65], v[48:49], v[6:7] op_sel_hi:[1,0,1]
	v_pk_mul_f32 v[38:39], v[6:7], v[48:49] op_sel:[0,1] op_sel_hi:[1,1]
	v_pk_fma_f32 v[8:9], v[64:65], v[50:51], v[8:9] op_sel_hi:[1,0,1]
	v_pk_fma_f32 v[38:39], v[8:9], v[50:51], v[38:39] op_sel:[0,1,0] op_sel_hi:[1,1,1]
	s_waitcnt lgkmcnt(2)
	v_pk_fma_f32 v[10:11], v[64:65], v[52:53], v[10:11] op_sel_hi:[1,0,1]
	v_pk_fma_f32 v[38:39], v[10:11], v[52:53], v[38:39] op_sel:[0,1,0] op_sel_hi:[1,1,1]
	v_pk_fma_f32 v[12:13], v[64:65], v[54:55], v[12:13] op_sel_hi:[1,0,1]
	v_pk_fma_f32 v[38:39], v[12:13], v[54:55], v[38:39] op_sel:[0,1,0] op_sel_hi:[1,1,1]
	s_waitcnt lgkmcnt(1)
	v_pk_fma_f32 v[14:15], v[64:65], v[56:57], v[14:15] op_sel_hi:[1,0,1]
	v_pk_fma_f32 v[38:39], v[14:15], v[56:57], v[38:39] op_sel:[0,1,0] op_sel_hi:[1,1,1]
	v_pk_fma_f32 v[16:17], v[64:65], v[58:59], v[16:17] op_sel_hi:[1,0,1]
	v_pk_fma_f32 v[38:39], v[16:17], v[58:59], v[38:39] op_sel:[0,1,0] op_sel_hi:[1,1,1]
	s_waitcnt lgkmcnt(0)
	v_pk_fma_f32 v[18:19], v[64:65], v[60:61], v[18:19] op_sel_hi:[1,0,1]
	v_pk_fma_f32 v[38:39], v[18:19], v[60:61], v[38:39] op_sel:[0,1,0] op_sel_hi:[1,1,1]
	v_pk_fma_f32 v[20:21], v[64:65], v[62:63], v[20:21] op_sel_hi:[1,0,1]
	v_pk_fma_f32 v[38:39], v[20:21], v[62:63], v[38:39] op_sel:[0,1,0] op_sel_hi:[1,1,1]
	s_add_u32 s14, s14, 0x1000
	s_addc_u32 s15, s15, 0
	v_add_f32_dpp v38, v38, v38 row_ror:8 row_mask:0xf bank_mask:0x3 bound_ctrl:1
	v_add_f32_dpp v38, v39, v39 row_ror:8 row_mask:0xf bank_mask:0xc bound_ctrl:1
	ds_read_b64 v[82:83], v23 offset:37376
	ds_read_b128 v[66:69], v2 offset:58624
	v_add_f32_dpp v38, v38, v38 row_half_mirror row_mask:0xf bank_mask:0xf bound_ctrl:1
	ds_read_b128 v[70:73], v2 offset:58880
	ds_read_b128 v[74:77], v2 offset:59136
	v_add_f32_dpp v38, v38, v38 quad_perm:[1,0,3,2] row_mask:0xf bank_mask:0xf bound_ctrl:1
	ds_read_b128 v[78:81], v2 offset:59392
	s_nop 0
	v_add_f32_dpp v38, v38, v38 quad_perm:[2,3,0,1] row_mask:0xf bank_mask:0xf bound_ctrl:1
	v_cvt_pk_bf16_f32 v47, v38, v38
	global_store_short v28, v47, s[14:15] offset:-4096
	s_waitcnt lgkmcnt(3)
	v_pk_fma_f32 v[6:7], v[82:83], v[66:67], v[6:7] op_sel_hi:[1,0,1]
	v_pk_mul_f32 v[38:39], v[6:7], v[66:67] op_sel:[0,1] op_sel_hi:[1,1]
	v_pk_fma_f32 v[8:9], v[82:83], v[68:69], v[8:9] op_sel_hi:[1,0,1]
	v_pk_fma_f32 v[38:39], v[8:9], v[68:69], v[38:39] op_sel:[0,1,0] op_sel_hi:[1,1,1]
	s_waitcnt lgkmcnt(2)
	v_pk_fma_f32 v[10:11], v[82:83], v[70:71], v[10:11] op_sel_hi:[1,0,1]
	v_pk_fma_f32 v[38:39], v[10:11], v[70:71], v[38:39] op_sel:[0,1,0] op_sel_hi:[1,1,1]
	v_pk_fma_f32 v[12:13], v[82:83], v[72:73], v[12:13] op_sel_hi:[1,0,1]
	v_pk_fma_f32 v[38:39], v[12:13], v[72:73], v[38:39] op_sel:[0,1,0] op_sel_hi:[1,1,1]
	s_waitcnt lgkmcnt(1)
	v_pk_fma_f32 v[14:15], v[82:83], v[74:75], v[14:15] op_sel_hi:[1,0,1]
	v_pk_fma_f32 v[38:39], v[14:15], v[74:75], v[38:39] op_sel:[0,1,0] op_sel_hi:[1,1,1]
	v_pk_fma_f32 v[16:17], v[82:83], v[76:77], v[16:17] op_sel_hi:[1,0,1]
	v_pk_fma_f32 v[38:39], v[16:17], v[76:77], v[38:39] op_sel:[0,1,0] op_sel_hi:[1,1,1]
	s_waitcnt lgkmcnt(0)
	v_pk_fma_f32 v[18:19], v[82:83], v[78:79], v[18:19] op_sel_hi:[1,0,1]
	v_pk_fma_f32 v[38:39], v[18:19], v[78:79], v[38:39] op_sel:[0,1,0] op_sel_hi:[1,1,1]
	v_pk_fma_f32 v[20:21], v[82:83], v[80:81], v[20:21] op_sel_hi:[1,0,1]
	v_pk_fma_f32 v[38:39], v[20:21], v[80:81], v[38:39] op_sel:[0,1,0] op_sel_hi:[1,1,1]
	s_add_u32 s14, s14, 0x1000
	s_addc_u32 s15, s15, 0
	v_add_f32_dpp v38, v38, v38 row_ror:8 row_mask:0xf bank_mask:0x3 bound_ctrl:1
	v_add_f32_dpp v38, v39, v39 row_ror:8 row_mask:0xf bank_mask:0xc bound_ctrl:1
	ds_read_b64 v[64:65], v23 offset:37632
	ds_read_b128 v[48:51], v2 offset:59648
	v_add_f32_dpp v38, v38, v38 row_half_mirror row_mask:0xf bank_mask:0xf bound_ctrl:1
	ds_read_b128 v[52:55], v2 offset:59904
	ds_read_b128 v[56:59], v2 offset:60160
	v_add_f32_dpp v38, v38, v38 quad_perm:[1,0,3,2] row_mask:0xf bank_mask:0xf bound_ctrl:1
	ds_read_b128 v[60:63], v2 offset:60416
	s_nop 0
	v_add_f32_dpp v38, v38, v38 quad_perm:[2,3,0,1] row_mask:0xf bank_mask:0xf bound_ctrl:1
	v_cvt_pk_bf16_f32 v47, v38, v38
	global_store_short v28, v47, s[14:15] offset:-4096
	s_waitcnt lgkmcnt(3)
	v_pk_fma_f32 v[6:7], v[64:65], v[48:49], v[6:7] op_sel_hi:[1,0,1]
	v_pk_mul_f32 v[38:39], v[6:7], v[48:49] op_sel:[0,1] op_sel_hi:[1,1]
	v_pk_fma_f32 v[8:9], v[64:65], v[50:51], v[8:9] op_sel_hi:[1,0,1]
	v_pk_fma_f32 v[38:39], v[8:9], v[50:51], v[38:39] op_sel:[0,1,0] op_sel_hi:[1,1,1]
	s_waitcnt lgkmcnt(2)
	v_pk_fma_f32 v[10:11], v[64:65], v[52:53], v[10:11] op_sel_hi:[1,0,1]
	v_pk_fma_f32 v[38:39], v[10:11], v[52:53], v[38:39] op_sel:[0,1,0] op_sel_hi:[1,1,1]
	v_pk_fma_f32 v[12:13], v[64:65], v[54:55], v[12:13] op_sel_hi:[1,0,1]
	v_pk_fma_f32 v[38:39], v[12:13], v[54:55], v[38:39] op_sel:[0,1,0] op_sel_hi:[1,1,1]
	s_waitcnt lgkmcnt(1)
	v_pk_fma_f32 v[14:15], v[64:65], v[56:57], v[14:15] op_sel_hi:[1,0,1]
	v_pk_fma_f32 v[38:39], v[14:15], v[56:57], v[38:39] op_sel:[0,1,0] op_sel_hi:[1,1,1]
	v_pk_fma_f32 v[16:17], v[64:65], v[58:59], v[16:17] op_sel_hi:[1,0,1]
	v_pk_fma_f32 v[38:39], v[16:17], v[58:59], v[38:39] op_sel:[0,1,0] op_sel_hi:[1,1,1]
	s_waitcnt lgkmcnt(0)
	v_pk_fma_f32 v[18:19], v[64:65], v[60:61], v[18:19] op_sel_hi:[1,0,1]
	v_pk_fma_f32 v[38:39], v[18:19], v[60:61], v[38:39] op_sel:[0,1,0] op_sel_hi:[1,1,1]
	v_pk_fma_f32 v[20:21], v[64:65], v[62:63], v[20:21] op_sel_hi:[1,0,1]
	v_pk_fma_f32 v[38:39], v[20:21], v[62:63], v[38:39] op_sel:[0,1,0] op_sel_hi:[1,1,1]
	s_add_u32 s14, s14, 0x1000
	s_addc_u32 s15, s15, 0
	v_add_f32_dpp v38, v38, v38 row_ror:8 row_mask:0xf bank_mask:0x3 bound_ctrl:1
	v_add_f32_dpp v38, v39, v39 row_ror:8 row_mask:0xf bank_mask:0xc bound_ctrl:1
	ds_read_b64 v[82:83], v23 offset:37888
	ds_read_b128 v[66:69], v2 offset:60672
	v_add_f32_dpp v38, v38, v38 row_half_mirror row_mask:0xf bank_mask:0xf bound_ctrl:1
	ds_read_b128 v[70:73], v2 offset:60928
	ds_read_b128 v[74:77], v2 offset:61184
	v_add_f32_dpp v38, v38, v38 quad_perm:[1,0,3,2] row_mask:0xf bank_mask:0xf bound_ctrl:1
	ds_read_b128 v[78:81], v2 offset:61440
	s_nop 0
	v_add_f32_dpp v38, v38, v38 quad_perm:[2,3,0,1] row_mask:0xf bank_mask:0xf bound_ctrl:1
	v_cvt_pk_bf16_f32 v47, v38, v38
	global_store_short v28, v47, s[14:15] offset:-4096
	s_waitcnt lgkmcnt(3)
	v_pk_fma_f32 v[6:7], v[82:83], v[66:67], v[6:7] op_sel_hi:[1,0,1]
	v_pk_mul_f32 v[38:39], v[6:7], v[66:67] op_sel:[0,1] op_sel_hi:[1,1]
	v_pk_fma_f32 v[8:9], v[82:83], v[68:69], v[8:9] op_sel_hi:[1,0,1]
	v_pk_fma_f32 v[38:39], v[8:9], v[68:69], v[38:39] op_sel:[0,1,0] op_sel_hi:[1,1,1]
	s_waitcnt lgkmcnt(2)
	v_pk_fma_f32 v[10:11], v[82:83], v[70:71], v[10:11] op_sel_hi:[1,0,1]
	v_pk_fma_f32 v[38:39], v[10:11], v[70:71], v[38:39] op_sel:[0,1,0] op_sel_hi:[1,1,1]
	v_pk_fma_f32 v[12:13], v[82:83], v[72:73], v[12:13] op_sel_hi:[1,0,1]
	v_pk_fma_f32 v[38:39], v[12:13], v[72:73], v[38:39] op_sel:[0,1,0] op_sel_hi:[1,1,1]
	s_waitcnt lgkmcnt(1)
	v_pk_fma_f32 v[14:15], v[82:83], v[74:75], v[14:15] op_sel_hi:[1,0,1]
	v_pk_fma_f32 v[38:39], v[14:15], v[74:75], v[38:39] op_sel:[0,1,0] op_sel_hi:[1,1,1]
	v_pk_fma_f32 v[16:17], v[82:83], v[76:77], v[16:17] op_sel_hi:[1,0,1]
	v_pk_fma_f32 v[38:39], v[16:17], v[76:77], v[38:39] op_sel:[0,1,0] op_sel_hi:[1,1,1]
	s_waitcnt lgkmcnt(0)
	v_pk_fma_f32 v[18:19], v[82:83], v[78:79], v[18:19] op_sel_hi:[1,0,1]
	v_pk_fma_f32 v[38:39], v[18:19], v[78:79], v[38:39] op_sel:[0,1,0] op_sel_hi:[1,1,1]
	v_pk_fma_f32 v[20:21], v[82:83], v[80:81], v[20:21] op_sel_hi:[1,0,1]
	v_pk_fma_f32 v[38:39], v[20:21], v[80:81], v[38:39] op_sel:[0,1,0] op_sel_hi:[1,1,1]
	s_add_u32 s14, s14, 0x1000
	s_addc_u32 s15, s15, 0
	v_add_f32_dpp v38, v38, v38 row_ror:8 row_mask:0xf bank_mask:0x3 bound_ctrl:1
	v_add_f32_dpp v38, v39, v39 row_ror:8 row_mask:0xf bank_mask:0xc bound_ctrl:1
	ds_read_b64 v[64:65], v23 offset:38144
	ds_read_b128 v[48:51], v2 offset:61696
	v_add_f32_dpp v38, v38, v38 row_half_mirror row_mask:0xf bank_mask:0xf bound_ctrl:1
	ds_read_b128 v[52:55], v2 offset:61952
	ds_read_b128 v[56:59], v2 offset:62208
	v_add_f32_dpp v38, v38, v38 quad_perm:[1,0,3,2] row_mask:0xf bank_mask:0xf bound_ctrl:1
	ds_read_b128 v[60:63], v2 offset:62464
	s_nop 0
	v_add_f32_dpp v38, v38, v38 quad_perm:[2,3,0,1] row_mask:0xf bank_mask:0xf bound_ctrl:1
	v_cvt_pk_bf16_f32 v47, v38, v38
	global_store_short v28, v47, s[14:15] offset:-4096
	s_waitcnt lgkmcnt(3)
	v_pk_fma_f32 v[6:7], v[64:65], v[48:49], v[6:7] op_sel_hi:[1,0,1]
	v_pk_mul_f32 v[38:39], v[6:7], v[48:49] op_sel:[0,1] op_sel_hi:[1,1]
	v_pk_fma_f32 v[8:9], v[64:65], v[50:51], v[8:9] op_sel_hi:[1,0,1]
	v_pk_fma_f32 v[38:39], v[8:9], v[50:51], v[38:39] op_sel:[0,1,0] op_sel_hi:[1,1,1]
	s_waitcnt lgkmcnt(2)
	v_pk_fma_f32 v[10:11], v[64:65], v[52:53], v[10:11] op_sel_hi:[1,0,1]
	v_pk_fma_f32 v[38:39], v[10:11], v[52:53], v[38:39] op_sel:[0,1,0] op_sel_hi:[1,1,1]
	v_pk_fma_f32 v[12:13], v[64:65], v[54:55], v[12:13] op_sel_hi:[1,0,1]
	v_pk_fma_f32 v[38:39], v[12:13], v[54:55], v[38:39] op_sel:[0,1,0] op_sel_hi:[1,1,1]
	s_waitcnt lgkmcnt(1)
	v_pk_fma_f32 v[14:15], v[64:65], v[56:57], v[14:15] op_sel_hi:[1,0,1]
	v_pk_fma_f32 v[38:39], v[14:15], v[56:57], v[38:39] op_sel:[0,1,0] op_sel_hi:[1,1,1]
	v_pk_fma_f32 v[16:17], v[64:65], v[58:59], v[16:17] op_sel_hi:[1,0,1]
	v_pk_fma_f32 v[38:39], v[16:17], v[58:59], v[38:39] op_sel:[0,1,0] op_sel_hi:[1,1,1]
	s_waitcnt lgkmcnt(0)
	v_pk_fma_f32 v[18:19], v[64:65], v[60:61], v[18:19] op_sel_hi:[1,0,1]
	v_pk_fma_f32 v[38:39], v[18:19], v[60:61], v[38:39] op_sel:[0,1,0] op_sel_hi:[1,1,1]
	v_pk_fma_f32 v[20:21], v[64:65], v[62:63], v[20:21] op_sel_hi:[1,0,1]
	v_pk_fma_f32 v[38:39], v[20:21], v[62:63], v[38:39] op_sel:[0,1,0] op_sel_hi:[1,1,1]
	s_add_u32 s14, s14, 0x1000
	s_addc_u32 s15, s15, 0
	v_add_f32_dpp v38, v38, v38 row_ror:8 row_mask:0xf bank_mask:0x3 bound_ctrl:1
	v_add_f32_dpp v38, v39, v39 row_ror:8 row_mask:0xf bank_mask:0xc bound_ctrl:1
	ds_read_b64 v[82:83], v23 offset:38400
	ds_read_b128 v[66:69], v2 offset:62720
	v_add_f32_dpp v38, v38, v38 row_half_mirror row_mask:0xf bank_mask:0xf bound_ctrl:1
	ds_read_b128 v[70:73], v2 offset:62976
	ds_read_b128 v[74:77], v2 offset:63232
	v_add_f32_dpp v38, v38, v38 quad_perm:[1,0,3,2] row_mask:0xf bank_mask:0xf bound_ctrl:1
	ds_read_b128 v[78:81], v2 offset:63488
	s_nop 0
	v_add_f32_dpp v38, v38, v38 quad_perm:[2,3,0,1] row_mask:0xf bank_mask:0xf bound_ctrl:1
	v_cvt_pk_bf16_f32 v47, v38, v38
	global_store_short v28, v47, s[14:15] offset:-4096
	s_waitcnt lgkmcnt(3)
	v_pk_fma_f32 v[6:7], v[82:83], v[66:67], v[6:7] op_sel_hi:[1,0,1]
	v_pk_mul_f32 v[38:39], v[6:7], v[66:67] op_sel:[0,1] op_sel_hi:[1,1]
	v_pk_fma_f32 v[8:9], v[82:83], v[68:69], v[8:9] op_sel_hi:[1,0,1]
	v_pk_fma_f32 v[38:39], v[8:9], v[68:69], v[38:39] op_sel:[0,1,0] op_sel_hi:[1,1,1]
	s_waitcnt lgkmcnt(2)
	v_pk_fma_f32 v[10:11], v[82:83], v[70:71], v[10:11] op_sel_hi:[1,0,1]
	v_pk_fma_f32 v[38:39], v[10:11], v[70:71], v[38:39] op_sel:[0,1,0] op_sel_hi:[1,1,1]
	v_pk_fma_f32 v[12:13], v[82:83], v[72:73], v[12:13] op_sel_hi:[1,0,1]
	v_pk_fma_f32 v[38:39], v[12:13], v[72:73], v[38:39] op_sel:[0,1,0] op_sel_hi:[1,1,1]
	s_waitcnt lgkmcnt(1)
	v_pk_fma_f32 v[14:15], v[82:83], v[74:75], v[14:15] op_sel_hi:[1,0,1]
	v_pk_fma_f32 v[38:39], v[14:15], v[74:75], v[38:39] op_sel:[0,1,0] op_sel_hi:[1,1,1]
	v_pk_fma_f32 v[16:17], v[82:83], v[76:77], v[16:17] op_sel_hi:[1,0,1]
	v_pk_fma_f32 v[38:39], v[16:17], v[76:77], v[38:39] op_sel:[0,1,0] op_sel_hi:[1,1,1]
	s_waitcnt lgkmcnt(0)
	v_pk_fma_f32 v[18:19], v[82:83], v[78:79], v[18:19] op_sel_hi:[1,0,1]
	v_pk_fma_f32 v[38:39], v[18:19], v[78:79], v[38:39] op_sel:[0,1,0] op_sel_hi:[1,1,1]
	v_pk_fma_f32 v[20:21], v[82:83], v[80:81], v[20:21] op_sel_hi:[1,0,1]
	v_pk_fma_f32 v[38:39], v[20:21], v[80:81], v[38:39] op_sel:[0,1,0] op_sel_hi:[1,1,1]
	s_add_u32 s14, s14, 0x1000
	s_addc_u32 s15, s15, 0
	v_add_f32_dpp v38, v38, v38 row_ror:8 row_mask:0xf bank_mask:0x3 bound_ctrl:1
	v_add_f32_dpp v38, v39, v39 row_ror:8 row_mask:0xf bank_mask:0xc bound_ctrl:1
	ds_read_b64 v[64:65], v23 offset:38656
	ds_read_b128 v[48:51], v2 offset:63744
	v_add_f32_dpp v38, v38, v38 row_half_mirror row_mask:0xf bank_mask:0xf bound_ctrl:1
	ds_read_b128 v[52:55], v2 offset:64000
	ds_read_b128 v[56:59], v2 offset:64256
	v_add_f32_dpp v38, v38, v38 quad_perm:[1,0,3,2] row_mask:0xf bank_mask:0xf bound_ctrl:1
	ds_read_b128 v[60:63], v2 offset:64512
	s_nop 0
	v_add_f32_dpp v38, v38, v38 quad_perm:[2,3,0,1] row_mask:0xf bank_mask:0xf bound_ctrl:1
	v_cvt_pk_bf16_f32 v47, v38, v38
	global_store_short v28, v47, s[14:15] offset:-4096
	s_waitcnt lgkmcnt(3)
	v_pk_fma_f32 v[6:7], v[64:65], v[48:49], v[6:7] op_sel_hi:[1,0,1]
	v_pk_mul_f32 v[38:39], v[6:7], v[48:49] op_sel:[0,1] op_sel_hi:[1,1]
	v_pk_fma_f32 v[8:9], v[64:65], v[50:51], v[8:9] op_sel_hi:[1,0,1]
	v_pk_fma_f32 v[38:39], v[8:9], v[50:51], v[38:39] op_sel:[0,1,0] op_sel_hi:[1,1,1]
	s_waitcnt lgkmcnt(2)
	v_pk_fma_f32 v[10:11], v[64:65], v[52:53], v[10:11] op_sel_hi:[1,0,1]
	v_pk_fma_f32 v[38:39], v[10:11], v[52:53], v[38:39] op_sel:[0,1,0] op_sel_hi:[1,1,1]
	v_pk_fma_f32 v[12:13], v[64:65], v[54:55], v[12:13] op_sel_hi:[1,0,1]
	v_pk_fma_f32 v[38:39], v[12:13], v[54:55], v[38:39] op_sel:[0,1,0] op_sel_hi:[1,1,1]
	s_waitcnt lgkmcnt(1)
	v_pk_fma_f32 v[14:15], v[64:65], v[56:57], v[14:15] op_sel_hi:[1,0,1]
	v_pk_fma_f32 v[38:39], v[14:15], v[56:57], v[38:39] op_sel:[0,1,0] op_sel_hi:[1,1,1]
	v_pk_fma_f32 v[16:17], v[64:65], v[58:59], v[16:17] op_sel_hi:[1,0,1]
	v_pk_fma_f32 v[38:39], v[16:17], v[58:59], v[38:39] op_sel:[0,1,0] op_sel_hi:[1,1,1]
	s_waitcnt lgkmcnt(0)
	v_pk_fma_f32 v[18:19], v[64:65], v[60:61], v[18:19] op_sel_hi:[1,0,1]
	v_pk_fma_f32 v[38:39], v[18:19], v[60:61], v[38:39] op_sel:[0,1,0] op_sel_hi:[1,1,1]
	v_pk_fma_f32 v[20:21], v[64:65], v[62:63], v[20:21] op_sel_hi:[1,0,1]
	v_pk_fma_f32 v[38:39], v[20:21], v[62:63], v[38:39] op_sel:[0,1,0] op_sel_hi:[1,1,1]
	s_add_u32 s14, s14, 0x1000
	s_addc_u32 s15, s15, 0
	v_add_f32_dpp v38, v38, v38 row_ror:8 row_mask:0xf bank_mask:0x3 bound_ctrl:1
	v_add_f32_dpp v38, v39, v39 row_ror:8 row_mask:0xf bank_mask:0xc bound_ctrl:1
	ds_read_b64 v[82:83], v23 offset:38912
	ds_read_b128 v[66:69], v2 offset:64768
	v_add_f32_dpp v38, v38, v38 row_half_mirror row_mask:0xf bank_mask:0xf bound_ctrl:1
	ds_read_b128 v[70:73], v2 offset:65024
	ds_read_b128 v[74:77], v2 offset:65280
	v_add_f32_dpp v38, v38, v38 quad_perm:[1,0,3,2] row_mask:0xf bank_mask:0xf bound_ctrl:1
	ds_read_b128 v[78:81], v22 offset:32768
	s_nop 0
	v_add_f32_dpp v38, v38, v38 quad_perm:[2,3,0,1] row_mask:0xf bank_mask:0xf bound_ctrl:1
	v_cvt_pk_bf16_f32 v47, v38, v38
	global_store_short v28, v47, s[14:15] offset:-4096
	s_waitcnt lgkmcnt(3)
	v_pk_fma_f32 v[6:7], v[82:83], v[66:67], v[6:7] op_sel_hi:[1,0,1]
	v_pk_mul_f32 v[38:39], v[6:7], v[66:67] op_sel:[0,1] op_sel_hi:[1,1]
	v_pk_fma_f32 v[8:9], v[82:83], v[68:69], v[8:9] op_sel_hi:[1,0,1]
	v_pk_fma_f32 v[38:39], v[8:9], v[68:69], v[38:39] op_sel:[0,1,0] op_sel_hi:[1,1,1]
	s_waitcnt lgkmcnt(2)
	v_pk_fma_f32 v[10:11], v[82:83], v[70:71], v[10:11] op_sel_hi:[1,0,1]
	v_pk_fma_f32 v[38:39], v[10:11], v[70:71], v[38:39] op_sel:[0,1,0] op_sel_hi:[1,1,1]
	v_pk_fma_f32 v[12:13], v[82:83], v[72:73], v[12:13] op_sel_hi:[1,0,1]
	v_pk_fma_f32 v[38:39], v[12:13], v[72:73], v[38:39] op_sel:[0,1,0] op_sel_hi:[1,1,1]
	s_waitcnt lgkmcnt(1)
	v_pk_fma_f32 v[14:15], v[82:83], v[74:75], v[14:15] op_sel_hi:[1,0,1]
	v_pk_fma_f32 v[38:39], v[14:15], v[74:75], v[38:39] op_sel:[0,1,0] op_sel_hi:[1,1,1]
	v_pk_fma_f32 v[16:17], v[82:83], v[76:77], v[16:17] op_sel_hi:[1,0,1]
	v_pk_fma_f32 v[38:39], v[16:17], v[76:77], v[38:39] op_sel:[0,1,0] op_sel_hi:[1,1,1]
	s_waitcnt lgkmcnt(0)
	v_pk_fma_f32 v[18:19], v[82:83], v[78:79], v[18:19] op_sel_hi:[1,0,1]
	v_pk_fma_f32 v[38:39], v[18:19], v[78:79], v[38:39] op_sel:[0,1,0] op_sel_hi:[1,1,1]
	v_pk_fma_f32 v[20:21], v[82:83], v[80:81], v[20:21] op_sel_hi:[1,0,1]
	v_pk_fma_f32 v[38:39], v[20:21], v[80:81], v[38:39] op_sel:[0,1,0] op_sel_hi:[1,1,1]
	s_add_u32 s14, s14, 0x1000
	s_addc_u32 s15, s15, 0
	v_add_f32_dpp v38, v38, v38 row_ror:8 row_mask:0xf bank_mask:0x3 bound_ctrl:1
	v_add_f32_dpp v38, v39, v39 row_ror:8 row_mask:0xf bank_mask:0xc bound_ctrl:1
	ds_read_b64 v[64:65], v3 offset:20736
	ds_read_b128 v[48:51], v2 offset:8448
	v_add_f32_dpp v38, v38, v38 row_half_mirror row_mask:0xf bank_mask:0xf bound_ctrl:1
	ds_read_b128 v[52:55], v2 offset:8704
	ds_read_b128 v[56:59], v2 offset:8960
	v_add_f32_dpp v38, v38, v38 quad_perm:[1,0,3,2] row_mask:0xf bank_mask:0xf bound_ctrl:1
	ds_read_b128 v[60:63], v2 offset:9216
	s_nop 0
	v_add_f32_dpp v38, v38, v38 quad_perm:[2,3,0,1] row_mask:0xf bank_mask:0xf bound_ctrl:1
	v_cvt_pk_bf16_f32 v47, v38, v38
	global_store_short v28, v47, s[14:15] offset:-4096
	s_waitcnt vmcnt(8)
	v_lshlrev_b32_e32 v108, 16, v84
	v_lshlrev_b32_e32 v109, 16, v85
	v_and_b32_e32 v110, s17, v84
	v_and_b32_e32 v111, s17, v85
	v_lshlrev_b32_e32 v112, 16, v86
	v_lshlrev_b32_e32 v113, 16, v87
	v_and_b32_e32 v114, s17, v86
	v_and_b32_e32 v115, s17, v87
	v_lshlrev_b32_e32 v116, 16, v88
	v_and_b32_e32 v117, s17, v88
	v_rcp_f32_e32 v25, v24
	v_mul_f32_e32 v113, v24, v113
	v_mul_f32_e32 v115, v24, v115
	v_mul_f32_e32 v109, 0x3db504f3, v109
	v_mul_f32_e32 v111, 0x3db504f3, v111
	v_cndmask_b32_e64 v27, 1.0, v25, s[20:21]
	v_mul_f32_e32 v24, v24, v26
	v_mul_f32_e32 v116, v27, v116
	v_mul_f32_e32 v117, v27, v117
	ds_write_b128 v29, v[108:111] offset:24832
	ds_write_b128 v29, v[112:115] offset:33024
	ds_write_b64 v30, v[90:91] offset:24832
	ds_write_b64 v31, v[116:117] offset:24832
	s_add_i32 s16, s16, 8
	s_waitcnt lgkmcnt(0)
	s_barrier
	s_cmpk_lt_u32 s16, 0x800
	s_cbranch_scc1 .Lret2_loop

.Lgla2_loop:
	global_load_dword v110, v32, s[10:11]
	global_load_dword v111, v32, s[10:11] offset:-1024
	global_load_dword v112, v33, s[10:11]
	global_load_dword v113, v33, s[10:11] offset:-1024
	global_load_dword v114, v34, s[10:11]
	global_load_dword v116, v35, s[12:13]
	global_load_dword v117, v35, s[12:13] offset:4
	s_add_u32 s10, s10, 0x18000
	s_addc_u32 s11, s11, 0
	s_add_u32 s12, s12, 0x4000
	s_addc_u32 s13, s13, 0
	s_waitcnt lgkmcnt(4)
	v_pk_mul_f32 v[42:43], v[72:73], v[48:49] op_sel_hi:[1,0]
	v_pk_fma_f32 v[6:7], v[6:7], v[64:65], v[42:43] op_sel:[0,0,0] op_sel_hi:[1,0,1]
	v_pk_mul_f32 v[38:39], v[6:7], v[48:49] op_sel:[0,1] op_sel_hi:[1,1]
	v_pk_mul_f32 v[44:45], v[72:73], v[50:51] op_sel_hi:[1,0]
	v_pk_fma_f32 v[8:9], v[8:9], v[64:65], v[44:45] op_sel:[0,1,0] op_sel_hi:[1,1,1]
	v_pk_fma_f32 v[38:39], v[8:9], v[50:51], v[38:39] op_sel:[0,1,0] op_sel_hi:[1,1,1]
	s_waitcnt lgkmcnt(3)
	v_pk_mul_f32 v[42:43], v[72:73], v[52:53] op_sel_hi:[1,0]
	v_pk_fma_f32 v[10:11], v[10:11], v[66:67], v[42:43] op_sel:[0,0,0] op_sel_hi:[1,0,1]
	v_pk_fma_f32 v[38:39], v[10:11], v[52:53], v[38:39] op_sel:[0,1,0] op_sel_hi:[1,1,1]
	v_pk_mul_f32 v[44:45], v[72:73], v[54:55] op_sel_hi:[1,0]
	v_pk_fma_f32 v[12:13], v[12:13], v[66:67], v[44:45] op_sel:[0,1,0] op_sel_hi:[1,1,1]
	v_pk_fma_f32 v[38:39], v[12:13], v[54:55], v[38:39] op_sel:[0,1,0] op_sel_hi:[1,1,1]
	s_waitcnt lgkmcnt(1)
	v_pk_mul_f32 v[42:43], v[72:73], v[56:57] op_sel_hi:[1,0]
	v_pk_fma_f32 v[14:15], v[14:15], v[68:69], v[42:43] op_sel:[0,0,0] op_sel_hi:[1,0,1]
	v_pk_fma_f32 v[38:39], v[14:15], v[56:57], v[38:39] op_sel:[0,1,0] op_sel_hi:[1,1,1]
	v_pk_mul_f32 v[44:45], v[72:73], v[58:59] op_sel_hi:[1,0]
	v_pk_fma_f32 v[16:17], v[16:17], v[68:69], v[44:45] op_sel:[0,1,0] op_sel_hi:[1,1,1]
	v_pk_fma_f32 v[38:39], v[16:17], v[58:59], v[38:39] op_sel:[0,1,0] op_sel_hi:[1,1,1]
	s_waitcnt lgkmcnt(0)
	v_pk_mul_f32 v[42:43], v[72:73], v[60:61] op_sel_hi:[1,0]
	v_pk_fma_f32 v[18:19], v[18:19], v[70:71], v[42:43] op_sel:[0,0,0] op_sel_hi:[1,0,1]
	v_pk_fma_f32 v[38:39], v[18:19], v[60:61], v[38:39] op_sel:[0,1,0] op_sel_hi:[1,1,1]
	v_pk_mul_f32 v[44:45], v[72:73], v[62:63] op_sel_hi:[1,0]
	v_pk_fma_f32 v[20:21], v[20:21], v[70:71], v[44:45] op_sel:[0,1,0] op_sel_hi:[1,1,1]
	v_pk_fma_f32 v[38:39], v[20:21], v[62:63], v[38:39] op_sel:[0,1,0] op_sel_hi:[1,1,1]
	s_add_u32 s14, s14, 0x1000
	s_addc_u32 s15, s15, 0
	v_add_f32_dpp v38, v38, v38 row_ror:8 row_mask:0xf bank_mask:0x3 bound_ctrl:1
	v_add_f32_dpp v38, v39, v39 row_ror:8 row_mask:0xf bank_mask:0xc bound_ctrl:1
	ds_read_b64 v[104:105], v3 offset:20992
	ds_read_b128 v[80:83], v2 offset:1280
	v_add_f32_dpp v38, v38, v38 row_half_mirror row_mask:0xf bank_mask:0xf bound_ctrl:1
	ds_read_b128 v[96:99], v2 offset:17152
	ds_read_b128 v[84:87], v2 offset:1536
	v_add_f32_dpp v38, v38, v38 quad_perm:[1,0,3,2] row_mask:0xf bank_mask:0xf bound_ctrl:1
	ds_read_b128 v[88:91], v2 offset:1792
	ds_read_b128 v[100:103], v2 offset:17408
	v_add_f32_dpp v38, v38, v38 quad_perm:[2,3,0,1] row_mask:0xf bank_mask:0xf bound_ctrl:1
	ds_read_b128 v[92:95], v2 offset:2048
	v_cvt_pk_bf16_f32 v47, v38, v38
	global_store_short v28, v47, s[14:15] offset:-4096
	s_waitcnt lgkmcnt(4)
	v_pk_mul_f32 v[42:43], v[104:105], v[80:81] op_sel_hi:[1,0]
	v_pk_fma_f32 v[6:7], v[6:7], v[96:97], v[42:43] op_sel:[0,0,0] op_sel_hi:[1,0,1]
	v_pk_mul_f32 v[38:39], v[6:7], v[80:81] op_sel:[0,1] op_sel_hi:[1,1]
	v_pk_mul_f32 v[44:45], v[104:105], v[82:83] op_sel_hi:[1,0]
	v_pk_fma_f32 v[8:9], v[8:9], v[96:97], v[44:45] op_sel:[0,1,0] op_sel_hi:[1,1,1]
	v_pk_fma_f32 v[38:39], v[8:9], v[82:83], v[38:39] op_sel:[0,1,0] op_sel_hi:[1,1,1]
	s_waitcnt lgkmcnt(3)
	v_pk_mul_f32 v[42:43], v[104:105], v[84:85] op_sel_hi:[1,0]
	v_pk_fma_f32 v[10:11], v[10:11], v[98:99], v[42:43] op_sel:[0,0,0] op_sel_hi:[1,0,1]
	v_pk_fma_f32 v[38:39], v[10:11], v[84:85], v[38:39] op_sel:[0,1,0] op_sel_hi:[1,1,1]
	v_pk_mul_f32 v[44:45], v[104:105], v[86:87] op_sel_hi:[1,0]
	v_pk_fma_f32 v[12:13], v[12:13], v[98:99], v[44:45] op_sel:[0,1,0] op_sel_hi:[1,1,1]
	v_pk_fma_f32 v[38:39], v[12:13], v[86:87], v[38:39] op_sel:[0,1,0] op_sel_hi:[1,1,1]
	s_waitcnt lgkmcnt(1)
	v_pk_mul_f32 v[42:43], v[104:105], v[88:89] op_sel_hi:[1,0]
	v_pk_fma_f32 v[14:15], v[14:15], v[100:101], v[42:43] op_sel:[0,0,0] op_sel_hi:[1,0,1]
	v_pk_fma_f32 v[38:39], v[14:15], v[88:89], v[38:39] op_sel:[0,1,0] op_sel_hi:[1,1,1]
	v_pk_mul_f32 v[44:45], v[104:105], v[90:91] op_sel_hi:[1,0]
	v_pk_fma_f32 v[16:17], v[16:17], v[100:101], v[44:45] op_sel:[0,1,0] op_sel_hi:[1,1,1]
	v_pk_fma_f32 v[38:39], v[16:17], v[90:91], v[38:39] op_sel:[0,1,0] op_sel_hi:[1,1,1]
	s_waitcnt lgkmcnt(0)
	v_pk_mul_f32 v[42:43], v[104:105], v[92:93] op_sel_hi:[1,0]
	v_pk_fma_f32 v[18:19], v[18:19], v[102:103], v[42:43] op_sel:[0,0,0] op_sel_hi:[1,0,1]
	v_pk_fma_f32 v[38:39], v[18:19], v[92:93], v[38:39] op_sel:[0,1,0] op_sel_hi:[1,1,1]
	v_pk_mul_f32 v[44:45], v[104:105], v[94:95] op_sel_hi:[1,0]
	v_pk_fma_f32 v[20:21], v[20:21], v[102:103], v[44:45] op_sel:[0,1,0] op_sel_hi:[1,1,1]
	v_pk_fma_f32 v[38:39], v[20:21], v[94:95], v[38:39] op_sel:[0,1,0] op_sel_hi:[1,1,1]
	s_add_u32 s14, s14, 0x1000
	s_addc_u32 s15, s15, 0
	v_add_f32_dpp v38, v38, v38 row_ror:8 row_mask:0xf bank_mask:0x3 bound_ctrl:1
	v_add_f32_dpp v38, v39, v39 row_ror:8 row_mask:0xf bank_mask:0xc bound_ctrl:1
	ds_read_b64 v[72:73], v3 offset:21248
	ds_read_b128 v[48:51], v2 offset:2304
	v_add_f32_dpp v38, v38, v38 row_half_mirror row_mask:0xf bank_mask:0xf bound_ctrl:1
	ds_read_b128 v[64:67], v2 offset:17664
	ds_read_b128 v[52:55], v2 offset:2560
	v_add_f32_dpp v38, v38, v38 quad_perm:[1,0,3,2] row_mask:0xf bank_mask:0xf bound_ctrl:1
	ds_read_b128 v[56:59], v2 offset:2816
	ds_read_b128 v[68:71], v2 offset:17920
	v_add_f32_dpp v38, v38, v38 quad_perm:[2,3,0,1] row_mask:0xf bank_mask:0xf bound_ctrl:1
	ds_read_b128 v[60:63], v2 offset:3072
	v_cvt_pk_bf16_f32 v47, v38, v38
	global_store_short v28, v47, s[14:15] offset:-4096
	s_waitcnt lgkmcnt(4)
	v_pk_mul_f32 v[42:43], v[72:73], v[48:49] op_sel_hi:[1,0]
	v_pk_fma_f32 v[6:7], v[6:7], v[64:65], v[42:43] op_sel:[0,0,0] op_sel_hi:[1,0,1]
	v_pk_mul_f32 v[38:39], v[6:7], v[48:49] op_sel:[0,1] op_sel_hi:[1,1]
	v_pk_mul_f32 v[44:45], v[72:73], v[50:51] op_sel_hi:[1,0]
	v_pk_fma_f32 v[8:9], v[8:9], v[64:65], v[44:45] op_sel:[0,1,0] op_sel_hi:[1,1,1]
	v_pk_fma_f32 v[38:39], v[8:9], v[50:51], v[38:39] op_sel:[0,1,0] op_sel_hi:[1,1,1]
	s_waitcnt lgkmcnt(3)
	v_pk_mul_f32 v[42:43], v[72:73], v[52:53] op_sel_hi:[1,0]
	v_pk_fma_f32 v[10:11], v[10:11], v[66:67], v[42:43] op_sel:[0,0,0] op_sel_hi:[1,0,1]
	v_pk_fma_f32 v[38:39], v[10:11], v[52:53], v[38:39] op_sel:[0,1,0] op_sel_hi:[1,1,1]
	v_pk_mul_f32 v[44:45], v[72:73], v[54:55] op_sel_hi:[1,0]
	v_pk_fma_f32 v[12:13], v[12:13], v[66:67], v[44:45] op_sel:[0,1,0] op_sel_hi:[1,1,1]
	v_pk_fma_f32 v[38:39], v[12:13], v[54:55], v[38:39] op_sel:[0,1,0] op_sel_hi:[1,1,1]
	s_waitcnt lgkmcnt(1)
	v_pk_mul_f32 v[42:43], v[72:73], v[56:57] op_sel_hi:[1,0]
	v_pk_fma_f32 v[14:15], v[14:15], v[68:69], v[42:43] op_sel:[0,0,0] op_sel_hi:[1,0,1]
	v_pk_fma_f32 v[38:39], v[14:15], v[56:57], v[38:39] op_sel:[0,1,0] op_sel_hi:[1,1,1]
	v_pk_mul_f32 v[44:45], v[72:73], v[58:59] op_sel_hi:[1,0]
	v_pk_fma_f32 v[16:17], v[16:17], v[68:69], v[44:45] op_sel:[0,1,0] op_sel_hi:[1,1,1]
	v_pk_fma_f32 v[38:39], v[16:17], v[58:59], v[38:39] op_sel:[0,1,0] op_sel_hi:[1,1,1]
	s_waitcnt lgkmcnt(0)
	v_pk_mul_f32 v[42:43], v[72:73], v[60:61] op_sel_hi:[1,0]
	v_pk_fma_f32 v[18:19], v[18:19], v[70:71], v[42:43] op_sel:[0,0,0] op_sel_hi:[1,0,1]
	v_pk_fma_f32 v[38:39], v[18:19], v[60:61], v[38:39] op_sel:[0,1,0] op_sel_hi:[1,1,1]
	v_pk_mul_f32 v[44:45], v[72:73], v[62:63] op_sel_hi:[1,0]
	v_pk_fma_f32 v[20:21], v[20:21], v[70:71], v[44:45] op_sel:[0,1,0] op_sel_hi:[1,1,1]
	v_pk_fma_f32 v[38:39], v[20:21], v[62:63], v[38:39] op_sel:[0,1,0] op_sel_hi:[1,1,1]
	s_add_u32 s14, s14, 0x1000
	s_addc_u32 s15, s15, 0
	v_add_f32_dpp v38, v38, v38 row_ror:8 row_mask:0xf bank_mask:0x3 bound_ctrl:1
	v_add_f32_dpp v38, v39, v39 row_ror:8 row_mask:0xf bank_mask:0xc bound_ctrl:1
	ds_read_b64 v[104:105], v3 offset:21504
	ds_read_b128 v[80:83], v2 offset:3328
	v_add_f32_dpp v38, v38, v38 row_half_mirror row_mask:0xf bank_mask:0xf bound_ctrl:1
	ds_read_b128 v[96:99], v2 offset:18176
	ds_read_b128 v[84:87], v2 offset:3584
	v_add_f32_dpp v38, v38, v38 quad_perm:[1,0,3,2] row_mask:0xf bank_mask:0xf bound_ctrl:1
	ds_read_b128 v[88:91], v2 offset:3840
	ds_read_b128 v[100:103], v2 offset:18432
	v_add_f32_dpp v38, v38, v38 quad_perm:[2,3,0,1] row_mask:0xf bank_mask:0xf bound_ctrl:1
	ds_read_b128 v[92:95], v2 offset:4096
	v_cvt_pk_bf16_f32 v47, v38, v38
	global_store_short v28, v47, s[14:15] offset:-4096
	s_waitcnt lgkmcnt(4)
	v_pk_mul_f32 v[42:43], v[104:105], v[80:81] op_sel_hi:[1,0]
	v_pk_fma_f32 v[6:7], v[6:7], v[96:97], v[42:43] op_sel:[0,0,0] op_sel_hi:[1,0,1]
	v_pk_mul_f32 v[38:39], v[6:7], v[80:81] op_sel:[0,1] op_sel_hi:[1,1]
	v_pk_mul_f32 v[44:45], v[104:105], v[82:83] op_sel_hi:[1,0]
	v_pk_fma_f32 v[8:9], v[8:9], v[96:97], v[44:45] op_sel:[0,1,0] op_sel_hi:[1,1,1]
	v_pk_fma_f32 v[38:39], v[8:9], v[82:83], v[38:39] op_sel:[0,1,0] op_sel_hi:[1,1,1]
	s_waitcnt lgkmcnt(3)
	v_pk_mul_f32 v[42:43], v[104:105], v[84:85] op_sel_hi:[1,0]
	v_pk_fma_f32 v[10:11], v[10:11], v[98:99], v[42:43] op_sel:[0,0,0] op_sel_hi:[1,0,1]
	v_pk_fma_f32 v[38:39], v[10:11], v[84:85], v[38:39] op_sel:[0,1,0] op_sel_hi:[1,1,1]
	v_pk_mul_f32 v[44:45], v[104:105], v[86:87] op_sel_hi:[1,0]
	v_pk_fma_f32 v[12:13], v[12:13], v[98:99], v[44:45] op_sel:[0,1,0] op_sel_hi:[1,1,1]
	v_pk_fma_f32 v[38:39], v[12:13], v[86:87], v[38:39] op_sel:[0,1,0] op_sel_hi:[1,1,1]
	s_waitcnt lgkmcnt(1)
	v_pk_mul_f32 v[42:43], v[104:105], v[88:89] op_sel_hi:[1,0]
	v_pk_fma_f32 v[14:15], v[14:15], v[100:101], v[42:43] op_sel:[0,0,0] op_sel_hi:[1,0,1]
	v_pk_fma_f32 v[38:39], v[14:15], v[88:89], v[38:39] op_sel:[0,1,0] op_sel_hi:[1,1,1]
	v_pk_mul_f32 v[44:45], v[104:105], v[90:91] op_sel_hi:[1,0]
	v_pk_fma_f32 v[16:17], v[16:17], v[100:101], v[44:45] op_sel:[0,1,0] op_sel_hi:[1,1,1]
	v_pk_fma_f32 v[38:39], v[16:17], v[90:91], v[38:39] op_sel:[0,1,0] op_sel_hi:[1,1,1]
	s_waitcnt lgkmcnt(0)
	v_pk_mul_f32 v[42:43], v[104:105], v[92:93] op_sel_hi:[1,0]
	v_pk_fma_f32 v[18:19], v[18:19], v[102:103], v[42:43] op_sel:[0,0,0] op_sel_hi:[1,0,1]
	v_pk_fma_f32 v[38:39], v[18:19], v[92:93], v[38:39] op_sel:[0,1,0] op_sel_hi:[1,1,1]
	v_pk_mul_f32 v[44:45], v[104:105], v[94:95] op_sel_hi:[1,0]
	v_pk_fma_f32 v[20:21], v[20:21], v[102:103], v[44:45] op_sel:[0,1,0] op_sel_hi:[1,1,1]
	v_pk_fma_f32 v[38:39], v[20:21], v[94:95], v[38:39] op_sel:[0,1,0] op_sel_hi:[1,1,1]
	s_add_u32 s14, s14, 0x1000
	s_addc_u32 s15, s15, 0
	v_add_f32_dpp v38, v38, v38 row_ror:8 row_mask:0xf bank_mask:0x3 bound_ctrl:1
	v_add_f32_dpp v38, v39, v39 row_ror:8 row_mask:0xf bank_mask:0xc bound_ctrl:1
	ds_read_b64 v[72:73], v3 offset:21760
	ds_read_b128 v[48:51], v2 offset:4352
	v_add_f32_dpp v38, v38, v38 row_half_mirror row_mask:0xf bank_mask:0xf bound_ctrl:1
	ds_read_b128 v[64:67], v2 offset:18688
	ds_read_b128 v[52:55], v2 offset:4608
	v_add_f32_dpp v38, v38, v38 quad_perm:[1,0,3,2] row_mask:0xf bank_mask:0xf bound_ctrl:1
	ds_read_b128 v[56:59], v2 offset:4864
	ds_read_b128 v[68:71], v2 offset:18944
	v_add_f32_dpp v38, v38, v38 quad_perm:[2,3,0,1] row_mask:0xf bank_mask:0xf bound_ctrl:1
	ds_read_b128 v[60:63], v2 offset:5120
	v_cvt_pk_bf16_f32 v47, v38, v38
	global_store_short v28, v47, s[14:15] offset:-4096
	s_waitcnt lgkmcnt(4)
	v_pk_mul_f32 v[42:43], v[72:73], v[48:49] op_sel_hi:[1,0]
	v_pk_fma_f32 v[6:7], v[6:7], v[64:65], v[42:43] op_sel:[0,0,0] op_sel_hi:[1,0,1]
	v_pk_mul_f32 v[38:39], v[6:7], v[48:49] op_sel:[0,1] op_sel_hi:[1,1]
	v_pk_mul_f32 v[44:45], v[72:73], v[50:51] op_sel_hi:[1,0]
	v_pk_fma_f32 v[8:9], v[8:9], v[64:65], v[44:45] op_sel:[0,1,0] op_sel_hi:[1,1,1]
	v_pk_fma_f32 v[38:39], v[8:9], v[50:51], v[38:39] op_sel:[0,1,0] op_sel_hi:[1,1,1]
	s_waitcnt lgkmcnt(3)
	v_pk_mul_f32 v[42:43], v[72:73], v[52:53] op_sel_hi:[1,0]
	v_pk_fma_f32 v[10:11], v[10:11], v[66:67], v[42:43] op_sel:[0,0,0] op_sel_hi:[1,0,1]
	v_pk_fma_f32 v[38:39], v[10:11], v[52:53], v[38:39] op_sel:[0,1,0] op_sel_hi:[1,1,1]
	v_pk_mul_f32 v[44:45], v[72:73], v[54:55] op_sel_hi:[1,0]
	v_pk_fma_f32 v[12:13], v[12:13], v[66:67], v[44:45] op_sel:[0,1,0] op_sel_hi:[1,1,1]
	v_pk_fma_f32 v[38:39], v[12:13], v[54:55], v[38:39] op_sel:[0,1,0] op_sel_hi:[1,1,1]
	s_waitcnt lgkmcnt(1)
	v_pk_mul_f32 v[42:43], v[72:73], v[56:57] op_sel_hi:[1,0]
	v_pk_fma_f32 v[14:15], v[14:15], v[68:69], v[42:43] op_sel:[0,0,0] op_sel_hi:[1,0,1]
	v_pk_fma_f32 v[38:39], v[14:15], v[56:57], v[38:39] op_sel:[0,1,0] op_sel_hi:[1,1,1]
	v_pk_mul_f32 v[44:45], v[72:73], v[58:59] op_sel_hi:[1,0]
	v_pk_fma_f32 v[16:17], v[16:17], v[68:69], v[44:45] op_sel:[0,1,0] op_sel_hi:[1,1,1]
	v_pk_fma_f32 v[38:39], v[16:17], v[58:59], v[38:39] op_sel:[0,1,0] op_sel_hi:[1,1,1]
	s_waitcnt lgkmcnt(0)
	v_pk_mul_f32 v[42:43], v[72:73], v[60:61] op_sel_hi:[1,0]
	v_pk_fma_f32 v[18:19], v[18:19], v[70:71], v[42:43] op_sel:[0,0,0] op_sel_hi:[1,0,1]
	v_pk_fma_f32 v[38:39], v[18:19], v[60:61], v[38:39] op_sel:[0,1,0] op_sel_hi:[1,1,1]
	v_pk_mul_f32 v[44:45], v[72:73], v[62:63] op_sel_hi:[1,0]
	v_pk_fma_f32 v[20:21], v[20:21], v[70:71], v[44:45] op_sel:[0,1,0] op_sel_hi:[1,1,1]
	v_pk_fma_f32 v[38:39], v[20:21], v[62:63], v[38:39] op_sel:[0,1,0] op_sel_hi:[1,1,1]
	s_add_u32 s14, s14, 0x1000
	s_addc_u32 s15, s15, 0
	v_add_f32_dpp v38, v38, v38 row_ror:8 row_mask:0xf bank_mask:0x3 bound_ctrl:1
	v_add_f32_dpp v38, v39, v39 row_ror:8 row_mask:0xf bank_mask:0xc bound_ctrl:1
	ds_read_b64 v[104:105], v3 offset:22016
	ds_read_b128 v[80:83], v2 offset:5376
	v_add_f32_dpp v38, v38, v38 row_half_mirror row_mask:0xf bank_mask:0xf bound_ctrl:1
	ds_read_b128 v[96:99], v2 offset:19200
	ds_read_b128 v[84:87], v2 offset:5632
	v_add_f32_dpp v38, v38, v38 quad_perm:[1,0,3,2] row_mask:0xf bank_mask:0xf bound_ctrl:1
	ds_read_b128 v[88:91], v2 offset:5888
	ds_read_b128 v[100:103], v2 offset:19456
	v_add_f32_dpp v38, v38, v38 quad_perm:[2,3,0,1] row_mask:0xf bank_mask:0xf bound_ctrl:1
	ds_read_b128 v[92:95], v2 offset:6144
	v_cvt_pk_bf16_f32 v47, v38, v38
	global_store_short v28, v47, s[14:15] offset:-4096
	s_waitcnt lgkmcnt(4)
	v_pk_mul_f32 v[42:43], v[104:105], v[80:81] op_sel_hi:[1,0]
	v_pk_fma_f32 v[6:7], v[6:7], v[96:97], v[42:43] op_sel:[0,0,0] op_sel_hi:[1,0,1]
	v_pk_mul_f32 v[38:39], v[6:7], v[80:81] op_sel:[0,1] op_sel_hi:[1,1]
	v_pk_mul_f32 v[44:45], v[104:105], v[82:83] op_sel_hi:[1,0]
	v_pk_fma_f32 v[8:9], v[8:9], v[96:97], v[44:45] op_sel:[0,1,0] op_sel_hi:[1,1,1]
	v_pk_fma_f32 v[38:39], v[8:9], v[82:83], v[38:39] op_sel:[0,1,0] op_sel_hi:[1,1,1]
	s_waitcnt lgkmcnt(3)
	v_pk_mul_f32 v[42:43], v[104:105], v[84:85] op_sel_hi:[1,0]
	v_pk_fma_f32 v[10:11], v[10:11], v[98:99], v[42:43] op_sel:[0,0,0] op_sel_hi:[1,0,1]
	v_pk_fma_f32 v[38:39], v[10:11], v[84:85], v[38:39] op_sel:[0,1,0] op_sel_hi:[1,1,1]
	v_pk_mul_f32 v[44:45], v[104:105], v[86:87] op_sel_hi:[1,0]
	v_pk_fma_f32 v[12:13], v[12:13], v[98:99], v[44:45] op_sel:[0,1,0] op_sel_hi:[1,1,1]
	v_pk_fma_f32 v[38:39], v[12:13], v[86:87], v[38:39] op_sel:[0,1,0] op_sel_hi:[1,1,1]
	s_waitcnt lgkmcnt(1)
	v_pk_mul_f32 v[42:43], v[104:105], v[88:89] op_sel_hi:[1,0]
	v_pk_fma_f32 v[14:15], v[14:15], v[100:101], v[42:43] op_sel:[0,0,0] op_sel_hi:[1,0,1]
	v_pk_fma_f32 v[38:39], v[14:15], v[88:89], v[38:39] op_sel:[0,1,0] op_sel_hi:[1,1,1]
	v_pk_mul_f32 v[44:45], v[104:105], v[90:91] op_sel_hi:[1,0]
	v_pk_fma_f32 v[16:17], v[16:17], v[100:101], v[44:45] op_sel:[0,1,0] op_sel_hi:[1,1,1]
	v_pk_fma_f32 v[38:39], v[16:17], v[90:91], v[38:39] op_sel:[0,1,0] op_sel_hi:[1,1,1]
	s_waitcnt lgkmcnt(0)
	v_pk_mul_f32 v[42:43], v[104:105], v[92:93] op_sel_hi:[1,0]
	v_pk_fma_f32 v[18:19], v[18:19], v[102:103], v[42:43] op_sel:[0,0,0] op_sel_hi:[1,0,1]
	v_pk_fma_f32 v[38:39], v[18:19], v[92:93], v[38:39] op_sel:[0,1,0] op_sel_hi:[1,1,1]
	v_pk_mul_f32 v[44:45], v[104:105], v[94:95] op_sel_hi:[1,0]
	v_pk_fma_f32 v[20:21], v[20:21], v[102:103], v[44:45] op_sel:[0,1,0] op_sel_hi:[1,1,1]
	v_pk_fma_f32 v[38:39], v[20:21], v[94:95], v[38:39] op_sel:[0,1,0] op_sel_hi:[1,1,1]
	s_add_u32 s14, s14, 0x1000
	s_addc_u32 s15, s15, 0
	v_add_f32_dpp v38, v38, v38 row_ror:8 row_mask:0xf bank_mask:0x3 bound_ctrl:1
	v_add_f32_dpp v38, v39, v39 row_ror:8 row_mask:0xf bank_mask:0xc bound_ctrl:1
	ds_read_b64 v[72:73], v3 offset:22272
	ds_read_b128 v[48:51], v2 offset:6400
	v_add_f32_dpp v38, v38, v38 row_half_mirror row_mask:0xf bank_mask:0xf bound_ctrl:1
	ds_read_b128 v[64:67], v2 offset:19712
	ds_read_b128 v[52:55], v2 offset:6656
	v_add_f32_dpp v38, v38, v38 quad_perm:[1,0,3,2] row_mask:0xf bank_mask:0xf bound_ctrl:1
	ds_read_b128 v[56:59], v2 offset:6912
	ds_read_b128 v[68:71], v2 offset:19968
	v_add_f32_dpp v38, v38, v38 quad_perm:[2,3,0,1] row_mask:0xf bank_mask:0xf bound_ctrl:1
	ds_read_b128 v[60:63], v2 offset:7168
	v_cvt_pk_bf16_f32 v47, v38, v38
	global_store_short v28, v47, s[14:15] offset:-4096
	s_waitcnt lgkmcnt(4)
	v_pk_mul_f32 v[42:43], v[72:73], v[48:49] op_sel_hi:[1,0]
	v_pk_fma_f32 v[6:7], v[6:7], v[64:65], v[42:43] op_sel:[0,0,0] op_sel_hi:[1,0,1]
	v_pk_mul_f32 v[38:39], v[6:7], v[48:49] op_sel:[0,1] op_sel_hi:[1,1]
	v_pk_mul_f32 v[44:45], v[72:73], v[50:51] op_sel_hi:[1,0]
	v_pk_fma_f32 v[8:9], v[8:9], v[64:65], v[44:45] op_sel:[0,1,0] op_sel_hi:[1,1,1]
	v_pk_fma_f32 v[38:39], v[8:9], v[50:51], v[38:39] op_sel:[0,1,0] op_sel_hi:[1,1,1]
	s_waitcnt lgkmcnt(3)
	v_pk_mul_f32 v[42:43], v[72:73], v[52:53] op_sel_hi:[1,0]
	v_pk_fma_f32 v[10:11], v[10:11], v[66:67], v[42:43] op_sel:[0,0,0] op_sel_hi:[1,0,1]
	v_pk_fma_f32 v[38:39], v[10:11], v[52:53], v[38:39] op_sel:[0,1,0] op_sel_hi:[1,1,1]
	v_pk_mul_f32 v[44:45], v[72:73], v[54:55] op_sel_hi:[1,0]
	v_pk_fma_f32 v[12:13], v[12:13], v[66:67], v[44:45] op_sel:[0,1,0] op_sel_hi:[1,1,1]
	v_pk_fma_f32 v[38:39], v[12:13], v[54:55], v[38:39] op_sel:[0,1,0] op_sel_hi:[1,1,1]
	s_waitcnt lgkmcnt(1)
	v_pk_mul_f32 v[42:43], v[72:73], v[56:57] op_sel_hi:[1,0]
	v_pk_fma_f32 v[14:15], v[14:15], v[68:69], v[42:43] op_sel:[0,0,0] op_sel_hi:[1,0,1]
	v_pk_fma_f32 v[38:39], v[14:15], v[56:57], v[38:39] op_sel:[0,1,0] op_sel_hi:[1,1,1]
	v_pk_mul_f32 v[44:45], v[72:73], v[58:59] op_sel_hi:[1,0]
	v_pk_fma_f32 v[16:17], v[16:17], v[68:69], v[44:45] op_sel:[0,1,0] op_sel_hi:[1,1,1]
	v_pk_fma_f32 v[38:39], v[16:17], v[58:59], v[38:39] op_sel:[0,1,0] op_sel_hi:[1,1,1]
	s_waitcnt lgkmcnt(0)
	v_pk_mul_f32 v[42:43], v[72:73], v[60:61] op_sel_hi:[1,0]
	v_pk_fma_f32 v[18:19], v[18:19], v[70:71], v[42:43] op_sel:[0,0,0] op_sel_hi:[1,0,1]
	v_pk_fma_f32 v[38:39], v[18:19], v[60:61], v[38:39] op_sel:[0,1,0] op_sel_hi:[1,1,1]
	v_pk_mul_f32 v[44:45], v[72:73], v[62:63] op_sel_hi:[1,0]
	v_pk_fma_f32 v[20:21], v[20:21], v[70:71], v[44:45] op_sel:[0,1,0] op_sel_hi:[1,1,1]
	v_pk_fma_f32 v[38:39], v[20:21], v[62:63], v[38:39] op_sel:[0,1,0] op_sel_hi:[1,1,1]
	s_add_u32 s14, s14, 0x1000
	s_addc_u32 s15, s15, 0
	v_add_f32_dpp v38, v38, v38 row_ror:8 row_mask:0xf bank_mask:0x3 bound_ctrl:1
	v_add_f32_dpp v38, v39, v39 row_ror:8 row_mask:0xf bank_mask:0xc bound_ctrl:1
	ds_read_b64 v[104:105], v3 offset:22528
	ds_read_b128 v[80:83], v2 offset:7424
	v_add_f32_dpp v38, v38, v38 row_half_mirror row_mask:0xf bank_mask:0xf bound_ctrl:1
	ds_read_b128 v[96:99], v2 offset:20224
	ds_read_b128 v[84:87], v2 offset:7680
	v_add_f32_dpp v38, v38, v38 quad_perm:[1,0,3,2] row_mask:0xf bank_mask:0xf bound_ctrl:1
	ds_read_b128 v[88:91], v2 offset:7936
	ds_read_b128 v[100:103], v2 offset:20480
	v_add_f32_dpp v38, v38, v38 quad_perm:[2,3,0,1] row_mask:0xf bank_mask:0xf bound_ctrl:1
	ds_read_b128 v[92:95], v2 offset:8192
	v_cvt_pk_bf16_f32 v47, v38, v38
	global_store_short v28, v47, s[14:15] offset:-4096
	s_waitcnt lgkmcnt(4)
	v_pk_mul_f32 v[42:43], v[104:105], v[80:81] op_sel_hi:[1,0]
	v_pk_fma_f32 v[6:7], v[6:7], v[96:97], v[42:43] op_sel:[0,0,0] op_sel_hi:[1,0,1]
	v_pk_mul_f32 v[38:39], v[6:7], v[80:81] op_sel:[0,1] op_sel_hi:[1,1]
	v_pk_mul_f32 v[44:45], v[104:105], v[82:83] op_sel_hi:[1,0]
	v_pk_fma_f32 v[8:9], v[8:9], v[96:97], v[44:45] op_sel:[0,1,0] op_sel_hi:[1,1,1]
	v_pk_fma_f32 v[38:39], v[8:9], v[82:83], v[38:39] op_sel:[0,1,0] op_sel_hi:[1,1,1]
	s_waitcnt lgkmcnt(3)
	v_pk_mul_f32 v[42:43], v[104:105], v[84:85] op_sel_hi:[1,0]
	v_pk_fma_f32 v[10:11], v[10:11], v[98:99], v[42:43] op_sel:[0,0,0] op_sel_hi:[1,0,1]
	v_pk_fma_f32 v[38:39], v[10:11], v[84:85], v[38:39] op_sel:[0,1,0] op_sel_hi:[1,1,1]
	v_pk_mul_f32 v[44:45], v[104:105], v[86:87] op_sel_hi:[1,0]
	v_pk_fma_f32 v[12:13], v[12:13], v[98:99], v[44:45] op_sel:[0,1,0] op_sel_hi:[1,1,1]
	v_pk_fma_f32 v[38:39], v[12:13], v[86:87], v[38:39] op_sel:[0,1,0] op_sel_hi:[1,1,1]
	s_waitcnt lgkmcnt(1)
	v_pk_mul_f32 v[42:43], v[104:105], v[88:89] op_sel_hi:[1,0]
	v_pk_fma_f32 v[14:15], v[14:15], v[100:101], v[42:43] op_sel:[0,0,0] op_sel_hi:[1,0,1]
	v_pk_fma_f32 v[38:39], v[14:15], v[88:89], v[38:39] op_sel:[0,1,0] op_sel_hi:[1,1,1]
	v_pk_mul_f32 v[44:45], v[104:105], v[90:91] op_sel_hi:[1,0]
	v_pk_fma_f32 v[16:17], v[16:17], v[100:101], v[44:45] op_sel:[0,1,0] op_sel_hi:[1,1,1]
	v_pk_fma_f32 v[38:39], v[16:17], v[90:91], v[38:39] op_sel:[0,1,0] op_sel_hi:[1,1,1]
	s_waitcnt lgkmcnt(0)
	v_pk_mul_f32 v[42:43], v[104:105], v[92:93] op_sel_hi:[1,0]
	v_pk_fma_f32 v[18:19], v[18:19], v[102:103], v[42:43] op_sel:[0,0,0] op_sel_hi:[1,0,1]
	v_pk_fma_f32 v[38:39], v[18:19], v[92:93], v[38:39] op_sel:[0,1,0] op_sel_hi:[1,1,1]
	v_pk_mul_f32 v[44:45], v[104:105], v[94:95] op_sel_hi:[1,0]
	v_pk_fma_f32 v[20:21], v[20:21], v[102:103], v[44:45] op_sel:[0,1,0] op_sel_hi:[1,1,1]
	v_pk_fma_f32 v[38:39], v[20:21], v[94:95], v[38:39] op_sel:[0,1,0] op_sel_hi:[1,1,1]
	s_add_u32 s14, s14, 0x1000
	s_addc_u32 s15, s15, 0
	v_add_f32_dpp v38, v38, v38 row_ror:8 row_mask:0xf bank_mask:0x3 bound_ctrl:1
	v_add_f32_dpp v38, v39, v39 row_ror:8 row_mask:0xf bank_mask:0xc bound_ctrl:1
	ds_read_b64 v[72:73], v3 offset:45312
	ds_read_b128 v[48:51], v2 offset:24832
	v_add_f32_dpp v38, v38, v38 row_half_mirror row_mask:0xf bank_mask:0xf bound_ctrl:1
	ds_read_b128 v[64:67], v2 offset:41216
	ds_read_b128 v[52:55], v2 offset:25088
	v_add_f32_dpp v38, v38, v38 quad_perm:[1,0,3,2] row_mask:0xf bank_mask:0xf bound_ctrl:1
	ds_read_b128 v[56:59], v2 offset:25344
	ds_read_b128 v[68:71], v2 offset:41472
	v_add_f32_dpp v38, v38, v38 quad_perm:[2,3,0,1] row_mask:0xf bank_mask:0xf bound_ctrl:1
	ds_read_b128 v[60:63], v2 offset:25600
	v_cvt_pk_bf16_f32 v47, v38, v38
	global_store_short v28, v47, s[14:15] offset:-4096
	s_waitcnt vmcnt(8)
	v_lshlrev_b32_e32 v144, 16, v110
	v_lshlrev_b32_e32 v145, 16, v111
	v_and_b32_e32 v146, s17, v110
	v_and_b32_e32 v147, s17, v111
	v_lshlrev_b32_e32 v148, 16, v112
	v_lshlrev_b32_e32 v149, 16, v113
	v_and_b32_e32 v150, s17, v112
	v_and_b32_e32 v151, s17, v113
	v_lshlrev_b32_e32 v152, 16, v114
	v_and_b32_e32 v153, s17, v114
	v_rcp_f32_e32 v25, v24
	v_mul_f32_e32 v149, v24, v149
	v_mul_f32_e32 v151, v24, v151
	v_mul_f32_e32 v145, 0x3db504f3, v145
	v_mul_f32_e32 v147, 0x3db504f3, v147
	v_cndmask_b32_e64 v27, 1.0, v25, s[20:21]
	v_mul_f32_e32 v24, v24, v26
	v_mul_f32_e32 v152, v27, v152
	v_mul_f32_e32 v153, v27, v153
	ds_write_b128 v29, v[144:147] offset:49408
	ds_write_b128 v29, v[148:151] offset:57600
	ds_write_b64 v30, v[116:117] offset:49408
	ds_write_b64 v31, v[152:153] offset:49408
	s_add_i32 s16, s16, 8
	s_waitcnt lgkmcnt(0)
	s_barrier
	s_cmpk_lt_u32 s16, 0x800
	s_cbranch_scc0 .Lgla2_done
	global_load_dword v110, v32, s[10:11]
	global_load_dword v111, v32, s[10:11] offset:-1024
	global_load_dword v112, v33, s[10:11]
	global_load_dword v113, v33, s[10:11] offset:-1024
	global_load_dword v114, v34, s[10:11]
	global_load_dword v116, v35, s[12:13]
	global_load_dword v117, v35, s[12:13] offset:4
	s_add_u32 s10, s10, 0x18000
	s_addc_u32 s11, s11, 0
	s_add_u32 s12, s12, 0x4000
	s_addc_u32 s13, s13, 0
	s_waitcnt lgkmcnt(4)
	v_pk_mul_f32 v[42:43], v[72:73], v[48:49] op_sel_hi:[1,0]
	v_pk_fma_f32 v[6:7], v[6:7], v[64:65], v[42:43] op_sel:[0,0,0] op_sel_hi:[1,0,1]
	v_pk_mul_f32 v[38:39], v[6:7], v[48:49] op_sel:[0,1] op_sel_hi:[1,1]
	v_pk_mul_f32 v[44:45], v[72:73], v[50:51] op_sel_hi:[1,0]
	v_pk_fma_f32 v[8:9], v[8:9], v[64:65], v[44:45] op_sel:[0,1,0] op_sel_hi:[1,1,1]
	v_pk_fma_f32 v[38:39], v[8:9], v[50:51], v[38:39] op_sel:[0,1,0] op_sel_hi:[1,1,1]
	s_waitcnt lgkmcnt(3)
	v_pk_mul_f32 v[42:43], v[72:73], v[52:53] op_sel_hi:[1,0]
	v_pk_fma_f32 v[10:11], v[10:11], v[66:67], v[42:43] op_sel:[0,0,0] op_sel_hi:[1,0,1]
	v_pk_fma_f32 v[38:39], v[10:11], v[52:53], v[38:39] op_sel:[0,1,0] op_sel_hi:[1,1,1]
	v_pk_mul_f32 v[44:45], v[72:73], v[54:55] op_sel_hi:[1,0]
	v_pk_fma_f32 v[12:13], v[12:13], v[66:67], v[44:45] op_sel:[0,1,0] op_sel_hi:[1,1,1]
	v_pk_fma_f32 v[38:39], v[12:13], v[54:55], v[38:39] op_sel:[0,1,0] op_sel_hi:[1,1,1]
	s_waitcnt lgkmcnt(1)
	v_pk_mul_f32 v[42:43], v[72:73], v[56:57] op_sel_hi:[1,0]
	v_pk_fma_f32 v[14:15], v[14:15], v[68:69], v[42:43] op_sel:[0,0,0] op_sel_hi:[1,0,1]
	v_pk_fma_f32 v[38:39], v[14:15], v[56:57], v[38:39] op_sel:[0,1,0] op_sel_hi:[1,1,1]
	v_pk_mul_f32 v[44:45], v[72:73], v[58:59] op_sel_hi:[1,0]
	v_pk_fma_f32 v[16:17], v[16:17], v[68:69], v[44:45] op_sel:[0,1,0] op_sel_hi:[1,1,1]
	v_pk_fma_f32 v[38:39], v[16:17], v[58:59], v[38:39] op_sel:[0,1,0] op_sel_hi:[1,1,1]
	s_waitcnt lgkmcnt(0)
	v_pk_mul_f32 v[42:43], v[72:73], v[60:61] op_sel_hi:[1,0]
	v_pk_fma_f32 v[18:19], v[18:19], v[70:71], v[42:43] op_sel:[0,0,0] op_sel_hi:[1,0,1]
	v_pk_fma_f32 v[38:39], v[18:19], v[60:61], v[38:39] op_sel:[0,1,0] op_sel_hi:[1,1,1]
	v_pk_mul_f32 v[44:45], v[72:73], v[62:63] op_sel_hi:[1,0]
	v_pk_fma_f32 v[20:21], v[20:21], v[70:71], v[44:45] op_sel:[0,1,0] op_sel_hi:[1,1,1]
	v_pk_fma_f32 v[38:39], v[20:21], v[62:63], v[38:39] op_sel:[0,1,0] op_sel_hi:[1,1,1]
	s_add_u32 s14, s14, 0x1000
	s_addc_u32 s15, s15, 0
	v_add_f32_dpp v38, v38, v38 row_ror:8 row_mask:0xf bank_mask:0x3 bound_ctrl:1
	v_add_f32_dpp v38, v39, v39 row_ror:8 row_mask:0xf bank_mask:0xc bound_ctrl:1
	ds_read_b64 v[104:105], v3 offset:45568
	ds_read_b128 v[80:83], v2 offset:25856
	v_add_f32_dpp v38, v38, v38 row_half_mirror row_mask:0xf bank_mask:0xf bound_ctrl:1
	ds_read_b128 v[96:99], v2 offset:41728
	ds_read_b128 v[84:87], v2 offset:26112
	v_add_f32_dpp v38, v38, v38 quad_perm:[1,0,3,2] row_mask:0xf bank_mask:0xf bound_ctrl:1
	ds_read_b128 v[88:91], v2 offset:26368
	ds_read_b128 v[100:103], v2 offset:41984
	v_add_f32_dpp v38, v38, v38 quad_perm:[2,3,0,1] row_mask:0xf bank_mask:0xf bound_ctrl:1
	ds_read_b128 v[92:95], v2 offset:26624
	v_cvt_pk_bf16_f32 v47, v38, v38
	global_store_short v28, v47, s[14:15] offset:-4096
	s_waitcnt lgkmcnt(4)
	v_pk_mul_f32 v[42:43], v[104:105], v[80:81] op_sel_hi:[1,0]
	v_pk_fma_f32 v[6:7], v[6:7], v[96:97], v[42:43] op_sel:[0,0,0] op_sel_hi:[1,0,1]
	v_pk_mul_f32 v[38:39], v[6:7], v[80:81] op_sel:[0,1] op_sel_hi:[1,1]
	v_pk_mul_f32 v[44:45], v[104:105], v[82:83] op_sel_hi:[1,0]
	v_pk_fma_f32 v[8:9], v[8:9], v[96:97], v[44:45] op_sel:[0,1,0] op_sel_hi:[1,1,1]
	v_pk_fma_f32 v[38:39], v[8:9], v[82:83], v[38:39] op_sel:[0,1,0] op_sel_hi:[1,1,1]
	s_waitcnt lgkmcnt(3)
	v_pk_mul_f32 v[42:43], v[104:105], v[84:85] op_sel_hi:[1,0]
	v_pk_fma_f32 v[10:11], v[10:11], v[98:99], v[42:43] op_sel:[0,0,0] op_sel_hi:[1,0,1]
	v_pk_fma_f32 v[38:39], v[10:11], v[84:85], v[38:39] op_sel:[0,1,0] op_sel_hi:[1,1,1]
	v_pk_mul_f32 v[44:45], v[104:105], v[86:87] op_sel_hi:[1,0]
	v_pk_fma_f32 v[12:13], v[12:13], v[98:99], v[44:45] op_sel:[0,1,0] op_sel_hi:[1,1,1]
	v_pk_fma_f32 v[38:39], v[12:13], v[86:87], v[38:39] op_sel:[0,1,0] op_sel_hi:[1,1,1]
	s_waitcnt lgkmcnt(1)
	v_pk_mul_f32 v[42:43], v[104:105], v[88:89] op_sel_hi:[1,0]
	v_pk_fma_f32 v[14:15], v[14:15], v[100:101], v[42:43] op_sel:[0,0,0] op_sel_hi:[1,0,1]
	v_pk_fma_f32 v[38:39], v[14:15], v[88:89], v[38:39] op_sel:[0,1,0] op_sel_hi:[1,1,1]
	v_pk_mul_f32 v[44:45], v[104:105], v[90:91] op_sel_hi:[1,0]
	v_pk_fma_f32 v[16:17], v[16:17], v[100:101], v[44:45] op_sel:[0,1,0] op_sel_hi:[1,1,1]
	v_pk_fma_f32 v[38:39], v[16:17], v[90:91], v[38:39] op_sel:[0,1,0] op_sel_hi:[1,1,1]
	s_waitcnt lgkmcnt(0)
	v_pk_mul_f32 v[42:43], v[104:105], v[92:93] op_sel_hi:[1,0]
	v_pk_fma_f32 v[18:19], v[18:19], v[102:103], v[42:43] op_sel:[0,0,0] op_sel_hi:[1,0,1]
	v_pk_fma_f32 v[38:39], v[18:19], v[92:93], v[38:39] op_sel:[0,1,0] op_sel_hi:[1,1,1]
	v_pk_mul_f32 v[44:45], v[104:105], v[94:95] op_sel_hi:[1,0]
	v_pk_fma_f32 v[20:21], v[20:21], v[102:103], v[44:45] op_sel:[0,1,0] op_sel_hi:[1,1,1]
	v_pk_fma_f32 v[38:39], v[20:21], v[94:95], v[38:39] op_sel:[0,1,0] op_sel_hi:[1,1,1]
	s_add_u32 s14, s14, 0x1000
	s_addc_u32 s15, s15, 0
	v_add_f32_dpp v38, v38, v38 row_ror:8 row_mask:0xf bank_mask:0x3 bound_ctrl:1
	v_add_f32_dpp v38, v39, v39 row_ror:8 row_mask:0xf bank_mask:0xc bound_ctrl:1
	ds_read_b64 v[72:73], v3 offset:45824
	ds_read_b128 v[48:51], v2 offset:26880
	v_add_f32_dpp v38, v38, v38 row_half_mirror row_mask:0xf bank_mask:0xf bound_ctrl:1
	ds_read_b128 v[64:67], v2 offset:42240
	ds_read_b128 v[52:55], v2 offset:27136
	v_add_f32_dpp v38, v38, v38 quad_perm:[1,0,3,2] row_mask:0xf bank_mask:0xf bound_ctrl:1
	ds_read_b128 v[56:59], v2 offset:27392
	ds_read_b128 v[68:71], v2 offset:42496
	v_add_f32_dpp v38, v38, v38 quad_perm:[2,3,0,1] row_mask:0xf bank_mask:0xf bound_ctrl:1
	ds_read_b128 v[60:63], v2 offset:27648
	v_cvt_pk_bf16_f32 v47, v38, v38
	global_store_short v28, v47, s[14:15] offset:-4096
	s_waitcnt lgkmcnt(4)
	v_pk_mul_f32 v[42:43], v[72:73], v[48:49] op_sel_hi:[1,0]
	v_pk_fma_f32 v[6:7], v[6:7], v[64:65], v[42:43] op_sel:[0,0,0] op_sel_hi:[1,0,1]
	v_pk_mul_f32 v[38:39], v[6:7], v[48:49] op_sel:[0,1] op_sel_hi:[1,1]
	v_pk_mul_f32 v[44:45], v[72:73], v[50:51] op_sel_hi:[1,0]
	v_pk_fma_f32 v[8:9], v[8:9], v[64:65], v[44:45] op_sel:[0,1,0] op_sel_hi:[1,1,1]
	v_pk_fma_f32 v[38:39], v[8:9], v[50:51], v[38:39] op_sel:[0,1,0] op_sel_hi:[1,1,1]
	s_waitcnt lgkmcnt(3)
	v_pk_mul_f32 v[42:43], v[72:73], v[52:53] op_sel_hi:[1,0]
	v_pk_fma_f32 v[10:11], v[10:11], v[66:67], v[42:43] op_sel:[0,0,0] op_sel_hi:[1,0,1]
	v_pk_fma_f32 v[38:39], v[10:11], v[52:53], v[38:39] op_sel:[0,1,0] op_sel_hi:[1,1,1]
	v_pk_mul_f32 v[44:45], v[72:73], v[54:55] op_sel_hi:[1,0]
	v_pk_fma_f32 v[12:13], v[12:13], v[66:67], v[44:45] op_sel:[0,1,0] op_sel_hi:[1,1,1]
	v_pk_fma_f32 v[38:39], v[12:13], v[54:55], v[38:39] op_sel:[0,1,0] op_sel_hi:[1,1,1]
	s_waitcnt lgkmcnt(1)
	v_pk_mul_f32 v[42:43], v[72:73], v[56:57] op_sel_hi:[1,0]
	v_pk_fma_f32 v[14:15], v[14:15], v[68:69], v[42:43] op_sel:[0,0,0] op_sel_hi:[1,0,1]
	v_pk_fma_f32 v[38:39], v[14:15], v[56:57], v[38:39] op_sel:[0,1,0] op_sel_hi:[1,1,1]
	v_pk_mul_f32 v[44:45], v[72:73], v[58:59] op_sel_hi:[1,0]
	v_pk_fma_f32 v[16:17], v[16:17], v[68:69], v[44:45] op_sel:[0,1,0] op_sel_hi:[1,1,1]
	v_pk_fma_f32 v[38:39], v[16:17], v[58:59], v[38:39] op_sel:[0,1,0] op_sel_hi:[1,1,1]
	s_waitcnt lgkmcnt(0)
	v_pk_mul_f32 v[42:43], v[72:73], v[60:61] op_sel_hi:[1,0]
	v_pk_fma_f32 v[18:19], v[18:19], v[70:71], v[42:43] op_sel:[0,0,0] op_sel_hi:[1,0,1]
	v_pk_fma_f32 v[38:39], v[18:19], v[60:61], v[38:39] op_sel:[0,1,0] op_sel_hi:[1,1,1]
	v_pk_mul_f32 v[44:45], v[72:73], v[62:63] op_sel_hi:[1,0]
	v_pk_fma_f32 v[20:21], v[20:21], v[70:71], v[44:45] op_sel:[0,1,0] op_sel_hi:[1,1,1]
	v_pk_fma_f32 v[38:39], v[20:21], v[62:63], v[38:39] op_sel:[0,1,0] op_sel_hi:[1,1,1]
	s_add_u32 s14, s14, 0x1000
	s_addc_u32 s15, s15, 0
	v_add_f32_dpp v38, v38, v38 row_ror:8 row_mask:0xf bank_mask:0x3 bound_ctrl:1
	v_add_f32_dpp v38, v39, v39 row_ror:8 row_mask:0xf bank_mask:0xc bound_ctrl:1
	ds_read_b64 v[104:105], v3 offset:46080
	ds_read_b128 v[80:83], v2 offset:27904
	v_add_f32_dpp v38, v38, v38 row_half_mirror row_mask:0xf bank_mask:0xf bound_ctrl:1
	ds_read_b128 v[96:99], v2 offset:42752
	ds_read_b128 v[84:87], v2 offset:28160
	v_add_f32_dpp v38, v38, v38 quad_perm:[1,0,3,2] row_mask:0xf bank_mask:0xf bound_ctrl:1
	ds_read_b128 v[88:91], v2 offset:28416
	ds_read_b128 v[100:103], v2 offset:43008
	v_add_f32_dpp v38, v38, v38 quad_perm:[2,3,0,1] row_mask:0xf bank_mask:0xf bound_ctrl:1
	ds_read_b128 v[92:95], v2 offset:28672
	v_cvt_pk_bf16_f32 v47, v38, v38
	global_store_short v28, v47, s[14:15] offset:-4096
	s_waitcnt lgkmcnt(4)
	v_pk_mul_f32 v[42:43], v[104:105], v[80:81] op_sel_hi:[1,0]
	v_pk_fma_f32 v[6:7], v[6:7], v[96:97], v[42:43] op_sel:[0,0,0] op_sel_hi:[1,0,1]
	v_pk_mul_f32 v[38:39], v[6:7], v[80:81] op_sel:[0,1] op_sel_hi:[1,1]
	v_pk_mul_f32 v[44:45], v[104:105], v[82:83] op_sel_hi:[1,0]
	v_pk_fma_f32 v[8:9], v[8:9], v[96:97], v[44:45] op_sel:[0,1,0] op_sel_hi:[1,1,1]
	v_pk_fma_f32 v[38:39], v[8:9], v[82:83], v[38:39] op_sel:[0,1,0] op_sel_hi:[1,1,1]
	s_waitcnt lgkmcnt(3)
	v_pk_mul_f32 v[42:43], v[104:105], v[84:85] op_sel_hi:[1,0]
	v_pk_fma_f32 v[10:11], v[10:11], v[98:99], v[42:43] op_sel:[0,0,0] op_sel_hi:[1,0,1]
	v_pk_fma_f32 v[38:39], v[10:11], v[84:85], v[38:39] op_sel:[0,1,0] op_sel_hi:[1,1,1]
	v_pk_mul_f32 v[44:45], v[104:105], v[86:87] op_sel_hi:[1,0]
	v_pk_fma_f32 v[12:13], v[12:13], v[98:99], v[44:45] op_sel:[0,1,0] op_sel_hi:[1,1,1]
	v_pk_fma_f32 v[38:39], v[12:13], v[86:87], v[38:39] op_sel:[0,1,0] op_sel_hi:[1,1,1]
	s_waitcnt lgkmcnt(1)
	v_pk_mul_f32 v[42:43], v[104:105], v[88:89] op_sel_hi:[1,0]
	v_pk_fma_f32 v[14:15], v[14:15], v[100:101], v[42:43] op_sel:[0,0,0] op_sel_hi:[1,0,1]
	v_pk_fma_f32 v[38:39], v[14:15], v[88:89], v[38:39] op_sel:[0,1,0] op_sel_hi:[1,1,1]
	v_pk_mul_f32 v[44:45], v[104:105], v[90:91] op_sel_hi:[1,0]
	v_pk_fma_f32 v[16:17], v[16:17], v[100:101], v[44:45] op_sel:[0,1,0] op_sel_hi:[1,1,1]
	v_pk_fma_f32 v[38:39], v[16:17], v[90:91], v[38:39] op_sel:[0,1,0] op_sel_hi:[1,1,1]
	s_waitcnt lgkmcnt(0)
	v_pk_mul_f32 v[42:43], v[104:105], v[92:93] op_sel_hi:[1,0]
	v_pk_fma_f32 v[18:19], v[18:19], v[102:103], v[42:43] op_sel:[0,0,0] op_sel_hi:[1,0,1]
	v_pk_fma_f32 v[38:39], v[18:19], v[92:93], v[38:39] op_sel:[0,1,0] op_sel_hi:[1,1,1]
	v_pk_mul_f32 v[44:45], v[104:105], v[94:95] op_sel_hi:[1,0]
	v_pk_fma_f32 v[20:21], v[20:21], v[102:103], v[44:45] op_sel:[0,1,0] op_sel_hi:[1,1,1]
	v_pk_fma_f32 v[38:39], v[20:21], v[94:95], v[38:39] op_sel:[0,1,0] op_sel_hi:[1,1,1]
	s_add_u32 s14, s14, 0x1000
	s_addc_u32 s15, s15, 0
	v_add_f32_dpp v38, v38, v38 row_ror:8 row_mask:0xf bank_mask:0x3 bound_ctrl:1
	v_add_f32_dpp v38, v39, v39 row_ror:8 row_mask:0xf bank_mask:0xc bound_ctrl:1
	ds_read_b64 v[72:73], v3 offset:46336
	ds_read_b128 v[48:51], v2 offset:28928
	v_add_f32_dpp v38, v38, v38 row_half_mirror row_mask:0xf bank_mask:0xf bound_ctrl:1
	ds_read_b128 v[64:67], v2 offset:43264
	ds_read_b128 v[52:55], v2 offset:29184
	v_add_f32_dpp v38, v38, v38 quad_perm:[1,0,3,2] row_mask:0xf bank_mask:0xf bound_ctrl:1
	ds_read_b128 v[56:59], v2 offset:29440
	ds_read_b128 v[68:71], v2 offset:43520
	v_add_f32_dpp v38, v38, v38 quad_perm:[2,3,0,1] row_mask:0xf bank_mask:0xf bound_ctrl:1
	ds_read_b128 v[60:63], v2 offset:29696
	v_cvt_pk_bf16_f32 v47, v38, v38
	global_store_short v28, v47, s[14:15] offset:-4096
	s_waitcnt lgkmcnt(4)
	v_pk_mul_f32 v[42:43], v[72:73], v[48:49] op_sel_hi:[1,0]
	v_pk_fma_f32 v[6:7], v[6:7], v[64:65], v[42:43] op_sel:[0,0,0] op_sel_hi:[1,0,1]
	v_pk_mul_f32 v[38:39], v[6:7], v[48:49] op_sel:[0,1] op_sel_hi:[1,1]
	v_pk_mul_f32 v[44:45], v[72:73], v[50:51] op_sel_hi:[1,0]
	v_pk_fma_f32 v[8:9], v[8:9], v[64:65], v[44:45] op_sel:[0,1,0] op_sel_hi:[1,1,1]
	v_pk_fma_f32 v[38:39], v[8:9], v[50:51], v[38:39] op_sel:[0,1,0] op_sel_hi:[1,1,1]
	s_waitcnt lgkmcnt(3)
	v_pk_mul_f32 v[42:43], v[72:73], v[52:53] op_sel_hi:[1,0]
	v_pk_fma_f32 v[10:11], v[10:11], v[66:67], v[42:43] op_sel:[0,0,0] op_sel_hi:[1,0,1]
	v_pk_fma_f32 v[38:39], v[10:11], v[52:53], v[38:39] op_sel:[0,1,0] op_sel_hi:[1,1,1]
	v_pk_mul_f32 v[44:45], v[72:73], v[54:55] op_sel_hi:[1,0]
	v_pk_fma_f32 v[12:13], v[12:13], v[66:67], v[44:45] op_sel:[0,1,0] op_sel_hi:[1,1,1]
	v_pk_fma_f32 v[38:39], v[12:13], v[54:55], v[38:39] op_sel:[0,1,0] op_sel_hi:[1,1,1]
	s_waitcnt lgkmcnt(1)
	v_pk_mul_f32 v[42:43], v[72:73], v[56:57] op_sel_hi:[1,0]
	v_pk_fma_f32 v[14:15], v[14:15], v[68:69], v[42:43] op_sel:[0,0,0] op_sel_hi:[1,0,1]
	v_pk_fma_f32 v[38:39], v[14:15], v[56:57], v[38:39] op_sel:[0,1,0] op_sel_hi:[1,1,1]
	v_pk_mul_f32 v[44:45], v[72:73], v[58:59] op_sel_hi:[1,0]
	v_pk_fma_f32 v[16:17], v[16:17], v[68:69], v[44:45] op_sel:[0,1,0] op_sel_hi:[1,1,1]
	v_pk_fma_f32 v[38:39], v[16:17], v[58:59], v[38:39] op_sel:[0,1,0] op_sel_hi:[1,1,1]
	s_waitcnt lgkmcnt(0)
	v_pk_mul_f32 v[42:43], v[72:73], v[60:61] op_sel_hi:[1,0]
	v_pk_fma_f32 v[18:19], v[18:19], v[70:71], v[42:43] op_sel:[0,0,0] op_sel_hi:[1,0,1]
	v_pk_fma_f32 v[38:39], v[18:19], v[60:61], v[38:39] op_sel:[0,1,0] op_sel_hi:[1,1,1]
	v_pk_mul_f32 v[44:45], v[72:73], v[62:63] op_sel_hi:[1,0]
	v_pk_fma_f32 v[20:21], v[20:21], v[70:71], v[44:45] op_sel:[0,1,0] op_sel_hi:[1,1,1]
	v_pk_fma_f32 v[38:39], v[20:21], v[62:63], v[38:39] op_sel:[0,1,0] op_sel_hi:[1,1,1]
	s_add_u32 s14, s14, 0x1000
	s_addc_u32 s15, s15, 0
	v_add_f32_dpp v38, v38, v38 row_ror:8 row_mask:0xf bank_mask:0x3 bound_ctrl:1
	v_add_f32_dpp v38, v39, v39 row_ror:8 row_mask:0xf bank_mask:0xc bound_ctrl:1
	ds_read_b64 v[104:105], v3 offset:46592
	ds_read_b128 v[80:83], v2 offset:29952
	v_add_f32_dpp v38, v38, v38 row_half_mirror row_mask:0xf bank_mask:0xf bound_ctrl:1
	ds_read_b128 v[96:99], v2 offset:43776
	ds_read_b128 v[84:87], v2 offset:30208
	v_add_f32_dpp v38, v38, v38 quad_perm:[1,0,3,2] row_mask:0xf bank_mask:0xf bound_ctrl:1
	ds_read_b128 v[88:91], v2 offset:30464
	ds_read_b128 v[100:103], v2 offset:44032
	v_add_f32_dpp v38, v38, v38 quad_perm:[2,3,0,1] row_mask:0xf bank_mask:0xf bound_ctrl:1
	ds_read_b128 v[92:95], v2 offset:30720
	v_cvt_pk_bf16_f32 v47, v38, v38
	global_store_short v28, v47, s[14:15] offset:-4096
	s_waitcnt lgkmcnt(4)
	v_pk_mul_f32 v[42:43], v[104:105], v[80:81] op_sel_hi:[1,0]
	v_pk_fma_f32 v[6:7], v[6:7], v[96:97], v[42:43] op_sel:[0,0,0] op_sel_hi:[1,0,1]
	v_pk_mul_f32 v[38:39], v[6:7], v[80:81] op_sel:[0,1] op_sel_hi:[1,1]
	v_pk_mul_f32 v[44:45], v[104:105], v[82:83] op_sel_hi:[1,0]
	v_pk_fma_f32 v[8:9], v[8:9], v[96:97], v[44:45] op_sel:[0,1,0] op_sel_hi:[1,1,1]
	v_pk_fma_f32 v[38:39], v[8:9], v[82:83], v[38:39] op_sel:[0,1,0] op_sel_hi:[1,1,1]
	s_waitcnt lgkmcnt(3)
	v_pk_mul_f32 v[42:43], v[104:105], v[84:85] op_sel_hi:[1,0]
	v_pk_fma_f32 v[10:11], v[10:11], v[98:99], v[42:43] op_sel:[0,0,0] op_sel_hi:[1,0,1]
	v_pk_fma_f32 v[38:39], v[10:11], v[84:85], v[38:39] op_sel:[0,1,0] op_sel_hi:[1,1,1]
	v_pk_mul_f32 v[44:45], v[104:105], v[86:87] op_sel_hi:[1,0]
	v_pk_fma_f32 v[12:13], v[12:13], v[98:99], v[44:45] op_sel:[0,1,0] op_sel_hi:[1,1,1]
	v_pk_fma_f32 v[38:39], v[12:13], v[86:87], v[38:39] op_sel:[0,1,0] op_sel_hi:[1,1,1]
	s_waitcnt lgkmcnt(1)
	v_pk_mul_f32 v[42:43], v[104:105], v[88:89] op_sel_hi:[1,0]
	v_pk_fma_f32 v[14:15], v[14:15], v[100:101], v[42:43] op_sel:[0,0,0] op_sel_hi:[1,0,1]
	v_pk_fma_f32 v[38:39], v[14:15], v[88:89], v[38:39] op_sel:[0,1,0] op_sel_hi:[1,1,1]
	v_pk_mul_f32 v[44:45], v[104:105], v[90:91] op_sel_hi:[1,0]
	v_pk_fma_f32 v[16:17], v[16:17], v[100:101], v[44:45] op_sel:[0,1,0] op_sel_hi:[1,1,1]
	v_pk_fma_f32 v[38:39], v[16:17], v[90:91], v[38:39] op_sel:[0,1,0] op_sel_hi:[1,1,1]
	s_waitcnt lgkmcnt(0)
	v_pk_mul_f32 v[42:43], v[104:105], v[92:93] op_sel_hi:[1,0]
	v_pk_fma_f32 v[18:19], v[18:19], v[102:103], v[42:43] op_sel:[0,0,0] op_sel_hi:[1,0,1]
	v_pk_fma_f32 v[38:39], v[18:19], v[92:93], v[38:39] op_sel:[0,1,0] op_sel_hi:[1,1,1]
	v_pk_mul_f32 v[44:45], v[104:105], v[94:95] op_sel_hi:[1,0]
	v_pk_fma_f32 v[20:21], v[20:21], v[102:103], v[44:45] op_sel:[0,1,0] op_sel_hi:[1,1,1]
	v_pk_fma_f32 v[38:39], v[20:21], v[94:95], v[38:39] op_sel:[0,1,0] op_sel_hi:[1,1,1]
	s_add_u32 s14, s14, 0x1000
	s_addc_u32 s15, s15, 0
	v_add_f32_dpp v38, v38, v38 row_ror:8 row_mask:0xf bank_mask:0x3 bound_ctrl:1
	v_add_f32_dpp v38, v39, v39 row_ror:8 row_mask:0xf bank_mask:0xc bound_ctrl:1
	ds_read_b64 v[72:73], v3 offset:46848
	ds_read_b128 v[48:51], v2 offset:30976
	v_add_f32_dpp v38, v38, v38 row_half_mirror row_mask:0xf bank_mask:0xf bound_ctrl:1
	ds_read_b128 v[64:67], v2 offset:44288
	ds_read_b128 v[52:55], v2 offset:31232
	v_add_f32_dpp v38, v38, v38 quad_perm:[1,0,3,2] row_mask:0xf bank_mask:0xf bound_ctrl:1
	ds_read_b128 v[56:59], v2 offset:31488
	ds_read_b128 v[68:71], v2 offset:44544
	v_add_f32_dpp v38, v38, v38 quad_perm:[2,3,0,1] row_mask:0xf bank_mask:0xf bound_ctrl:1
	ds_read_b128 v[60:63], v2 offset:31744
	v_cvt_pk_bf16_f32 v47, v38, v38
	global_store_short v28, v47, s[14:15] offset:-4096
	s_waitcnt lgkmcnt(4)
	v_pk_mul_f32 v[42:43], v[72:73], v[48:49] op_sel_hi:[1,0]
	v_pk_fma_f32 v[6:7], v[6:7], v[64:65], v[42:43] op_sel:[0,0,0] op_sel_hi:[1,0,1]
	v_pk_mul_f32 v[38:39], v[6:7], v[48:49] op_sel:[0,1] op_sel_hi:[1,1]
	v_pk_mul_f32 v[44:45], v[72:73], v[50:51] op_sel_hi:[1,0]
	v_pk_fma_f32 v[8:9], v[8:9], v[64:65], v[44:45] op_sel:[0,1,0] op_sel_hi:[1,1,1]
	v_pk_fma_f32 v[38:39], v[8:9], v[50:51], v[38:39] op_sel:[0,1,0] op_sel_hi:[1,1,1]
	s_waitcnt lgkmcnt(3)
	v_pk_mul_f32 v[42:43], v[72:73], v[52:53] op_sel_hi:[1,0]
	v_pk_fma_f32 v[10:11], v[10:11], v[66:67], v[42:43] op_sel:[0,0,0] op_sel_hi:[1,0,1]
	v_pk_fma_f32 v[38:39], v[10:11], v[52:53], v[38:39] op_sel:[0,1,0] op_sel_hi:[1,1,1]
	v_pk_mul_f32 v[44:45], v[72:73], v[54:55] op_sel_hi:[1,0]
	v_pk_fma_f32 v[12:13], v[12:13], v[66:67], v[44:45] op_sel:[0,1,0] op_sel_hi:[1,1,1]
	v_pk_fma_f32 v[38:39], v[12:13], v[54:55], v[38:39] op_sel:[0,1,0] op_sel_hi:[1,1,1]
	s_waitcnt lgkmcnt(1)
	v_pk_mul_f32 v[42:43], v[72:73], v[56:57] op_sel_hi:[1,0]
	v_pk_fma_f32 v[14:15], v[14:15], v[68:69], v[42:43] op_sel:[0,0,0] op_sel_hi:[1,0,1]
	v_pk_fma_f32 v[38:39], v[14:15], v[56:57], v[38:39] op_sel:[0,1,0] op_sel_hi:[1,1,1]
	v_pk_mul_f32 v[44:45], v[72:73], v[58:59] op_sel_hi:[1,0]
	v_pk_fma_f32 v[16:17], v[16:17], v[68:69], v[44:45] op_sel:[0,1,0] op_sel_hi:[1,1,1]
	v_pk_fma_f32 v[38:39], v[16:17], v[58:59], v[38:39] op_sel:[0,1,0] op_sel_hi:[1,1,1]
	s_waitcnt lgkmcnt(0)
	v_pk_mul_f32 v[42:43], v[72:73], v[60:61] op_sel_hi:[1,0]
	v_pk_fma_f32 v[18:19], v[18:19], v[70:71], v[42:43] op_sel:[0,0,0] op_sel_hi:[1,0,1]
	v_pk_fma_f32 v[38:39], v[18:19], v[60:61], v[38:39] op_sel:[0,1,0] op_sel_hi:[1,1,1]
	v_pk_mul_f32 v[44:45], v[72:73], v[62:63] op_sel_hi:[1,0]
	v_pk_fma_f32 v[20:21], v[20:21], v[70:71], v[44:45] op_sel:[0,1,0] op_sel_hi:[1,1,1]
	v_pk_fma_f32 v[38:39], v[20:21], v[62:63], v[38:39] op_sel:[0,1,0] op_sel_hi:[1,1,1]
	s_add_u32 s14, s14, 0x1000
	s_addc_u32 s15, s15, 0
	v_add_f32_dpp v38, v38, v38 row_ror:8 row_mask:0xf bank_mask:0x3 bound_ctrl:1
	v_add_f32_dpp v38, v39, v39 row_ror:8 row_mask:0xf bank_mask:0xc bound_ctrl:1
	ds_read_b64 v[104:105], v3 offset:47104
	ds_read_b128 v[80:83], v2 offset:32000
	v_add_f32_dpp v38, v38, v38 row_half_mirror row_mask:0xf bank_mask:0xf bound_ctrl:1
	ds_read_b128 v[96:99], v2 offset:44800
	ds_read_b128 v[84:87], v2 offset:32256
	v_add_f32_dpp v38, v38, v38 quad_perm:[1,0,3,2] row_mask:0xf bank_mask:0xf bound_ctrl:1
	ds_read_b128 v[88:91], v2 offset:32512
	ds_read_b128 v[100:103], v2 offset:45056
	v_add_f32_dpp v38, v38, v38 quad_perm:[2,3,0,1] row_mask:0xf bank_mask:0xf bound_ctrl:1
	ds_read_b128 v[92:95], v2 offset:32768
	v_cvt_pk_bf16_f32 v47, v38, v38
	global_store_short v28, v47, s[14:15] offset:-4096
	s_waitcnt lgkmcnt(4)
	v_pk_mul_f32 v[42:43], v[104:105], v[80:81] op_sel_hi:[1,0]
	v_pk_fma_f32 v[6:7], v[6:7], v[96:97], v[42:43] op_sel:[0,0,0] op_sel_hi:[1,0,1]
	v_pk_mul_f32 v[38:39], v[6:7], v[80:81] op_sel:[0,1] op_sel_hi:[1,1]
	v_pk_mul_f32 v[44:45], v[104:105], v[82:83] op_sel_hi:[1,0]
	v_pk_fma_f32 v[8:9], v[8:9], v[96:97], v[44:45] op_sel:[0,1,0] op_sel_hi:[1,1,1]
	v_pk_fma_f32 v[38:39], v[8:9], v[82:83], v[38:39] op_sel:[0,1,0] op_sel_hi:[1,1,1]
	s_waitcnt lgkmcnt(3)
	v_pk_mul_f32 v[42:43], v[104:105], v[84:85] op_sel_hi:[1,0]
	v_pk_fma_f32 v[10:11], v[10:11], v[98:99], v[42:43] op_sel:[0,0,0] op_sel_hi:[1,0,1]
	v_pk_fma_f32 v[38:39], v[10:11], v[84:85], v[38:39] op_sel:[0,1,0] op_sel_hi:[1,1,1]
	v_pk_mul_f32 v[44:45], v[104:105], v[86:87] op_sel_hi:[1,0]
	v_pk_fma_f32 v[12:13], v[12:13], v[98:99], v[44:45] op_sel:[0,1,0] op_sel_hi:[1,1,1]
	v_pk_fma_f32 v[38:39], v[12:13], v[86:87], v[38:39] op_sel:[0,1,0] op_sel_hi:[1,1,1]
	s_waitcnt lgkmcnt(1)
	v_pk_mul_f32 v[42:43], v[104:105], v[88:89] op_sel_hi:[1,0]
	v_pk_fma_f32 v[14:15], v[14:15], v[100:101], v[42:43] op_sel:[0,0,0] op_sel_hi:[1,0,1]
	v_pk_fma_f32 v[38:39], v[14:15], v[88:89], v[38:39] op_sel:[0,1,0] op_sel_hi:[1,1,1]
	v_pk_mul_f32 v[44:45], v[104:105], v[90:91] op_sel_hi:[1,0]
	v_pk_fma_f32 v[16:17], v[16:17], v[100:101], v[44:45] op_sel:[0,1,0] op_sel_hi:[1,1,1]
	v_pk_fma_f32 v[38:39], v[16:17], v[90:91], v[38:39] op_sel:[0,1,0] op_sel_hi:[1,1,1]
	s_waitcnt lgkmcnt(0)
	v_pk_mul_f32 v[42:43], v[104:105], v[92:93] op_sel_hi:[1,0]
	v_pk_fma_f32 v[18:19], v[18:19], v[102:103], v[42:43] op_sel:[0,0,0] op_sel_hi:[1,0,1]
	v_pk_fma_f32 v[38:39], v[18:19], v[92:93], v[38:39] op_sel:[0,1,0] op_sel_hi:[1,1,1]
	v_pk_mul_f32 v[44:45], v[104:105], v[94:95] op_sel_hi:[1,0]
	v_pk_fma_f32 v[20:21], v[20:21], v[102:103], v[44:45] op_sel:[0,1,0] op_sel_hi:[1,1,1]
	v_pk_fma_f32 v[38:39], v[20:21], v[94:95], v[38:39] op_sel:[0,1,0] op_sel_hi:[1,1,1]
	s_add_u32 s14, s14, 0x1000
	s_addc_u32 s15, s15, 0
	v_add_f32_dpp v38, v38, v38 row_ror:8 row_mask:0xf bank_mask:0x3 bound_ctrl:1
	v_add_f32_dpp v38, v39, v39 row_ror:8 row_mask:0xf bank_mask:0xc bound_ctrl:1
	ds_read_b64 v[72:73], v23 offset:37120
	ds_read_b128 v[48:51], v2 offset:49408
	v_add_f32_dpp v38, v38, v38 row_half_mirror row_mask:0xf bank_mask:0xf bound_ctrl:1
	ds_read_b128 v[64:67], v22 offset:33024
	ds_read_b128 v[52:55], v2 offset:49664
	v_add_f32_dpp v38, v38, v38 quad_perm:[1,0,3,2] row_mask:0xf bank_mask:0xf bound_ctrl:1
	ds_read_b128 v[56:59], v2 offset:49920
	ds_read_b128 v[68:71], v22 offset:33280
	v_add_f32_dpp v38, v38, v38 quad_perm:[2,3,0,1] row_mask:0xf bank_mask:0xf bound_ctrl:1
	ds_read_b128 v[60:63], v2 offset:50176
	v_cvt_pk_bf16_f32 v47, v38, v38
	global_store_short v28, v47, s[14:15] offset:-4096
	s_waitcnt vmcnt(8)
	v_lshlrev_b32_e32 v144, 16, v110
	v_lshlrev_b32_e32 v145, 16, v111
	v_and_b32_e32 v146, s17, v110
	v_and_b32_e32 v147, s17, v111
	v_lshlrev_b32_e32 v148, 16, v112
	v_lshlrev_b32_e32 v149, 16, v113
	v_and_b32_e32 v150, s17, v112
	v_and_b32_e32 v151, s17, v113
	v_lshlrev_b32_e32 v152, 16, v114
	v_and_b32_e32 v153, s17, v114
	v_rcp_f32_e32 v25, v24
	v_mul_f32_e32 v149, v24, v149
	v_mul_f32_e32 v151, v24, v151
	v_mul_f32_e32 v145, 0x3db504f3, v145
	v_mul_f32_e32 v147, 0x3db504f3, v147
	v_cndmask_b32_e64 v27, 1.0, v25, s[20:21]
	v_mul_f32_e32 v24, v24, v26
	v_mul_f32_e32 v152, v27, v152
	v_mul_f32_e32 v153, v27, v153
	ds_write_b128 v29, v[144:147] offset:256
	ds_write_b128 v29, v[148:151] offset:8448
	ds_write_b64 v30, v[116:117] offset:256
	ds_write_b64 v31, v[152:153] offset:256
	s_add_i32 s16, s16, 8
	s_waitcnt lgkmcnt(0)
	s_barrier
	s_cmpk_lt_u32 s16, 0x800
	s_cbranch_scc0 .Lgla2_done
	global_load_dword v110, v32, s[10:11]
	global_load_dword v111, v32, s[10:11] offset:-1024
	global_load_dword v112, v33, s[10:11]
	global_load_dword v113, v33, s[10:11] offset:-1024
	global_load_dword v114, v34, s[10:11]
	global_load_dword v116, v35, s[12:13]
	global_load_dword v117, v35, s[12:13] offset:4
	s_add_u32 s10, s10, 0x18000
	s_addc_u32 s11, s11, 0
	s_add_u32 s12, s12, 0x4000
	s_addc_u32 s13, s13, 0
	s_waitcnt lgkmcnt(4)
	v_pk_mul_f32 v[42:43], v[72:73], v[48:49] op_sel_hi:[1,0]
	v_pk_fma_f32 v[6:7], v[6:7], v[64:65], v[42:43] op_sel:[0,0,0] op_sel_hi:[1,0,1]
	v_pk_mul_f32 v[38:39], v[6:7], v[48:49] op_sel:[0,1] op_sel_hi:[1,1]
	v_pk_mul_f32 v[44:45], v[72:73], v[50:51] op_sel_hi:[1,0]
	v_pk_fma_f32 v[8:9], v[8:9], v[64:65], v[44:45] op_sel:[0,1,0] op_sel_hi:[1,1,1]
	v_pk_fma_f32 v[38:39], v[8:9], v[50:51], v[38:39] op_sel:[0,1,0] op_sel_hi:[1,1,1]
	s_waitcnt lgkmcnt(3)
	v_pk_mul_f32 v[42:43], v[72:73], v[52:53] op_sel_hi:[1,0]
	v_pk_fma_f32 v[10:11], v[10:11], v[66:67], v[42:43] op_sel:[0,0,0] op_sel_hi:[1,0,1]
	v_pk_fma_f32 v[38:39], v[10:11], v[52:53], v[38:39] op_sel:[0,1,0] op_sel_hi:[1,1,1]
	v_pk_mul_f32 v[44:45], v[72:73], v[54:55] op_sel_hi:[1,0]
	v_pk_fma_f32 v[12:13], v[12:13], v[66:67], v[44:45] op_sel:[0,1,0] op_sel_hi:[1,1,1]
	v_pk_fma_f32 v[38:39], v[12:13], v[54:55], v[38:39] op_sel:[0,1,0] op_sel_hi:[1,1,1]
	s_waitcnt lgkmcnt(1)
	v_pk_mul_f32 v[42:43], v[72:73], v[56:57] op_sel_hi:[1,0]
	v_pk_fma_f32 v[14:15], v[14:15], v[68:69], v[42:43] op_sel:[0,0,0] op_sel_hi:[1,0,1]
	v_pk_fma_f32 v[38:39], v[14:15], v[56:57], v[38:39] op_sel:[0,1,0] op_sel_hi:[1,1,1]
	v_pk_mul_f32 v[44:45], v[72:73], v[58:59] op_sel_hi:[1,0]
	v_pk_fma_f32 v[16:17], v[16:17], v[68:69], v[44:45] op_sel:[0,1,0] op_sel_hi:[1,1,1]
	v_pk_fma_f32 v[38:39], v[16:17], v[58:59], v[38:39] op_sel:[0,1,0] op_sel_hi:[1,1,1]
	s_waitcnt lgkmcnt(0)
	v_pk_mul_f32 v[42:43], v[72:73], v[60:61] op_sel_hi:[1,0]
	v_pk_fma_f32 v[18:19], v[18:19], v[70:71], v[42:43] op_sel:[0,0,0] op_sel_hi:[1,0,1]
	v_pk_fma_f32 v[38:39], v[18:19], v[60:61], v[38:39] op_sel:[0,1,0] op_sel_hi:[1,1,1]
	v_pk_mul_f32 v[44:45], v[72:73], v[62:63] op_sel_hi:[1,0]
	v_pk_fma_f32 v[20:21], v[20:21], v[70:71], v[44:45] op_sel:[0,1,0] op_sel_hi:[1,1,1]
	v_pk_fma_f32 v[38:39], v[20:21], v[62:63], v[38:39] op_sel:[0,1,0] op_sel_hi:[1,1,1]
	s_add_u32 s14, s14, 0x1000
	s_addc_u32 s15, s15, 0
	v_add_f32_dpp v38, v38, v38 row_ror:8 row_mask:0xf bank_mask:0x3 bound_ctrl:1
	v_add_f32_dpp v38, v39, v39 row_ror:8 row_mask:0xf bank_mask:0xc bound_ctrl:1
	ds_read_b64 v[104:105], v23 offset:37376
	ds_read_b128 v[80:83], v2 offset:50432
	v_add_f32_dpp v38, v38, v38 row_half_mirror row_mask:0xf bank_mask:0xf bound_ctrl:1
	ds_read_b128 v[96:99], v22 offset:33536
	ds_read_b128 v[84:87], v2 offset:50688
	v_add_f32_dpp v38, v38, v38 quad_perm:[1,0,3,2] row_mask:0xf bank_mask:0xf bound_ctrl:1
	ds_read_b128 v[88:91], v2 offset:50944
	ds_read_b128 v[100:103], v22 offset:33792
	v_add_f32_dpp v38, v38, v38 quad_perm:[2,3,0,1] row_mask:0xf bank_mask:0xf bound_ctrl:1
	ds_read_b128 v[92:95], v2 offset:51200
	v_cvt_pk_bf16_f32 v47, v38, v38
	global_store_short v28, v47, s[14:15] offset:-4096
	s_waitcnt lgkmcnt(4)
	v_pk_mul_f32 v[42:43], v[104:105], v[80:81] op_sel_hi:[1,0]
	v_pk_fma_f32 v[6:7], v[6:7], v[96:97], v[42:43] op_sel:[0,0,0] op_sel_hi:[1,0,1]
	v_pk_mul_f32 v[38:39], v[6:7], v[80:81] op_sel:[0,1] op_sel_hi:[1,1]
	v_pk_mul_f32 v[44:45], v[104:105], v[82:83] op_sel_hi:[1,0]
	v_pk_fma_f32 v[8:9], v[8:9], v[96:97], v[44:45] op_sel:[0,1,0] op_sel_hi:[1,1,1]
	v_pk_fma_f32 v[38:39], v[8:9], v[82:83], v[38:39] op_sel:[0,1,0] op_sel_hi:[1,1,1]
	s_waitcnt lgkmcnt(3)
	v_pk_mul_f32 v[42:43], v[104:105], v[84:85] op_sel_hi:[1,0]
	v_pk_fma_f32 v[10:11], v[10:11], v[98:99], v[42:43] op_sel:[0,0,0] op_sel_hi:[1,0,1]
	v_pk_fma_f32 v[38:39], v[10:11], v[84:85], v[38:39] op_sel:[0,1,0] op_sel_hi:[1,1,1]
	v_pk_mul_f32 v[44:45], v[104:105], v[86:87] op_sel_hi:[1,0]
	v_pk_fma_f32 v[12:13], v[12:13], v[98:99], v[44:45] op_sel:[0,1,0] op_sel_hi:[1,1,1]
	v_pk_fma_f32 v[38:39], v[12:13], v[86:87], v[38:39] op_sel:[0,1,0] op_sel_hi:[1,1,1]
	s_waitcnt lgkmcnt(1)
	v_pk_mul_f32 v[42:43], v[104:105], v[88:89] op_sel_hi:[1,0]
	v_pk_fma_f32 v[14:15], v[14:15], v[100:101], v[42:43] op_sel:[0,0,0] op_sel_hi:[1,0,1]
	v_pk_fma_f32 v[38:39], v[14:15], v[88:89], v[38:39] op_sel:[0,1,0] op_sel_hi:[1,1,1]
	v_pk_mul_f32 v[44:45], v[104:105], v[90:91] op_sel_hi:[1,0]
	v_pk_fma_f32 v[16:17], v[16:17], v[100:101], v[44:45] op_sel:[0,1,0] op_sel_hi:[1,1,1]
	v_pk_fma_f32 v[38:39], v[16:17], v[90:91], v[38:39] op_sel:[0,1,0] op_sel_hi:[1,1,1]
	s_waitcnt lgkmcnt(0)
	v_pk_mul_f32 v[42:43], v[104:105], v[92:93] op_sel_hi:[1,0]
	v_pk_fma_f32 v[18:19], v[18:19], v[102:103], v[42:43] op_sel:[0,0,0] op_sel_hi:[1,0,1]
	v_pk_fma_f32 v[38:39], v[18:19], v[92:93], v[38:39] op_sel:[0,1,0] op_sel_hi:[1,1,1]
	v_pk_mul_f32 v[44:45], v[104:105], v[94:95] op_sel_hi:[1,0]
	v_pk_fma_f32 v[20:21], v[20:21], v[102:103], v[44:45] op_sel:[0,1,0] op_sel_hi:[1,1,1]
	v_pk_fma_f32 v[38:39], v[20:21], v[94:95], v[38:39] op_sel:[0,1,0] op_sel_hi:[1,1,1]
	s_add_u32 s14, s14, 0x1000
	s_addc_u32 s15, s15, 0
	v_add_f32_dpp v38, v38, v38 row_ror:8 row_mask:0xf bank_mask:0x3 bound_ctrl:1
	v_add_f32_dpp v38, v39, v39 row_ror:8 row_mask:0xf bank_mask:0xc bound_ctrl:1
	ds_read_b64 v[72:73], v23 offset:37632
	ds_read_b128 v[48:51], v2 offset:51456
	v_add_f32_dpp v38, v38, v38 row_half_mirror row_mask:0xf bank_mask:0xf bound_ctrl:1
	ds_read_b128 v[64:67], v22 offset:34048
	ds_read_b128 v[52:55], v2 offset:51712
	v_add_f32_dpp v38, v38, v38 quad_perm:[1,0,3,2] row_mask:0xf bank_mask:0xf bound_ctrl:1
	ds_read_b128 v[56:59], v2 offset:51968
	ds_read_b128 v[68:71], v22 offset:34304
	v_add_f32_dpp v38, v38, v38 quad_perm:[2,3,0,1] row_mask:0xf bank_mask:0xf bound_ctrl:1
	ds_read_b128 v[60:63], v2 offset:52224
	v_cvt_pk_bf16_f32 v47, v38, v38
	global_store_short v28, v47, s[14:15] offset:-4096
	s_waitcnt lgkmcnt(4)
	v_pk_mul_f32 v[42:43], v[72:73], v[48:49] op_sel_hi:[1,0]
	v_pk_fma_f32 v[6:7], v[6:7], v[64:65], v[42:43] op_sel:[0,0,0] op_sel_hi:[1,0,1]
	v_pk_mul_f32 v[38:39], v[6:7], v[48:49] op_sel:[0,1] op_sel_hi:[1,1]
	v_pk_mul_f32 v[44:45], v[72:73], v[50:51] op_sel_hi:[1,0]
	v_pk_fma_f32 v[8:9], v[8:9], v[64:65], v[44:45] op_sel:[0,1,0] op_sel_hi:[1,1,1]
	v_pk_fma_f32 v[38:39], v[8:9], v[50:51], v[38:39] op_sel:[0,1,0] op_sel_hi:[1,1,1]
	s_waitcnt lgkmcnt(3)
	v_pk_mul_f32 v[42:43], v[72:73], v[52:53] op_sel_hi:[1,0]
	v_pk_fma_f32 v[10:11], v[10:11], v[66:67], v[42:43] op_sel:[0,0,0] op_sel_hi:[1,0,1]
	v_pk_fma_f32 v[38:39], v[10:11], v[52:53], v[38:39] op_sel:[0,1,0] op_sel_hi:[1,1,1]
	v_pk_mul_f32 v[44:45], v[72:73], v[54:55] op_sel_hi:[1,0]
	v_pk_fma_f32 v[12:13], v[12:13], v[66:67], v[44:45] op_sel:[0,1,0] op_sel_hi:[1,1,1]
	v_pk_fma_f32 v[38:39], v[12:13], v[54:55], v[38:39] op_sel:[0,1,0] op_sel_hi:[1,1,1]
	s_waitcnt lgkmcnt(1)
	v_pk_mul_f32 v[42:43], v[72:73], v[56:57] op_sel_hi:[1,0]
	v_pk_fma_f32 v[14:15], v[14:15], v[68:69], v[42:43] op_sel:[0,0,0] op_sel_hi:[1,0,1]
	v_pk_fma_f32 v[38:39], v[14:15], v[56:57], v[38:39] op_sel:[0,1,0] op_sel_hi:[1,1,1]
	v_pk_mul_f32 v[44:45], v[72:73], v[58:59] op_sel_hi:[1,0]
	v_pk_fma_f32 v[16:17], v[16:17], v[68:69], v[44:45] op_sel:[0,1,0] op_sel_hi:[1,1,1]
	v_pk_fma_f32 v[38:39], v[16:17], v[58:59], v[38:39] op_sel:[0,1,0] op_sel_hi:[1,1,1]
	s_waitcnt lgkmcnt(0)
	v_pk_mul_f32 v[42:43], v[72:73], v[60:61] op_sel_hi:[1,0]
	v_pk_fma_f32 v[18:19], v[18:19], v[70:71], v[42:43] op_sel:[0,0,0] op_sel_hi:[1,0,1]
	v_pk_fma_f32 v[38:39], v[18:19], v[60:61], v[38:39] op_sel:[0,1,0] op_sel_hi:[1,1,1]
	v_pk_mul_f32 v[44:45], v[72:73], v[62:63] op_sel_hi:[1,0]
	v_pk_fma_f32 v[20:21], v[20:21], v[70:71], v[44:45] op_sel:[0,1,0] op_sel_hi:[1,1,1]
	v_pk_fma_f32 v[38:39], v[20:21], v[62:63], v[38:39] op_sel:[0,1,0] op_sel_hi:[1,1,1]
	s_add_u32 s14, s14, 0x1000
	s_addc_u32 s15, s15, 0
	v_add_f32_dpp v38, v38, v38 row_ror:8 row_mask:0xf bank_mask:0x3 bound_ctrl:1
	v_add_f32_dpp v38, v39, v39 row_ror:8 row_mask:0xf bank_mask:0xc bound_ctrl:1
	ds_read_b64 v[104:105], v23 offset:37888
	ds_read_b128 v[80:83], v2 offset:52480
	v_add_f32_dpp v38, v38, v38 row_half_mirror row_mask:0xf bank_mask:0xf bound_ctrl:1
	ds_read_b128 v[96:99], v22 offset:34560
	ds_read_b128 v[84:87], v2 offset:52736
	v_add_f32_dpp v38, v38, v38 quad_perm:[1,0,3,2] row_mask:0xf bank_mask:0xf bound_ctrl:1
	ds_read_b128 v[88:91], v2 offset:52992
	ds_read_b128 v[100:103], v22 offset:34816
	v_add_f32_dpp v38, v38, v38 quad_perm:[2,3,0,1] row_mask:0xf bank_mask:0xf bound_ctrl:1
	ds_read_b128 v[92:95], v2 offset:53248
	v_cvt_pk_bf16_f32 v47, v38, v38
	global_store_short v28, v47, s[14:15] offset:-4096
	s_waitcnt lgkmcnt(4)
	v_pk_mul_f32 v[42:43], v[104:105], v[80:81] op_sel_hi:[1,0]
	v_pk_fma_f32 v[6:7], v[6:7], v[96:97], v[42:43] op_sel:[0,0,0] op_sel_hi:[1,0,1]
	v_pk_mul_f32 v[38:39], v[6:7], v[80:81] op_sel:[0,1] op_sel_hi:[1,1]
	v_pk_mul_f32 v[44:45], v[104:105], v[82:83] op_sel_hi:[1,0]
	v_pk_fma_f32 v[8:9], v[8:9], v[96:97], v[44:45] op_sel:[0,1,0] op_sel_hi:[1,1,1]
	v_pk_fma_f32 v[38:39], v[8:9], v[82:83], v[38:39] op_sel:[0,1,0] op_sel_hi:[1,1,1]
	s_waitcnt lgkmcnt(3)
	v_pk_mul_f32 v[42:43], v[104:105], v[84:85] op_sel_hi:[1,0]
	v_pk_fma_f32 v[10:11], v[10:11], v[98:99], v[42:43] op_sel:[0,0,0] op_sel_hi:[1,0,1]
	v_pk_fma_f32 v[38:39], v[10:11], v[84:85], v[38:39] op_sel:[0,1,0] op_sel_hi:[1,1,1]
	v_pk_mul_f32 v[44:45], v[104:105], v[86:87] op_sel_hi:[1,0]
	v_pk_fma_f32 v[12:13], v[12:13], v[98:99], v[44:45] op_sel:[0,1,0] op_sel_hi:[1,1,1]
	v_pk_fma_f32 v[38:39], v[12:13], v[86:87], v[38:39] op_sel:[0,1,0] op_sel_hi:[1,1,1]
	s_waitcnt lgkmcnt(1)
	v_pk_mul_f32 v[42:43], v[104:105], v[88:89] op_sel_hi:[1,0]
	v_pk_fma_f32 v[14:15], v[14:15], v[100:101], v[42:43] op_sel:[0,0,0] op_sel_hi:[1,0,1]
	v_pk_fma_f32 v[38:39], v[14:15], v[88:89], v[38:39] op_sel:[0,1,0] op_sel_hi:[1,1,1]
	v_pk_mul_f32 v[44:45], v[104:105], v[90:91] op_sel_hi:[1,0]
	v_pk_fma_f32 v[16:17], v[16:17], v[100:101], v[44:45] op_sel:[0,1,0] op_sel_hi:[1,1,1]
	v_pk_fma_f32 v[38:39], v[16:17], v[90:91], v[38:39] op_sel:[0,1,0] op_sel_hi:[1,1,1]
	s_waitcnt lgkmcnt(0)
	v_pk_mul_f32 v[42:43], v[104:105], v[92:93] op_sel_hi:[1,0]
	v_pk_fma_f32 v[18:19], v[18:19], v[102:103], v[42:43] op_sel:[0,0,0] op_sel_hi:[1,0,1]
	v_pk_fma_f32 v[38:39], v[18:19], v[92:93], v[38:39] op_sel:[0,1,0] op_sel_hi:[1,1,1]
	v_pk_mul_f32 v[44:45], v[104:105], v[94:95] op_sel_hi:[1,0]
	v_pk_fma_f32 v[20:21], v[20:21], v[102:103], v[44:45] op_sel:[0,1,0] op_sel_hi:[1,1,1]
	v_pk_fma_f32 v[38:39], v[20:21], v[94:95], v[38:39] op_sel:[0,1,0] op_sel_hi:[1,1,1]
	s_add_u32 s14, s14, 0x1000
	s_addc_u32 s15, s15, 0
	v_add_f32_dpp v38, v38, v38 row_ror:8 row_mask:0xf bank_mask:0x3 bound_ctrl:1
	v_add_f32_dpp v38, v39, v39 row_ror:8 row_mask:0xf bank_mask:0xc bound_ctrl:1
	ds_read_b64 v[72:73], v23 offset:38144
	ds_read_b128 v[48:51], v2 offset:53504
	v_add_f32_dpp v38, v38, v38 row_half_mirror row_mask:0xf bank_mask:0xf bound_ctrl:1
	ds_read_b128 v[64:67], v22 offset:35072
	ds_read_b128 v[52:55], v2 offset:53760
	v_add_f32_dpp v38, v38, v38 quad_perm:[1,0,3,2] row_mask:0xf bank_mask:0xf bound_ctrl:1
	ds_read_b128 v[56:59], v2 offset:54016
	ds_read_b128 v[68:71], v22 offset:35328
	v_add_f32_dpp v38, v38, v38 quad_perm:[2,3,0,1] row_mask:0xf bank_mask:0xf bound_ctrl:1
	ds_read_b128 v[60:63], v2 offset:54272
	v_cvt_pk_bf16_f32 v47, v38, v38
	global_store_short v28, v47, s[14:15] offset:-4096
	s_waitcnt lgkmcnt(4)
	v_pk_mul_f32 v[42:43], v[72:73], v[48:49] op_sel_hi:[1,0]
	v_pk_fma_f32 v[6:7], v[6:7], v[64:65], v[42:43] op_sel:[0,0,0] op_sel_hi:[1,0,1]
	v_pk_mul_f32 v[38:39], v[6:7], v[48:49] op_sel:[0,1] op_sel_hi:[1,1]
	v_pk_mul_f32 v[44:45], v[72:73], v[50:51] op_sel_hi:[1,0]
	v_pk_fma_f32 v[8:9], v[8:9], v[64:65], v[44:45] op_sel:[0,1,0] op_sel_hi:[1,1,1]
	v_pk_fma_f32 v[38:39], v[8:9], v[50:51], v[38:39] op_sel:[0,1,0] op_sel_hi:[1,1,1]
	s_waitcnt lgkmcnt(3)
	v_pk_mul_f32 v[42:43], v[72:73], v[52:53] op_sel_hi:[1,0]
	v_pk_fma_f32 v[10:11], v[10:11], v[66:67], v[42:43] op_sel:[0,0,0] op_sel_hi:[1,0,1]
	v_pk_fma_f32 v[38:39], v[10:11], v[52:53], v[38:39] op_sel:[0,1,0] op_sel_hi:[1,1,1]
	v_pk_mul_f32 v[44:45], v[72:73], v[54:55] op_sel_hi:[1,0]
	v_pk_fma_f32 v[12:13], v[12:13], v[66:67], v[44:45] op_sel:[0,1,0] op_sel_hi:[1,1,1]
	v_pk_fma_f32 v[38:39], v[12:13], v[54:55], v[38:39] op_sel:[0,1,0] op_sel_hi:[1,1,1]
	s_waitcnt lgkmcnt(1)
	v_pk_mul_f32 v[42:43], v[72:73], v[56:57] op_sel_hi:[1,0]
	v_pk_fma_f32 v[14:15], v[14:15], v[68:69], v[42:43] op_sel:[0,0,0] op_sel_hi:[1,0,1]
	v_pk_fma_f32 v[38:39], v[14:15], v[56:57], v[38:39] op_sel:[0,1,0] op_sel_hi:[1,1,1]
	v_pk_mul_f32 v[44:45], v[72:73], v[58:59] op_sel_hi:[1,0]
	v_pk_fma_f32 v[16:17], v[16:17], v[68:69], v[44:45] op_sel:[0,1,0] op_sel_hi:[1,1,1]
	v_pk_fma_f32 v[38:39], v[16:17], v[58:59], v[38:39] op_sel:[0,1,0] op_sel_hi:[1,1,1]
	s_waitcnt lgkmcnt(0)
	v_pk_mul_f32 v[42:43], v[72:73], v[60:61] op_sel_hi:[1,0]
	v_pk_fma_f32 v[18:19], v[18:19], v[70:71], v[42:43] op_sel:[0,0,0] op_sel_hi:[1,0,1]
	v_pk_fma_f32 v[38:39], v[18:19], v[60:61], v[38:39] op_sel:[0,1,0] op_sel_hi:[1,1,1]
	v_pk_mul_f32 v[44:45], v[72:73], v[62:63] op_sel_hi:[1,0]
	v_pk_fma_f32 v[20:21], v[20:21], v[70:71], v[44:45] op_sel:[0,1,0] op_sel_hi:[1,1,1]
	v_pk_fma_f32 v[38:39], v[20:21], v[62:63], v[38:39] op_sel:[0,1,0] op_sel_hi:[1,1,1]
	s_add_u32 s14, s14, 0x1000
	s_addc_u32 s15, s15, 0
	v_add_f32_dpp v38, v38, v38 row_ror:8 row_mask:0xf bank_mask:0x3 bound_ctrl:1
	v_add_f32_dpp v38, v39, v39 row_ror:8 row_mask:0xf bank_mask:0xc bound_ctrl:1
	ds_read_b64 v[104:105], v23 offset:38400
	ds_read_b128 v[80:83], v2 offset:54528
	v_add_f32_dpp v38, v38, v38 row_half_mirror row_mask:0xf bank_mask:0xf bound_ctrl:1
	ds_read_b128 v[96:99], v22 offset:35584
	ds_read_b128 v[84:87], v2 offset:54784
	v_add_f32_dpp v38, v38, v38 quad_perm:[1,0,3,2] row_mask:0xf bank_mask:0xf bound_ctrl:1
	ds_read_b128 v[88:91], v2 offset:55040
	ds_read_b128 v[100:103], v22 offset:35840
	v_add_f32_dpp v38, v38, v38 quad_perm:[2,3,0,1] row_mask:0xf bank_mask:0xf bound_ctrl:1
	ds_read_b128 v[92:95], v2 offset:55296
	v_cvt_pk_bf16_f32 v47, v38, v38
	global_store_short v28, v47, s[14:15] offset:-4096
	s_waitcnt lgkmcnt(4)
	v_pk_mul_f32 v[42:43], v[104:105], v[80:81] op_sel_hi:[1,0]
	v_pk_fma_f32 v[6:7], v[6:7], v[96:97], v[42:43] op_sel:[0,0,0] op_sel_hi:[1,0,1]
	v_pk_mul_f32 v[38:39], v[6:7], v[80:81] op_sel:[0,1] op_sel_hi:[1,1]
	v_pk_mul_f32 v[44:45], v[104:105], v[82:83] op_sel_hi:[1,0]
	v_pk_fma_f32 v[8:9], v[8:9], v[96:97], v[44:45] op_sel:[0,1,0] op_sel_hi:[1,1,1]
	v_pk_fma_f32 v[38:39], v[8:9], v[82:83], v[38:39] op_sel:[0,1,0] op_sel_hi:[1,1,1]
	s_waitcnt lgkmcnt(3)
	v_pk_mul_f32 v[42:43], v[104:105], v[84:85] op_sel_hi:[1,0]
	v_pk_fma_f32 v[10:11], v[10:11], v[98:99], v[42:43] op_sel:[0,0,0] op_sel_hi:[1,0,1]
	v_pk_fma_f32 v[38:39], v[10:11], v[84:85], v[38:39] op_sel:[0,1,0] op_sel_hi:[1,1,1]
	v_pk_mul_f32 v[44:45], v[104:105], v[86:87] op_sel_hi:[1,0]
	v_pk_fma_f32 v[12:13], v[12:13], v[98:99], v[44:45] op_sel:[0,1,0] op_sel_hi:[1,1,1]
	v_pk_fma_f32 v[38:39], v[12:13], v[86:87], v[38:39] op_sel:[0,1,0] op_sel_hi:[1,1,1]
	s_waitcnt lgkmcnt(1)
	v_pk_mul_f32 v[42:43], v[104:105], v[88:89] op_sel_hi:[1,0]
	v_pk_fma_f32 v[14:15], v[14:15], v[100:101], v[42:43] op_sel:[0,0,0] op_sel_hi:[1,0,1]
	v_pk_fma_f32 v[38:39], v[14:15], v[88:89], v[38:39] op_sel:[0,1,0] op_sel_hi:[1,1,1]
	v_pk_mul_f32 v[44:45], v[104:105], v[90:91] op_sel_hi:[1,0]
	v_pk_fma_f32 v[16:17], v[16:17], v[100:101], v[44:45] op_sel:[0,1,0] op_sel_hi:[1,1,1]
	v_pk_fma_f32 v[38:39], v[16:17], v[90:91], v[38:39] op_sel:[0,1,0] op_sel_hi:[1,1,1]
	s_waitcnt lgkmcnt(0)
	v_pk_mul_f32 v[42:43], v[104:105], v[92:93] op_sel_hi:[1,0]
	v_pk_fma_f32 v[18:19], v[18:19], v[102:103], v[42:43] op_sel:[0,0,0] op_sel_hi:[1,0,1]
	v_pk_fma_f32 v[38:39], v[18:19], v[92:93], v[38:39] op_sel:[0,1,0] op_sel_hi:[1,1,1]
	v_pk_mul_f32 v[44:45], v[104:105], v[94:95] op_sel_hi:[1,0]
	v_pk_fma_f32 v[20:21], v[20:21], v[102:103], v[44:45] op_sel:[0,1,0] op_sel_hi:[1,1,1]
	v_pk_fma_f32 v[38:39], v[20:21], v[94:95], v[38:39] op_sel:[0,1,0] op_sel_hi:[1,1,1]
	s_add_u32 s14, s14, 0x1000
	s_addc_u32 s15, s15, 0
	v_add_f32_dpp v38, v38, v38 row_ror:8 row_mask:0xf bank_mask:0x3 bound_ctrl:1
	v_add_f32_dpp v38, v39, v39 row_ror:8 row_mask:0xf bank_mask:0xc bound_ctrl:1
	ds_read_b64 v[72:73], v23 offset:38656
	ds_read_b128 v[48:51], v2 offset:55552
	v_add_f32_dpp v38, v38, v38 row_half_mirror row_mask:0xf bank_mask:0xf bound_ctrl:1
	ds_read_b128 v[64:67], v22 offset:36096
	ds_read_b128 v[52:55], v2 offset:55808
	v_add_f32_dpp v38, v38, v38 quad_perm:[1,0,3,2] row_mask:0xf bank_mask:0xf bound_ctrl:1
	ds_read_b128 v[56:59], v2 offset:56064
	ds_read_b128 v[68:71], v22 offset:36352
	v_add_f32_dpp v38, v38, v38 quad_perm:[2,3,0,1] row_mask:0xf bank_mask:0xf bound_ctrl:1
	ds_read_b128 v[60:63], v2 offset:56320
	v_cvt_pk_bf16_f32 v47, v38, v38
	global_store_short v28, v47, s[14:15] offset:-4096
	s_waitcnt lgkmcnt(4)
	v_pk_mul_f32 v[42:43], v[72:73], v[48:49] op_sel_hi:[1,0]
	v_pk_fma_f32 v[6:7], v[6:7], v[64:65], v[42:43] op_sel:[0,0,0] op_sel_hi:[1,0,1]
	v_pk_mul_f32 v[38:39], v[6:7], v[48:49] op_sel:[0,1] op_sel_hi:[1,1]
	v_pk_mul_f32 v[44:45], v[72:73], v[50:51] op_sel_hi:[1,0]
	v_pk_fma_f32 v[8:9], v[8:9], v[64:65], v[44:45] op_sel:[0,1,0] op_sel_hi:[1,1,1]
	v_pk_fma_f32 v[38:39], v[8:9], v[50:51], v[38:39] op_sel:[0,1,0] op_sel_hi:[1,1,1]
	s_waitcnt lgkmcnt(3)
	v_pk_mul_f32 v[42:43], v[72:73], v[52:53] op_sel_hi:[1,0]
	v_pk_fma_f32 v[10:11], v[10:11], v[66:67], v[42:43] op_sel:[0,0,0] op_sel_hi:[1,0,1]
	v_pk_fma_f32 v[38:39], v[10:11], v[52:53], v[38:39] op_sel:[0,1,0] op_sel_hi:[1,1,1]
	v_pk_mul_f32 v[44:45], v[72:73], v[54:55] op_sel_hi:[1,0]
	v_pk_fma_f32 v[12:13], v[12:13], v[66:67], v[44:45] op_sel:[0,1,0] op_sel_hi:[1,1,1]
	v_pk_fma_f32 v[38:39], v[12:13], v[54:55], v[38:39] op_sel:[0,1,0] op_sel_hi:[1,1,1]
	s_waitcnt lgkmcnt(1)
	v_pk_mul_f32 v[42:43], v[72:73], v[56:57] op_sel_hi:[1,0]
	v_pk_fma_f32 v[14:15], v[14:15], v[68:69], v[42:43] op_sel:[0,0,0] op_sel_hi:[1,0,1]
	v_pk_fma_f32 v[38:39], v[14:15], v[56:57], v[38:39] op_sel:[0,1,0] op_sel_hi:[1,1,1]
	v_pk_mul_f32 v[44:45], v[72:73], v[58:59] op_sel_hi:[1,0]
	v_pk_fma_f32 v[16:17], v[16:17], v[68:69], v[44:45] op_sel:[0,1,0] op_sel_hi:[1,1,1]
	v_pk_fma_f32 v[38:39], v[16:17], v[58:59], v[38:39] op_sel:[0,1,0] op_sel_hi:[1,1,1]
	s_waitcnt lgkmcnt(0)
	v_pk_mul_f32 v[42:43], v[72:73], v[60:61] op_sel_hi:[1,0]
	v_pk_fma_f32 v[18:19], v[18:19], v[70:71], v[42:43] op_sel:[0,0,0] op_sel_hi:[1,0,1]
	v_pk_fma_f32 v[38:39], v[18:19], v[60:61], v[38:39] op_sel:[0,1,0] op_sel_hi:[1,1,1]
	v_pk_mul_f32 v[44:45], v[72:73], v[62:63] op_sel_hi:[1,0]
	v_pk_fma_f32 v[20:21], v[20:21], v[70:71], v[44:45] op_sel:[0,1,0] op_sel_hi:[1,1,1]
	v_pk_fma_f32 v[38:39], v[20:21], v[62:63], v[38:39] op_sel:[0,1,0] op_sel_hi:[1,1,1]
	s_add_u32 s14, s14, 0x1000
	s_addc_u32 s15, s15, 0
	v_add_f32_dpp v38, v38, v38 row_ror:8 row_mask:0xf bank_mask:0x3 bound_ctrl:1
	v_add_f32_dpp v38, v39, v39 row_ror:8 row_mask:0xf bank_mask:0xc bound_ctrl:1
	ds_read_b64 v[104:105], v23 offset:38912
	ds_read_b128 v[80:83], v2 offset:56576
	v_add_f32_dpp v38, v38, v38 row_half_mirror row_mask:0xf bank_mask:0xf bound_ctrl:1
	ds_read_b128 v[96:99], v22 offset:36608
	ds_read_b128 v[84:87], v2 offset:56832
	v_add_f32_dpp v38, v38, v38 quad_perm:[1,0,3,2] row_mask:0xf bank_mask:0xf bound_ctrl:1
	ds_read_b128 v[88:91], v2 offset:57088
	ds_read_b128 v[100:103], v22 offset:36864
	v_add_f32_dpp v38, v38, v38 quad_perm:[2,3,0,1] row_mask:0xf bank_mask:0xf bound_ctrl:1
	ds_read_b128 v[92:95], v2 offset:57344
	v_cvt_pk_bf16_f32 v47, v38, v38
	global_store_short v28, v47, s[14:15] offset:-4096
	s_waitcnt lgkmcnt(4)
	v_pk_mul_f32 v[42:43], v[104:105], v[80:81] op_sel_hi:[1,0]
	v_pk_fma_f32 v[6:7], v[6:7], v[96:97], v[42:43] op_sel:[0,0,0] op_sel_hi:[1,0,1]
	v_pk_mul_f32 v[38:39], v[6:7], v[80:81] op_sel:[0,1] op_sel_hi:[1,1]
	v_pk_mul_f32 v[44:45], v[104:105], v[82:83] op_sel_hi:[1,0]
	v_pk_fma_f32 v[8:9], v[8:9], v[96:97], v[44:45] op_sel:[0,1,0] op_sel_hi:[1,1,1]
	v_pk_fma_f32 v[38:39], v[8:9], v[82:83], v[38:39] op_sel:[0,1,0] op_sel_hi:[1,1,1]
	s_waitcnt lgkmcnt(3)
	v_pk_mul_f32 v[42:43], v[104:105], v[84:85] op_sel_hi:[1,0]
	v_pk_fma_f32 v[10:11], v[10:11], v[98:99], v[42:43] op_sel:[0,0,0] op_sel_hi:[1,0,1]
	v_pk_fma_f32 v[38:39], v[10:11], v[84:85], v[38:39] op_sel:[0,1,0] op_sel_hi:[1,1,1]
	v_pk_mul_f32 v[44:45], v[104:105], v[86:87] op_sel_hi:[1,0]
	v_pk_fma_f32 v[12:13], v[12:13], v[98:99], v[44:45] op_sel:[0,1,0] op_sel_hi:[1,1,1]
	v_pk_fma_f32 v[38:39], v[12:13], v[86:87], v[38:39] op_sel:[0,1,0] op_sel_hi:[1,1,1]
	s_waitcnt lgkmcnt(1)
	v_pk_mul_f32 v[42:43], v[104:105], v[88:89] op_sel_hi:[1,0]
	v_pk_fma_f32 v[14:15], v[14:15], v[100:101], v[42:43] op_sel:[0,0,0] op_sel_hi:[1,0,1]
	v_pk_fma_f32 v[38:39], v[14:15], v[88:89], v[38:39] op_sel:[0,1,0] op_sel_hi:[1,1,1]
	v_pk_mul_f32 v[44:45], v[104:105], v[90:91] op_sel_hi:[1,0]
	v_pk_fma_f32 v[16:17], v[16:17], v[100:101], v[44:45] op_sel:[0,1,0] op_sel_hi:[1,1,1]
	v_pk_fma_f32 v[38:39], v[16:17], v[90:91], v[38:39] op_sel:[0,1,0] op_sel_hi:[1,1,1]
	s_waitcnt lgkmcnt(0)
	v_pk_mul_f32 v[42:43], v[104:105], v[92:93] op_sel_hi:[1,0]
	v_pk_fma_f32 v[18:19], v[18:19], v[102:103], v[42:43] op_sel:[0,0,0] op_sel_hi:[1,0,1]
	v_pk_fma_f32 v[38:39], v[18:19], v[92:93], v[38:39] op_sel:[0,1,0] op_sel_hi:[1,1,1]
	v_pk_mul_f32 v[44:45], v[104:105], v[94:95] op_sel_hi:[1,0]
	v_pk_fma_f32 v[20:21], v[20:21], v[102:103], v[44:45] op_sel:[0,1,0] op_sel_hi:[1,1,1]
	v_pk_fma_f32 v[38:39], v[20:21], v[94:95], v[38:39] op_sel:[0,1,0] op_sel_hi:[1,1,1]
	s_add_u32 s14, s14, 0x1000
	s_addc_u32 s15, s15, 0
	v_add_f32_dpp v38, v38, v38 row_ror:8 row_mask:0xf bank_mask:0x3 bound_ctrl:1
	v_add_f32_dpp v38, v39, v39 row_ror:8 row_mask:0xf bank_mask:0xc bound_ctrl:1
	ds_read_b64 v[72:73], v3 offset:20736
	ds_read_b128 v[48:51], v2 offset:256
	v_add_f32_dpp v38, v38, v38 row_half_mirror row_mask:0xf bank_mask:0xf bound_ctrl:1
	ds_read_b128 v[64:67], v2 offset:16640
	ds_read_b128 v[52:55], v2 offset:512
	v_add_f32_dpp v38, v38, v38 quad_perm:[1,0,3,2] row_mask:0xf bank_mask:0xf bound_ctrl:1
	ds_read_b128 v[56:59], v2 offset:768
	ds_read_b128 v[68:71], v2 offset:16896
	v_add_f32_dpp v38, v38, v38 quad_perm:[2,3,0,1] row_mask:0xf bank_mask:0xf bound_ctrl:1
	ds_read_b128 v[60:63], v2 offset:1024
	v_cvt_pk_bf16_f32 v47, v38, v38
	global_store_short v28, v47, s[14:15] offset:-4096
	s_waitcnt vmcnt(8)
	v_lshlrev_b32_e32 v144, 16, v110
	v_lshlrev_b32_e32 v145, 16, v111
	v_and_b32_e32 v146, s17, v110
	v_and_b32_e32 v147, s17, v111
	v_lshlrev_b32_e32 v148, 16, v112
	v_lshlrev_b32_e32 v149, 16, v113
	v_and_b32_e32 v150, s17, v112
	v_and_b32_e32 v151, s17, v113
	v_lshlrev_b32_e32 v152, 16, v114
	v_and_b32_e32 v153, s17, v114
	v_rcp_f32_e32 v25, v24
	v_mul_f32_e32 v149, v24, v149
	v_mul_f32_e32 v151, v24, v151
	v_mul_f32_e32 v145, 0x3db504f3, v145
	v_mul_f32_e32 v147, 0x3db504f3, v147
	v_cndmask_b32_e64 v27, 1.0, v25, s[20:21]
	v_mul_f32_e32 v24, v24, v26
	v_mul_f32_e32 v152, v27, v152
	v_mul_f32_e32 v153, v27, v153
	ds_write_b128 v29, v[144:147] offset:24832
	ds_write_b128 v29, v[148:151] offset:33024
	ds_write_b64 v30, v[116:117] offset:24832
	ds_write_b64 v31, v[152:153] offset:24832
	s_add_i32 s16, s16, 8
	s_waitcnt lgkmcnt(0)
	s_barrier
	s_cmpk_lt_u32 s16, 0x800
	s_cbranch_scc1 .Lgla2_loop
